# rg full-scan pass: x column read into the high half (no unpack shift) for the forward tiles and the first backward tile, where XC is still clean
# speedup vs baseline: 1.0077x; 1.0039x over previous
; #define LAS __attribute__((address_space(3)))
; template <bool FINAL>
; __device__ __forceinline__ void rg_item(PREF p, int l, int item, LAS unsigned char* wl, int lane) {
;     ...
;     const int h = item & 7, rest = item >> 3;
;     const int ci = rest < 512 ? 4 + (rest & 255) : ((rest - 512) & 3), b = rest < 512 ? (rest >> 8) : ((rest - 512) >> 2);
;     const int seq_row0 = ci < 4 ? TL + b * 256 : b * 16384;
;     const int t0 = ci < 4 ? ci * 64 : (ci - 4) * 64;
;     const int seqlen = ci < 4 ? 256 : 16384;
;     const int ch = h * 64 + lane;
;     LAS bf16_t* sXc = (LAS bf16_t*)wl;
;     LAS float* stg = (LAS float*)(wl + 9216);
;     {
;         const float cw0 = p.conv_w[(l * 4 + 0) * 512 + ch], cw1 = p.conv_w[(l * 4 + 1) * 512 + ch], cw2 = p.conv_w[(l * 4 + 2) * 512 + ch], cw3 = p.conv_w[(l * 4 + 3) * 512 + ch];
;         const float cb = p.conv_b[l * 512 + ch];
;         float xv[67]; unsigned xr_[67];
; #pragma unroll
;         for (int i = 0; i < 67; ++i) { const int t = t0 - 2 + i; const int tc = t < 0 ? 0 : (t >= seqlen ? seqlen - 1 : t);
;             xr_[i] = P[(size_t)(seq_row0 + tc) * PW + ch]; }
.Lrg7_dec:
	s_add_i32 s15, s11, s10
	s_mul_i32 s36, s9, 0x104
	s_add_i32 s36, s36, s8
	s_lshl_b32 s36, s36, 12
	s_cmp_eq_u32 s10, 0
	s_cselect_b32 s37, 0, -1
	s_add_i32 s38, s10, 64
	s_cmp_eq_u32 s38, s14
	s_cselect_b32 s38, 0, -1
	s_bfe_u32 s44, s44, 0x30006
	s_mul_i32 s44, s44, 0x4800
	v_lshl_or_b32 v234, s7, 6, v233
	v_lshlrev_b32_e32 v235, 2, v234
	v_lshlrev_b32_e32 v234, 1, v234
	v_and_b32_e32 v236, 15, v233
	v_lshrrev_b32_e32 v241, 4, v233
	s_movk_i32 s39, 0x90
	v_mul_u32_u24_e32 v237, 0x90, v236
	v_lshl_add_u32 v237, v241, 4, v237
	v_lshlrev_b32_e32 v238, 7, v236
	v_lshl_add_u32 v238, v241, 4, v238
	v_lshlrev_b32_e32 v239, 10, v241
	v_lshl_add_u32 v239, v236, 2, v239
	v_mov_b32_e32 v241, v238
	v_add_u32_e32 v236, s44, v237
	s_add_i32 s39, s44, 0x2400
	v_add_u32_e32 v237, s39, v239
	v_add_u32_e32 v238, 0x1000, v237
	v_lshl_add_u32 v239, v233, 2, s44
	v_lshl_add_u32 v240, v233, 1, s44
	s_add_i32 s39, s15, -2
	s_mul_hi_i32 s83, s39, 0x1600
	s_mul_i32 s82, s39, 0x1600
	s_waitcnt lgkmcnt(0)
	s_add_u32 s82, s82, s0
	s_addc_u32 s83, s83, s1
	s_add_u32 s82, s82, 0xbc00000
	s_addc_u32 s83, s83, 0
	global_load_ushort v158, v234, s[82:83]
	s_add_u32 s82, s82, 0x1600
	s_addc_u32 s83, s83, 0
	global_load_ushort v159, v234, s[82:83]
	s_add_u32 s82, s82, 0x1600
	s_addc_u32 s83, s83, 0
	global_load_ushort v160, v234, s[82:83]
	s_add_u32 s82, s82, 0x1600
	s_addc_u32 s83, s83, 0
	global_load_ushort v161, v234, s[82:83]
	s_add_u32 s82, s82, 0x1600
	s_addc_u32 s83, s83, 0
	global_load_ushort v162, v234, s[82:83]
	s_add_u32 s82, s82, 0x1600
	s_addc_u32 s83, s83, 0
	global_load_ushort v163, v234, s[82:83]
	s_add_u32 s82, s82, 0x1600
	s_addc_u32 s83, s83, 0
	global_load_ushort v164, v234, s[82:83]
	s_add_u32 s82, s82, 0x1600
	s_addc_u32 s83, s83, 0
	global_load_ushort v165, v234, s[82:83]
	s_add_u32 s82, s82, 0x1600
	s_addc_u32 s83, s83, 0
	global_load_ushort v166, v234, s[82:83]
	s_add_u32 s82, s82, 0x1600
	s_addc_u32 s83, s83, 0
	global_load_ushort v167, v234, s[82:83]
	s_add_u32 s82, s82, 0x1600
	s_addc_u32 s83, s83, 0
	global_load_ushort v168, v234, s[82:83]
	s_add_u32 s82, s82, 0x1600
	s_addc_u32 s83, s83, 0
	global_load_ushort v169, v234, s[82:83]
	s_add_u32 s82, s82, 0x1600
	s_addc_u32 s83, s83, 0
	global_load_ushort v170, v234, s[82:83]
	s_add_u32 s82, s82, 0x1600
	s_addc_u32 s83, s83, 0
	global_load_ushort v171, v234, s[82:83]
	s_add_u32 s82, s82, 0x1600
	s_addc_u32 s83, s83, 0
	global_load_ushort v172, v234, s[82:83]
	s_add_u32 s82, s82, 0x1600
	s_addc_u32 s83, s83, 0
	global_load_ushort v173, v234, s[82:83]
	s_add_u32 s82, s82, 0x1600
	s_addc_u32 s83, s83, 0
	global_load_ushort v174, v234, s[82:83]
	s_add_u32 s82, s82, 0x1600
	s_addc_u32 s83, s83, 0
	global_load_ushort v175, v234, s[82:83]
	s_add_u32 s82, s82, 0x1600
	s_addc_u32 s83, s83, 0
	global_load_ushort v176, v234, s[82:83]
	s_add_u32 s82, s82, 0x1600
	s_addc_u32 s83, s83, 0
	global_load_ushort v177, v234, s[82:83]
	s_add_u32 s82, s82, 0x1600
	s_addc_u32 s83, s83, 0
	global_load_ushort v178, v234, s[82:83]
	s_add_u32 s82, s82, 0x1600
	s_addc_u32 s83, s83, 0
	global_load_ushort v179, v234, s[82:83]
	s_add_u32 s82, s82, 0x1600
	s_addc_u32 s83, s83, 0
	global_load_ushort v180, v234, s[82:83]
	s_add_u32 s82, s82, 0x1600
	s_addc_u32 s83, s83, 0
	global_load_ushort v181, v234, s[82:83]
	s_add_u32 s82, s82, 0x1600
	s_addc_u32 s83, s83, 0
	global_load_ushort v182, v234, s[82:83]
	s_add_u32 s82, s82, 0x1600
	s_addc_u32 s83, s83, 0
	global_load_ushort v183, v234, s[82:83]
	s_add_u32 s82, s82, 0x1600
	s_addc_u32 s83, s83, 0
	global_load_ushort v184, v234, s[82:83]
	s_add_u32 s82, s82, 0x1600
	s_addc_u32 s83, s83, 0
	global_load_ushort v185, v234, s[82:83]
	s_add_u32 s82, s82, 0x1600
	s_addc_u32 s83, s83, 0
	global_load_ushort v186, v234, s[82:83]
	s_add_u32 s82, s82, 0x1600
	s_addc_u32 s83, s83, 0
	global_load_ushort v187, v234, s[82:83]
	s_add_u32 s82, s82, 0x1600
	s_addc_u32 s83, s83, 0
	global_load_ushort v188, v234, s[82:83]
	s_add_u32 s82, s82, 0x1600
	s_addc_u32 s83, s83, 0
	global_load_ushort v189, v234, s[82:83]
	s_add_u32 s82, s82, 0x1600
	s_addc_u32 s83, s83, 0
	global_load_ushort v190, v234, s[82:83]
	s_add_u32 s82, s82, 0x1600
	s_addc_u32 s83, s83, 0
	global_load_ushort v191, v234, s[82:83]
	s_add_u32 s82, s82, 0x1600
	s_addc_u32 s83, s83, 0
	global_load_ushort v192, v234, s[82:83]
	s_add_u32 s82, s82, 0x1600
	s_addc_u32 s83, s83, 0
	global_load_ushort v193, v234, s[82:83]
	s_add_u32 s82, s82, 0x1600
	s_addc_u32 s83, s83, 0
	global_load_ushort v194, v234, s[82:83]
	s_add_u32 s82, s82, 0x1600
	s_addc_u32 s83, s83, 0
	global_load_ushort v195, v234, s[82:83]
	s_add_u32 s82, s82, 0x1600
	s_addc_u32 s83, s83, 0
	global_load_ushort v196, v234, s[82:83]
	s_add_u32 s82, s82, 0x1600
	s_addc_u32 s83, s83, 0
	global_load_ushort v197, v234, s[82:83]
	s_add_u32 s82, s82, 0x1600
	s_addc_u32 s83, s83, 0
	global_load_ushort v198, v234, s[82:83]
	s_add_u32 s82, s82, 0x1600
	s_addc_u32 s83, s83, 0
	global_load_ushort v199, v234, s[82:83]
	s_add_u32 s82, s82, 0x1600
	s_addc_u32 s83, s83, 0
	global_load_ushort v200, v234, s[82:83]
	s_add_u32 s82, s82, 0x1600
	s_addc_u32 s83, s83, 0
	global_load_ushort v201, v234, s[82:83]
	s_add_u32 s82, s82, 0x1600
	s_addc_u32 s83, s83, 0
	global_load_ushort v202, v234, s[82:83]
	s_add_u32 s82, s82, 0x1600
	s_addc_u32 s83, s83, 0
	global_load_ushort v203, v234, s[82:83]
	s_add_u32 s82, s82, 0x1600
	s_addc_u32 s83, s83, 0
	global_load_ushort v204, v234, s[82:83]
	s_add_u32 s82, s82, 0x1600
	s_addc_u32 s83, s83, 0
	global_load_ushort v205, v234, s[82:83]
	s_add_u32 s82, s82, 0x1600
	s_addc_u32 s83, s83, 0
	global_load_ushort v206, v234, s[82:83]
	s_add_u32 s82, s82, 0x1600
; __device__ __forceinline__ float rcpf_(float x) { return __builtin_amdgcn_rcpf(x); }
; template <bool FINAL, int D>
; __device__ __forceinline__ void rg_dir(PREF p, int l, int h, int ch, int sidx, int rowbase  , LAS bf16_t* sXc, LAS float* stg, int lane) {
;     ...
;     const bf16_t* wr_ = WgT + (size_t)(((l * 2 + D) * 2 + 0) * 8 + h) * 4096; const bf16_t* wi_ = WgT + (size_t)(((l * 2 + D) * 2 + 1) * 8 + h) * 4096;
;     const float ba = p.rg_ba[(l * 2 + D) * 512 + ch], bi = p.rg_bi[(l * 2 + D) * 512 + ch], lam = p.rg_lam[(l * 2 + D) * 512 + ch];
;     const float e_ = __expf(-lam), u_ = 1.f + e_;
;     const float l1p = (u_ == 1.f) ? e_ : __logf(u_) * e_ * rcpf_(u_ - 1.f);
;     const float sp8 = -8.f * 1.4426950408889634f * l1p;
;     float hc = FINAL ? RGC[sidx] : 0.f, Ap = 1.f;
;     bf16x8 Br[4][2], Bi[4][2];
; #pragma unroll
;     for (int nt = 0; nt < 4; ++nt) { const int o0 = (nt * 16 + (lane & 15)) * 64 + (lane >> 4) * 8;
;         Br[nt][0] = *(const bf16x8*)(wr_ + o0); Br[nt][1] = *(const bf16x8*)(wr_ + o0 + 32); Bi[nt][0] = *(const bf16x8*)(wi_ + o0); Bi[nt][1] = *(const bf16x8*)(wi_ + o0 + 32); }
; template <bool FINAL>
; __device__ __forceinline__ void rg_item(PREF p, int l, int item, LAS unsigned char* wl, int lane) {
;     ...
;         const float cw0 = p.conv_w[(l * 4 + 0) * 512 + ch], cw1 = p.conv_w[(l * 4 + 1) * 512 + ch], cw2 = p.conv_w[(l * 4 + 2) * 512 + ch], cw3 = p.conv_w[(l * 4 + 3) * 512 + ch];
;         const float cb = p.conv_b[l * 512 + ch];
;         float xv[67]; unsigned xr_[67];
; #pragma unroll
;         for (int i = 0; i < 67; ++i) { const int t = t0 - 2 + i; const int tc = t < 0 ? 0 : (t >= seqlen ? seqlen - 1 : t);
;             xr_[i] = P[(size_t)(seq_row0 + tc) * PW + ch]; }
;         __builtin_amdgcn_sched_barrier(0);
; #pragma unroll
;         for (int i = 0; i < 67; ++i) { const int t = t0 - 2 + i; const int tc = t < 0 ? 0 : (t >= seqlen ? seqlen - 1 : t); xv[i] = (t == tc) ? bf2f(xr_[i]) : 0.f; }
	s_addc_u32 s83, s83, 0
	global_load_ushort v207, v234, s[82:83]
	s_add_u32 s82, s82, 0x1600
	s_addc_u32 s83, s83, 0
	global_load_ushort v208, v234, s[82:83]
	s_add_u32 s82, s82, 0x1600
	s_addc_u32 s83, s83, 0
	global_load_ushort v209, v234, s[82:83]
	s_add_u32 s82, s82, 0x1600
	s_addc_u32 s83, s83, 0
	global_load_ushort v210, v234, s[82:83]
	s_add_u32 s82, s82, 0x1600
	s_addc_u32 s83, s83, 0
	global_load_ushort v211, v234, s[82:83]
	s_add_u32 s82, s82, 0x1600
	s_addc_u32 s83, s83, 0
	global_load_ushort v212, v234, s[82:83]
	s_add_u32 s82, s82, 0x1600
	s_addc_u32 s83, s83, 0
	global_load_ushort v213, v234, s[82:83]
	s_add_u32 s82, s82, 0x1600
	s_addc_u32 s83, s83, 0
	global_load_ushort v214, v234, s[82:83]
	s_add_u32 s82, s82, 0x1600
	s_addc_u32 s83, s83, 0
	global_load_ushort v215, v234, s[82:83]
	s_add_u32 s82, s82, 0x1600
	s_addc_u32 s83, s83, 0
	global_load_ushort v216, v234, s[82:83]
	s_add_u32 s82, s82, 0x1600
	s_addc_u32 s83, s83, 0
	global_load_ushort v217, v234, s[82:83]
	s_add_u32 s82, s82, 0x1600
	s_addc_u32 s83, s83, 0
	global_load_ushort v218, v234, s[82:83]
	s_add_u32 s82, s82, 0x1600
	s_addc_u32 s83, s83, 0
	global_load_ushort v219, v234, s[82:83]
	s_add_u32 s82, s82, 0x1600
	s_addc_u32 s83, s83, 0
	global_load_ushort v222, v234, s[82:83]
	s_add_u32 s82, s82, 0x1600
	s_addc_u32 s83, s83, 0
	global_load_ushort v223, v234, s[82:83]
	s_add_u32 s82, s82, 0x1600
	s_addc_u32 s83, s83, 0
	global_load_ushort v140, v234, s[82:83]
	s_add_u32 s82, s82, 0x1600
	s_addc_u32 s83, s83, 0
	global_load_ushort v141, v234, s[82:83]
	s_add_u32 s82, s82, 0x1600
	s_addc_u32 s83, s83, 0
	global_load_ushort v232, v234, s[82:83]
	s_lshl_b32 s39, s47, 13
	s_add_u32 s72, s72, s39
	s_addc_u32 s73, s73, 0
	global_load_dword v40, v235, s[72:73]
	global_load_dword v41, v235, s[72:73] offset:2048
	s_add_u32 s72, s72, 0x1000
	s_addc_u32 s73, s73, 0
	global_load_dword v42, v235, s[72:73]
	global_load_dword v43, v235, s[72:73] offset:2048
	s_lshl_b32 s39, s47, 11
	s_add_u32 s74, s74, s39
	s_addc_u32 s75, s75, 0
	global_load_dword v44, v235, s[74:75]
	s_lshl_b32 s39, s47, 12
	s_add_u32 s76, s76, s39
	s_addc_u32 s77, s77, 0
	s_add_u32 s78, s78, s39
	s_addc_u32 s79, s79, 0
	s_add_u32 s80, s80, s39
	s_addc_u32 s81, s81, 0
	s_add_u32 s96, s0, 0xa00000
	s_addc_u32 s97, s1, 0
	s_add_u32 s96, s96, s36
	s_addc_u32 s97, s97, 0
	s_lshl_b32 s39, s47, 5
	s_add_i32 s39, s39, s7
	s_lshl_b32 s39, s39, 13
	s_add_u32 s92, s0, 0x300000
	s_addc_u32 s93, s1, 0
	s_add_u32 s92, s92, s39
	s_addc_u32 s93, s93, 0
	global_load_dword v45, v235, s[76:77]
	global_load_dword v46, v235, s[78:79]
	global_load_dword v47, v235, s[80:81]
	global_load_dword v250, v235, s[96:97]
	s_add_u32 s90, s92, 0x0
	s_addc_u32 s91, s93, 0
	global_load_dwordx4 v[80:83], v241, s[90:91]
	global_load_dwordx4 v[84:87], v241, s[90:91] offset:64
	global_load_dwordx4 v[88:91], v241, s[90:91] offset:2048
	global_load_dwordx4 v[92:95], v241, s[90:91] offset:2112
	s_add_u32 s90, s92, 0x1000
	s_addc_u32 s91, s93, 0
	global_load_dwordx4 v[96:99], v241, s[90:91]
	global_load_dwordx4 v[100:103], v241, s[90:91] offset:64
	global_load_dwordx4 v[104:107], v241, s[90:91] offset:2048
	global_load_dwordx4 v[108:111], v241, s[90:91] offset:2112
	s_add_u32 s90, s92, 0x10000
	s_addc_u32 s91, s93, 0
	global_load_dwordx4 v[112:115], v241, s[90:91]
	global_load_dwordx4 v[116:119], v241, s[90:91] offset:64
	global_load_dwordx4 v[120:123], v241, s[90:91] offset:2048
	global_load_dwordx4 v[124:127], v241, s[90:91] offset:2112
	s_add_u32 s90, s92, 0x11000
	s_addc_u32 s91, s93, 0
	global_load_dwordx4 v[128:131], v241, s[90:91]
	global_load_dwordx4 v[132:135], v241, s[90:91] offset:64
	global_load_dwordx4 v[136:139], v241, s[90:91] offset:2048
	global_load_dwordx4 v[228:231], v241, s[90:91] offset:2112
	s_waitcnt vmcnt(20)
	v_lshlrev_b32_e32 v158, 16, v158
	v_lshlrev_b32_e32 v159, 16, v159
	v_lshlrev_b32_e32 v160, 16, v160
	v_lshlrev_b32_e32 v161, 16, v161
	v_lshlrev_b32_e32 v162, 16, v162
	v_lshlrev_b32_e32 v163, 16, v163
	v_lshlrev_b32_e32 v164, 16, v164
	v_lshlrev_b32_e32 v165, 16, v165
	v_lshlrev_b32_e32 v166, 16, v166
	v_lshlrev_b32_e32 v167, 16, v167
	v_lshlrev_b32_e32 v168, 16, v168
	v_lshlrev_b32_e32 v169, 16, v169
	v_lshlrev_b32_e32 v170, 16, v170
	v_lshlrev_b32_e32 v171, 16, v171
	v_lshlrev_b32_e32 v172, 16, v172
	v_lshlrev_b32_e32 v173, 16, v173
	v_lshlrev_b32_e32 v174, 16, v174
	v_lshlrev_b32_e32 v175, 16, v175
	v_lshlrev_b32_e32 v176, 16, v176
	v_lshlrev_b32_e32 v177, 16, v177
	v_lshlrev_b32_e32 v178, 16, v178
	v_lshlrev_b32_e32 v179, 16, v179
	v_lshlrev_b32_e32 v180, 16, v180
	v_lshlrev_b32_e32 v181, 16, v181
	v_lshlrev_b32_e32 v182, 16, v182
	v_lshlrev_b32_e32 v183, 16, v183
	v_lshlrev_b32_e32 v184, 16, v184
	v_lshlrev_b32_e32 v185, 16, v185
	v_lshlrev_b32_e32 v186, 16, v186
	v_lshlrev_b32_e32 v187, 16, v187
	v_lshlrev_b32_e32 v188, 16, v188
	v_lshlrev_b32_e32 v189, 16, v189
	v_lshlrev_b32_e32 v190, 16, v190
	v_lshlrev_b32_e32 v191, 16, v191
	v_lshlrev_b32_e32 v192, 16, v192
	v_lshlrev_b32_e32 v193, 16, v193
	v_lshlrev_b32_e32 v194, 16, v194
	v_lshlrev_b32_e32 v195, 16, v195
	v_lshlrev_b32_e32 v196, 16, v196
	v_lshlrev_b32_e32 v197, 16, v197
	v_lshlrev_b32_e32 v198, 16, v198
	v_lshlrev_b32_e32 v199, 16, v199
	v_lshlrev_b32_e32 v200, 16, v200
	v_lshlrev_b32_e32 v201, 16, v201
	v_lshlrev_b32_e32 v202, 16, v202
	v_lshlrev_b32_e32 v203, 16, v203
	v_lshlrev_b32_e32 v204, 16, v204
	v_lshlrev_b32_e32 v205, 16, v205
	v_lshlrev_b32_e32 v206, 16, v206
	v_lshlrev_b32_e32 v207, 16, v207
	v_lshlrev_b32_e32 v208, 16, v208
	v_lshlrev_b32_e32 v209, 16, v209
	v_lshlrev_b32_e32 v210, 16, v210
	v_lshlrev_b32_e32 v211, 16, v211
; __device__ __forceinline__ unsigned f2bf(float f) { unsigned r; asm("v_cvt_pk_bf16_f32 %0, %1, %1" : "=v"(r) : "v"(f)); return r & 0xffffu; }
; template <bool FINAL>
; __device__ __forceinline__ void rg_item(PREF p, int l, int item, LAS unsigned char* wl, int lane) {
;     ...
;         for (int i = 0; i < 67; ++i) { const int t = t0 - 2 + i; const int tc = t < 0 ? 0 : (t >= seqlen ? seqlen - 1 : t); xv[i] = (t == tc) ? bf2f(xr_[i]) : 0.f; }
; #pragma unroll
;         for (int tt = 0; tt < 64; ++tt) { const float xc = xv[tt] * cw0 + xv[tt + 1] * cw1 + xv[tt + 2] * cw2 + xv[tt + 3] * cw3 + cb; sXc[tt * 72 + lane] = (bf16_t)f2bf(xc); }
	v_lshlrev_b32_e32 v212, 16, v212
	v_lshlrev_b32_e32 v213, 16, v213
	v_lshlrev_b32_e32 v214, 16, v214
	v_lshlrev_b32_e32 v215, 16, v215
	v_lshlrev_b32_e32 v216, 16, v216
	v_lshlrev_b32_e32 v217, 16, v217
	v_lshlrev_b32_e32 v218, 16, v218
	v_lshlrev_b32_e32 v219, 16, v219
	v_lshlrev_b32_e32 v222, 16, v222
	v_lshlrev_b32_e32 v223, 16, v223
	v_lshlrev_b32_e32 v140, 16, v140
	v_lshlrev_b32_e32 v141, 16, v141
	v_lshlrev_b32_e32 v232, 16, v232
	v_and_b32_e32 v158, s37, v158
	v_and_b32_e32 v159, s37, v159
	v_and_b32_e32 v232, s38, v232
	v_mul_f32_e32 v32, v41, v159
	v_mul_f32_e32 v33, v41, v160
	v_mul_f32_e32 v34, v41, v161
	v_mul_f32_e32 v35, v41, v162
	v_mul_f32_e32 v36, v41, v163
	v_mul_f32_e32 v37, v41, v164
	v_mul_f32_e32 v38, v41, v165
	v_mul_f32_e32 v39, v41, v166
	v_fmac_f32_e32 v32, v40, v158
	v_fmac_f32_e32 v33, v40, v159
	v_fmac_f32_e32 v34, v40, v160
	v_fmac_f32_e32 v35, v40, v161
	v_fmac_f32_e32 v36, v40, v162
	v_fmac_f32_e32 v37, v40, v163
	v_fmac_f32_e32 v38, v40, v164
	v_fmac_f32_e32 v39, v40, v165
	v_fmac_f32_e32 v32, v42, v160
	v_fmac_f32_e32 v33, v42, v161
	v_fmac_f32_e32 v34, v42, v162
	v_fmac_f32_e32 v35, v42, v163
	v_fmac_f32_e32 v36, v42, v164
	v_fmac_f32_e32 v37, v42, v165
	v_fmac_f32_e32 v38, v42, v166
	v_fmac_f32_e32 v39, v42, v167
	v_fmac_f32_e32 v32, v43, v161
	v_fmac_f32_e32 v33, v43, v162
	v_fmac_f32_e32 v34, v43, v163
	v_fmac_f32_e32 v35, v43, v164
	v_fmac_f32_e32 v36, v43, v165
	v_fmac_f32_e32 v37, v43, v166
	v_fmac_f32_e32 v38, v43, v167
	v_fmac_f32_e32 v39, v43, v168
	v_add_f32_e32 v32, v44, v32
	v_add_f32_e32 v33, v44, v33
	v_add_f32_e32 v34, v44, v34
	v_add_f32_e32 v35, v44, v35
	v_add_f32_e32 v36, v44, v36
	v_add_f32_e32 v37, v44, v37
	v_add_f32_e32 v38, v44, v38
	v_add_f32_e32 v39, v44, v39
	v_cvt_pk_bf16_f32 v32, v32, v33
	v_cvt_pk_bf16_f32 v34, v34, v35
	v_cvt_pk_bf16_f32 v36, v36, v37
	v_cvt_pk_bf16_f32 v38, v38, v39
	ds_write_b16 v240, v32 offset:0
	ds_write_b16_d16_hi v240, v32 offset:144
	ds_write_b16 v240, v34 offset:288
	ds_write_b16_d16_hi v240, v34 offset:432
	ds_write_b16 v240, v36 offset:576
	ds_write_b16_d16_hi v240, v36 offset:720
	ds_write_b16 v240, v38 offset:864
	ds_write_b16_d16_hi v240, v38 offset:1008
	v_mul_f32_e32 v32, v41, v167
	v_mul_f32_e32 v33, v41, v168
	v_mul_f32_e32 v34, v41, v169
	v_mul_f32_e32 v35, v41, v170
	v_mul_f32_e32 v36, v41, v171
	v_mul_f32_e32 v37, v41, v172
	v_mul_f32_e32 v38, v41, v173
	v_mul_f32_e32 v39, v41, v174
	v_fmac_f32_e32 v32, v40, v166
	v_fmac_f32_e32 v33, v40, v167
	v_fmac_f32_e32 v34, v40, v168
	v_fmac_f32_e32 v35, v40, v169
	v_fmac_f32_e32 v36, v40, v170
	v_fmac_f32_e32 v37, v40, v171
	v_fmac_f32_e32 v38, v40, v172
	v_fmac_f32_e32 v39, v40, v173
	v_fmac_f32_e32 v32, v42, v168
	v_fmac_f32_e32 v33, v42, v169
	v_fmac_f32_e32 v34, v42, v170
	v_fmac_f32_e32 v35, v42, v171
	v_fmac_f32_e32 v36, v42, v172
	v_fmac_f32_e32 v37, v42, v173
	v_fmac_f32_e32 v38, v42, v174
	v_fmac_f32_e32 v39, v42, v175
	v_fmac_f32_e32 v32, v43, v169
	v_fmac_f32_e32 v33, v43, v170
	v_fmac_f32_e32 v34, v43, v171
	v_fmac_f32_e32 v35, v43, v172
	v_fmac_f32_e32 v36, v43, v173
	v_fmac_f32_e32 v37, v43, v174
	v_fmac_f32_e32 v38, v43, v175
	v_fmac_f32_e32 v39, v43, v176
	v_add_f32_e32 v32, v44, v32
	v_add_f32_e32 v33, v44, v33
	v_add_f32_e32 v34, v44, v34
	v_add_f32_e32 v35, v44, v35
	v_add_f32_e32 v36, v44, v36
	v_add_f32_e32 v37, v44, v37
	v_add_f32_e32 v38, v44, v38
	v_add_f32_e32 v39, v44, v39
	v_cvt_pk_bf16_f32 v32, v32, v33
	v_cvt_pk_bf16_f32 v34, v34, v35
	v_cvt_pk_bf16_f32 v36, v36, v37
	v_cvt_pk_bf16_f32 v38, v38, v39
	ds_write_b16 v240, v32 offset:1152
	ds_write_b16_d16_hi v240, v32 offset:1296
	ds_write_b16 v240, v34 offset:1440
	ds_write_b16_d16_hi v240, v34 offset:1584
	ds_write_b16 v240, v36 offset:1728
	ds_write_b16_d16_hi v240, v36 offset:1872
	ds_write_b16 v240, v38 offset:2016
	ds_write_b16_d16_hi v240, v38 offset:2160
	v_mul_f32_e32 v32, v41, v175
	v_mul_f32_e32 v33, v41, v176
	v_mul_f32_e32 v34, v41, v177
	v_mul_f32_e32 v35, v41, v178
	v_mul_f32_e32 v36, v41, v179
	v_mul_f32_e32 v37, v41, v180
	v_mul_f32_e32 v38, v41, v181
	v_mul_f32_e32 v39, v41, v182
	v_fmac_f32_e32 v32, v40, v174
	v_fmac_f32_e32 v33, v40, v175
	v_fmac_f32_e32 v34, v40, v176
	v_fmac_f32_e32 v35, v40, v177
	v_fmac_f32_e32 v36, v40, v178
	v_fmac_f32_e32 v37, v40, v179
	v_fmac_f32_e32 v38, v40, v180
	v_fmac_f32_e32 v39, v40, v181
	v_fmac_f32_e32 v32, v42, v176
	v_fmac_f32_e32 v33, v42, v177
	v_fmac_f32_e32 v34, v42, v178
	v_fmac_f32_e32 v35, v42, v179
	v_fmac_f32_e32 v36, v42, v180
	v_fmac_f32_e32 v37, v42, v181
	v_fmac_f32_e32 v38, v42, v182
	v_fmac_f32_e32 v39, v42, v183
	v_fmac_f32_e32 v32, v43, v177
	v_fmac_f32_e32 v33, v43, v178
	v_fmac_f32_e32 v34, v43, v179
	v_fmac_f32_e32 v35, v43, v180
	v_fmac_f32_e32 v36, v43, v181
	v_fmac_f32_e32 v37, v43, v182
	v_fmac_f32_e32 v38, v43, v183
	v_fmac_f32_e32 v39, v43, v184
	v_add_f32_e32 v32, v44, v32
	v_add_f32_e32 v33, v44, v33
	v_add_f32_e32 v34, v44, v34
	v_add_f32_e32 v35, v44, v35
	v_add_f32_e32 v36, v44, v36
	v_add_f32_e32 v37, v44, v37
	v_add_f32_e32 v38, v44, v38
	v_add_f32_e32 v39, v44, v39
	v_cvt_pk_bf16_f32 v32, v32, v33
	v_cvt_pk_bf16_f32 v34, v34, v35
	v_cvt_pk_bf16_f32 v36, v36, v37
	v_cvt_pk_bf16_f32 v38, v38, v39
	ds_write_b16 v240, v32 offset:2304
	ds_write_b16_d16_hi v240, v32 offset:2448
	ds_write_b16 v240, v34 offset:2592
	ds_write_b16_d16_hi v240, v34 offset:2736
	ds_write_b16 v240, v36 offset:2880
	ds_write_b16_d16_hi v240, v36 offset:3024
	ds_write_b16 v240, v38 offset:3168
	ds_write_b16_d16_hi v240, v38 offset:3312
	v_mul_f32_e32 v32, v41, v183
	v_mul_f32_e32 v33, v41, v184
	v_mul_f32_e32 v34, v41, v185
	v_mul_f32_e32 v35, v41, v186
; __device__ __forceinline__ unsigned f2bf(float f) { unsigned r; asm("v_cvt_pk_bf16_f32 %0, %1, %1" : "=v"(r) : "v"(f)); return r & 0xffffu; }
; template <bool FINAL>
; __device__ __forceinline__ void rg_item(PREF p, int l, int item, LAS unsigned char* wl, int lane) {
;     ...
;         for (int i = 0; i < 67; ++i) { const int t = t0 - 2 + i; const int tc = t < 0 ? 0 : (t >= seqlen ? seqlen - 1 : t); xv[i] = (t == tc) ? bf2f(xr_[i]) : 0.f; }
; #pragma unroll
;         for (int tt = 0; tt < 64; ++tt) { const float xc = xv[tt] * cw0 + xv[tt + 1] * cw1 + xv[tt + 2] * cw2 + xv[tt + 3] * cw3 + cb; sXc[tt * 72 + lane] = (bf16_t)f2bf(xc); }
	v_mul_f32_e32 v36, v41, v187
	v_mul_f32_e32 v37, v41, v188
	v_mul_f32_e32 v38, v41, v189
	v_mul_f32_e32 v39, v41, v190
	v_fmac_f32_e32 v32, v40, v182
	v_fmac_f32_e32 v33, v40, v183
	v_fmac_f32_e32 v34, v40, v184
	v_fmac_f32_e32 v35, v40, v185
	v_fmac_f32_e32 v36, v40, v186
	v_fmac_f32_e32 v37, v40, v187
	v_fmac_f32_e32 v38, v40, v188
	v_fmac_f32_e32 v39, v40, v189
	v_fmac_f32_e32 v32, v42, v184
	v_fmac_f32_e32 v33, v42, v185
	v_fmac_f32_e32 v34, v42, v186
	v_fmac_f32_e32 v35, v42, v187
	v_fmac_f32_e32 v36, v42, v188
	v_fmac_f32_e32 v37, v42, v189
	v_fmac_f32_e32 v38, v42, v190
	v_fmac_f32_e32 v39, v42, v191
	v_fmac_f32_e32 v32, v43, v185
	v_fmac_f32_e32 v33, v43, v186
	v_fmac_f32_e32 v34, v43, v187
	v_fmac_f32_e32 v35, v43, v188
	v_fmac_f32_e32 v36, v43, v189
	v_fmac_f32_e32 v37, v43, v190
	v_fmac_f32_e32 v38, v43, v191
	v_fmac_f32_e32 v39, v43, v192
	v_add_f32_e32 v32, v44, v32
	v_add_f32_e32 v33, v44, v33
	v_add_f32_e32 v34, v44, v34
	v_add_f32_e32 v35, v44, v35
	v_add_f32_e32 v36, v44, v36
	v_add_f32_e32 v37, v44, v37
	v_add_f32_e32 v38, v44, v38
	v_add_f32_e32 v39, v44, v39
	v_cvt_pk_bf16_f32 v32, v32, v33
	v_cvt_pk_bf16_f32 v34, v34, v35
	v_cvt_pk_bf16_f32 v36, v36, v37
	v_cvt_pk_bf16_f32 v38, v38, v39
	ds_write_b16 v240, v32 offset:3456
	ds_write_b16_d16_hi v240, v32 offset:3600
	ds_write_b16 v240, v34 offset:3744
	ds_write_b16_d16_hi v240, v34 offset:3888
	ds_write_b16 v240, v36 offset:4032
	ds_write_b16_d16_hi v240, v36 offset:4176
	ds_write_b16 v240, v38 offset:4320
	ds_write_b16_d16_hi v240, v38 offset:4464
	v_mul_f32_e32 v32, v41, v191
	v_mul_f32_e32 v33, v41, v192
	v_mul_f32_e32 v34, v41, v193
	v_mul_f32_e32 v35, v41, v194
	v_mul_f32_e32 v36, v41, v195
	v_mul_f32_e32 v37, v41, v196
	v_mul_f32_e32 v38, v41, v197
	v_mul_f32_e32 v39, v41, v198
	v_fmac_f32_e32 v32, v40, v190
	v_fmac_f32_e32 v33, v40, v191
	v_fmac_f32_e32 v34, v40, v192
	v_fmac_f32_e32 v35, v40, v193
	v_fmac_f32_e32 v36, v40, v194
	v_fmac_f32_e32 v37, v40, v195
	v_fmac_f32_e32 v38, v40, v196
	v_fmac_f32_e32 v39, v40, v197
	v_fmac_f32_e32 v32, v42, v192
	v_fmac_f32_e32 v33, v42, v193
	v_fmac_f32_e32 v34, v42, v194
	v_fmac_f32_e32 v35, v42, v195
	v_fmac_f32_e32 v36, v42, v196
	v_fmac_f32_e32 v37, v42, v197
	v_fmac_f32_e32 v38, v42, v198
	v_fmac_f32_e32 v39, v42, v199
	v_fmac_f32_e32 v32, v43, v193
	v_fmac_f32_e32 v33, v43, v194
	v_fmac_f32_e32 v34, v43, v195
	v_fmac_f32_e32 v35, v43, v196
	v_fmac_f32_e32 v36, v43, v197
	v_fmac_f32_e32 v37, v43, v198
	v_fmac_f32_e32 v38, v43, v199
	v_fmac_f32_e32 v39, v43, v200
	v_add_f32_e32 v32, v44, v32
	v_add_f32_e32 v33, v44, v33
	v_add_f32_e32 v34, v44, v34
	v_add_f32_e32 v35, v44, v35
	v_add_f32_e32 v36, v44, v36
	v_add_f32_e32 v37, v44, v37
	v_add_f32_e32 v38, v44, v38
	v_add_f32_e32 v39, v44, v39
	v_cvt_pk_bf16_f32 v32, v32, v33
	v_cvt_pk_bf16_f32 v34, v34, v35
	v_cvt_pk_bf16_f32 v36, v36, v37
	v_cvt_pk_bf16_f32 v38, v38, v39
	ds_write_b16 v240, v32 offset:4608
	ds_write_b16_d16_hi v240, v32 offset:4752
	ds_write_b16 v240, v34 offset:4896
	ds_write_b16_d16_hi v240, v34 offset:5040
	ds_write_b16 v240, v36 offset:5184
	ds_write_b16_d16_hi v240, v36 offset:5328
	ds_write_b16 v240, v38 offset:5472
	ds_write_b16_d16_hi v240, v38 offset:5616
	v_mul_f32_e32 v32, v41, v199
	v_mul_f32_e32 v33, v41, v200
	v_mul_f32_e32 v34, v41, v201
	v_mul_f32_e32 v35, v41, v202
	v_mul_f32_e32 v36, v41, v203
	v_mul_f32_e32 v37, v41, v204
	v_mul_f32_e32 v38, v41, v205
	v_mul_f32_e32 v39, v41, v206
	v_fmac_f32_e32 v32, v40, v198
	v_fmac_f32_e32 v33, v40, v199
	v_fmac_f32_e32 v34, v40, v200
	v_fmac_f32_e32 v35, v40, v201
	v_fmac_f32_e32 v36, v40, v202
	v_fmac_f32_e32 v37, v40, v203
	v_fmac_f32_e32 v38, v40, v204
	v_fmac_f32_e32 v39, v40, v205
	v_fmac_f32_e32 v32, v42, v200
	v_fmac_f32_e32 v33, v42, v201
	v_fmac_f32_e32 v34, v42, v202
	v_fmac_f32_e32 v35, v42, v203
	v_fmac_f32_e32 v36, v42, v204
	v_fmac_f32_e32 v37, v42, v205
	v_fmac_f32_e32 v38, v42, v206
	v_fmac_f32_e32 v39, v42, v207
	v_fmac_f32_e32 v32, v43, v201
	v_fmac_f32_e32 v33, v43, v202
	v_fmac_f32_e32 v34, v43, v203
	v_fmac_f32_e32 v35, v43, v204
	v_fmac_f32_e32 v36, v43, v205
	v_fmac_f32_e32 v37, v43, v206
	v_fmac_f32_e32 v38, v43, v207
	v_fmac_f32_e32 v39, v43, v208
	v_add_f32_e32 v32, v44, v32
	v_add_f32_e32 v33, v44, v33
	v_add_f32_e32 v34, v44, v34
	v_add_f32_e32 v35, v44, v35
	v_add_f32_e32 v36, v44, v36
	v_add_f32_e32 v37, v44, v37
	v_add_f32_e32 v38, v44, v38
	v_add_f32_e32 v39, v44, v39
	v_cvt_pk_bf16_f32 v32, v32, v33
	v_cvt_pk_bf16_f32 v34, v34, v35
	v_cvt_pk_bf16_f32 v36, v36, v37
	v_cvt_pk_bf16_f32 v38, v38, v39
	ds_write_b16 v240, v32 offset:5760
	ds_write_b16_d16_hi v240, v32 offset:5904
	ds_write_b16 v240, v34 offset:6048
	ds_write_b16_d16_hi v240, v34 offset:6192
	ds_write_b16 v240, v36 offset:6336
	ds_write_b16_d16_hi v240, v36 offset:6480
	ds_write_b16 v240, v38 offset:6624
	ds_write_b16_d16_hi v240, v38 offset:6768
	v_mul_f32_e32 v32, v41, v207
	v_mul_f32_e32 v33, v41, v208
	v_mul_f32_e32 v34, v41, v209
	v_mul_f32_e32 v35, v41, v210
	v_mul_f32_e32 v36, v41, v211
	v_mul_f32_e32 v37, v41, v212
	v_mul_f32_e32 v38, v41, v213
	v_mul_f32_e32 v39, v41, v214
	v_fmac_f32_e32 v32, v40, v206
	v_fmac_f32_e32 v33, v40, v207
	v_fmac_f32_e32 v34, v40, v208
	v_fmac_f32_e32 v35, v40, v209
	v_fmac_f32_e32 v36, v40, v210
	v_fmac_f32_e32 v37, v40, v211
	v_fmac_f32_e32 v38, v40, v212
	v_fmac_f32_e32 v39, v40, v213
	v_fmac_f32_e32 v32, v42, v208
	v_fmac_f32_e32 v33, v42, v209
	v_fmac_f32_e32 v34, v42, v210
	v_fmac_f32_e32 v35, v42, v211
	v_fmac_f32_e32 v36, v42, v212
	v_fmac_f32_e32 v37, v42, v213
	v_fmac_f32_e32 v38, v42, v214
	v_fmac_f32_e32 v39, v42, v215
	v_fmac_f32_e32 v32, v43, v209
; __device__ __forceinline__ unsigned f2bf(float f) { unsigned r; asm("v_cvt_pk_bf16_f32 %0, %1, %1" : "=v"(r) : "v"(f)); return r & 0xffffu; }
; __device__ __forceinline__ float rcpf_(float x) { return __builtin_amdgcn_rcpf(x); }
; template <bool FINAL, int D>
; __device__ __forceinline__ void rg_dir(PREF p, int l, int h, int ch, int sidx, int rowbase  , LAS bf16_t* sXc, LAS float* stg, int lane) {
;     ...
;     const float e_ = __expf(-lam), u_ = 1.f + e_;
;     const float l1p = (u_ == 1.f) ? e_ : __logf(u_) * e_ * rcpf_(u_ - 1.f);
;     const float sp8 = -8.f * 1.4426950408889634f * l1p;
;     float hc = FINAL ? RGC[sidx] : 0.f, Ap = 1.f;
;     bf16x8 Br[4][2], Bi[4][2];
; #pragma unroll
;     for (int nt = 0; nt < 4; ++nt) { const int o0 = (nt * 16 + (lane & 15)) * 64 + (lane >> 4) * 8;
;         Br[nt][0] = *(const bf16x8*)(wr_ + o0); Br[nt][1] = *(const bf16x8*)(wr_ + o0 + 32); Bi[nt][0] = *(const bf16x8*)(wi_ + o0); Bi[nt][1] = *(const bf16x8*)(wi_ + o0 + 32); }
;     if (FINAL && D == 1) asm volatile("s_waitcnt vmcnt(0)" ::: "memory");
; #pragma unroll 1
;     for (int mi = 0; mi < 4; ++mi) { const int mt = D ? 3 - mi : mi;
;         float grv[16], hfv[16];
;         if (FINAL && D == 1) {
; #pragma unroll
;             for (int ti = 0; ti < 16; ++ti) { const size_t row = (size_t)(rowbase + mt * 16 + 15 - ti); grv[ti] = __builtin_bit_cast(float, (unsigned)P[row * PW + 512 + ch]); hfv[ti] = __builtin_bit_cast(float, (unsigned)TMP[row * 512 + ch]); }
; template <bool FINAL>
; __device__ __forceinline__ void rg_item(PREF p, int l, int item, LAS unsigned char* wl, int lane) {
;     ...
;         for (int tt = 0; tt < 64; ++tt) { const float xc = xv[tt] * cw0 + xv[tt + 1] * cw1 + xv[tt + 2] * cw2 + xv[tt + 3] * cw3 + cb; sXc[tt * 72 + lane] = (bf16_t)f2bf(xc); }
	v_fmac_f32_e32 v33, v43, v210
	v_fmac_f32_e32 v34, v43, v211
	v_fmac_f32_e32 v35, v43, v212
	v_fmac_f32_e32 v36, v43, v213
	v_fmac_f32_e32 v37, v43, v214
	v_fmac_f32_e32 v38, v43, v215
	v_fmac_f32_e32 v39, v43, v216
	v_add_f32_e32 v32, v44, v32
	v_add_f32_e32 v33, v44, v33
	v_add_f32_e32 v34, v44, v34
	v_add_f32_e32 v35, v44, v35
	v_add_f32_e32 v36, v44, v36
	v_add_f32_e32 v37, v44, v37
	v_add_f32_e32 v38, v44, v38
	v_add_f32_e32 v39, v44, v39
	v_cvt_pk_bf16_f32 v32, v32, v33
	v_cvt_pk_bf16_f32 v34, v34, v35
	v_cvt_pk_bf16_f32 v36, v36, v37
	v_cvt_pk_bf16_f32 v38, v38, v39
	ds_write_b16 v240, v32 offset:6912
	ds_write_b16_d16_hi v240, v32 offset:7056
	ds_write_b16 v240, v34 offset:7200
	ds_write_b16_d16_hi v240, v34 offset:7344
	ds_write_b16 v240, v36 offset:7488
	ds_write_b16_d16_hi v240, v36 offset:7632
	ds_write_b16 v240, v38 offset:7776
	ds_write_b16_d16_hi v240, v38 offset:7920
	v_mul_f32_e32 v32, v41, v215
	v_mul_f32_e32 v33, v41, v216
	v_mul_f32_e32 v34, v41, v217
	v_mul_f32_e32 v35, v41, v218
	v_mul_f32_e32 v36, v41, v219
	v_mul_f32_e32 v37, v41, v222
	v_mul_f32_e32 v38, v41, v223
	v_mul_f32_e32 v39, v41, v140
	v_fmac_f32_e32 v32, v40, v214
	v_fmac_f32_e32 v33, v40, v215
	v_fmac_f32_e32 v34, v40, v216
	v_fmac_f32_e32 v35, v40, v217
	v_fmac_f32_e32 v36, v40, v218
	v_fmac_f32_e32 v37, v40, v219
	v_fmac_f32_e32 v38, v40, v222
	v_fmac_f32_e32 v39, v40, v223
	v_fmac_f32_e32 v32, v42, v216
	v_fmac_f32_e32 v33, v42, v217
	v_fmac_f32_e32 v34, v42, v218
	v_fmac_f32_e32 v35, v42, v219
	v_fmac_f32_e32 v36, v42, v222
	v_fmac_f32_e32 v37, v42, v223
	v_fmac_f32_e32 v38, v42, v140
	v_fmac_f32_e32 v39, v42, v141
	v_fmac_f32_e32 v32, v43, v217
	v_fmac_f32_e32 v33, v43, v218
	v_fmac_f32_e32 v34, v43, v219
	v_fmac_f32_e32 v35, v43, v222
	v_fmac_f32_e32 v36, v43, v223
	v_fmac_f32_e32 v37, v43, v140
	v_fmac_f32_e32 v38, v43, v141
	v_fmac_f32_e32 v39, v43, v232
	v_add_f32_e32 v32, v44, v32
	v_add_f32_e32 v33, v44, v33
	v_add_f32_e32 v34, v44, v34
	v_add_f32_e32 v35, v44, v35
	v_add_f32_e32 v36, v44, v36
	v_add_f32_e32 v37, v44, v37
	v_add_f32_e32 v38, v44, v38
	v_add_f32_e32 v39, v44, v39
	v_cvt_pk_bf16_f32 v32, v32, v33
	v_cvt_pk_bf16_f32 v34, v34, v35
	v_cvt_pk_bf16_f32 v36, v36, v37
	v_cvt_pk_bf16_f32 v38, v38, v39
	ds_write_b16 v240, v32 offset:8064
	ds_write_b16_d16_hi v240, v32 offset:8208
	ds_write_b16 v240, v34 offset:8352
	ds_write_b16_d16_hi v240, v34 offset:8496
	ds_write_b16 v240, v36 offset:8640
	ds_write_b16_d16_hi v240, v36 offset:8784
	ds_write_b16 v240, v38 offset:8928
	ds_write_b16_d16_hi v240, v38 offset:9072
	v_mov_b32_e32 v248, 0xbfb8aa3b
	v_mov_b32_e32 v249, 0xbfb8aa3b
	v_mov_b32_e32 v140, 0x3d372713
	v_mov_b32_e32 v141, 0x3d372713
	s_waitcnt vmcnt(16)
	s_mov_b32 s8, 0x800000
	s_mov_b32 s9, 0x3f317217
	s_mov_b32 s14, 0x7f800000
	v_mul_f32_e32 v32, 0xbfb8aa3b, v45
	v_exp_f32_e32 v32, v32
	s_nop 0
	v_add_f32_e32 v33, 1.0, v32
	v_cmp_gt_f32_e32 vcc, s8, v33
	s_nop 1
	v_cndmask_b32_e64 v34, 0, 32, vcc
	v_ldexp_f32 v34, v33, v34
	v_log_f32_e32 v34, v34
	v_cndmask_b32_e32 v36, 0, v226, vcc
	v_cmp_eq_f32_e32 vcc, 1.0, v33
	v_mul_f32_e32 v35, 0x3f317217, v34
	v_fma_f32 v35, v34, s9, -v35
	v_fmac_f32_e32 v35, 0x3377d1cf, v34
	v_fmac_f32_e32 v35, 0x3f317217, v34
	v_cmp_lt_f32_e64 s[10:11], |v34|, s14
	s_nop 1
	v_cndmask_b32_e64 v34, v34, v35, s[10:11]
	v_add_f32_e32 v35, -1.0, v33
	v_rcp_f32_e32 v35, v35
	v_sub_f32_e32 v34, v34, v36
	v_mul_f32_e32 v34, v32, v34
	v_mul_f32_e32 v34, v34, v35
	v_cndmask_b32_e32 v32, v34, v32, vcc
	v_mul_f32_e32 v246, 0xc138aa3b, v32
	v_mov_b32_e32 v247, v246
	v_mul_f32_e32 v242, 0xbfb8aa3b, v46
	v_mul_f32_e32 v244, 0xbfb8aa3b, v47
	v_mov_b32_e32 v243, v242
	v_mov_b32_e32 v245, v244
	s_waitcnt vmcnt(0)
	s_add_i32 s39, s15, 48
	s_mul_hi_u32 s83, s39, 0x1600
	s_mul_i32 s82, s39, 0x1600
	s_add_u32 s82, s82, s0
	s_addc_u32 s83, s83, s1
	s_add_u32 s82, s82, 0xbc00400
	s_addc_u32 s83, s83, 0
	global_load_ushort v190, v234, s[82:83]
	s_add_u32 s82, s82, 0x1600
	s_addc_u32 s83, s83, 0
	global_load_ushort v191, v234, s[82:83]
	s_add_u32 s82, s82, 0x1600
	s_addc_u32 s83, s83, 0
	global_load_ushort v192, v234, s[82:83]
	s_add_u32 s82, s82, 0x1600
	s_addc_u32 s83, s83, 0
	global_load_ushort v193, v234, s[82:83]
	s_add_u32 s82, s82, 0x1600
	s_addc_u32 s83, s83, 0
	global_load_ushort v194, v234, s[82:83]
	s_add_u32 s82, s82, 0x1600
	s_addc_u32 s83, s83, 0
	global_load_ushort v195, v234, s[82:83]
	s_add_u32 s82, s82, 0x1600
	s_addc_u32 s83, s83, 0
	global_load_ushort v196, v234, s[82:83]
	s_add_u32 s82, s82, 0x1600
	s_addc_u32 s83, s83, 0
	global_load_ushort v197, v234, s[82:83]
	s_add_u32 s82, s82, 0x1600
	s_addc_u32 s83, s83, 0
	global_load_ushort v198, v234, s[82:83]
	s_add_u32 s82, s82, 0x1600
	s_addc_u32 s83, s83, 0
	global_load_ushort v199, v234, s[82:83]
	s_add_u32 s82, s82, 0x1600
	s_addc_u32 s83, s83, 0
	global_load_ushort v200, v234, s[82:83]
	s_add_u32 s82, s82, 0x1600
	s_addc_u32 s83, s83, 0
	global_load_ushort v201, v234, s[82:83]
	s_add_u32 s82, s82, 0x1600
	s_addc_u32 s83, s83, 0
	global_load_ushort v202, v234, s[82:83]
	s_add_u32 s82, s82, 0x1600
	s_addc_u32 s83, s83, 0
	global_load_ushort v203, v234, s[82:83]
	s_add_u32 s82, s82, 0x1600
	s_addc_u32 s83, s83, 0
	global_load_ushort v204, v234, s[82:83]
	s_add_u32 s82, s82, 0x1600
	s_addc_u32 s83, s83, 0
	global_load_ushort v205, v234, s[82:83]
	ds_read_b128 v[32:35], v236 offset:0
	ds_read_b128 v[36:39], v236 offset:64
	s_waitcnt lgkmcnt(0)
; #define LAS __attribute__((address_space(3)))
; #define WAVE_SYNC() asm volatile("s_waitcnt lgkmcnt(0)" ::: "memory")
; __device__ __forceinline__ float sigmoid_f(float x) { return rcpf_(1.f + __expf(-x)); }
; __device__ __forceinline__ f32x4 mfma16(bf16x8 a, bf16x8 b, f32x4 c) { return __builtin_amdgcn_mfma_f32_16x16x32_bf16(a, b, c, 0, 0, 0); }
; template <bool FINAL, int D>
; __device__ __forceinline__ void rg_dir(PREF p, int l, int h, int ch, int sidx, int rowbase  , LAS bf16_t* sXc, LAS float* stg, int lane) {
;     ...
;         const bf16x8 A0 = *(const LAS bf16x8*)(sXc + (mt * 16 + (lane & 15)) * 72 + (lane >> 4) * 8), A1 = *(const LAS bf16x8*)(sXc + (mt * 16 + (lane & 15)) * 72 + 32 + (lane >> 4) * 8);
;         f32x4 ar[4], ai[4];
; #pragma unroll
;         for (int nt = 0; nt < 4; ++nt) { const f32x4 z = {0.f, 0.f, 0.f, 0.f};
;             ar[nt] = mfma16(A0, Br[nt][0], z); ar[nt] = mfma16(A1, Br[nt][1], ar[nt]); ai[nt] = mfma16(A0, Bi[nt][0], z); ai[nt] = mfma16(A1, Bi[nt][1], ai[nt]); }
;         WAVE_SYNC();
; #pragma unroll
;         for (int nt = 0; nt < 4; ++nt)
; #pragma unroll
;             for (int j = 0; j < 4; ++j) { const int o = ((lane >> 4) * 4 + j) * 64 + nt * 16 + (lane & 15); stg[o] = ar[nt][j]; stg[1024 + o] = ai[nt][j]; }
;         WAVE_SYNC();
;         float av[16], iv[16];
; #pragma unroll
;         for (int ti = 0; ti < 16; ++ti) { const int tk = D ? 15 - ti : ti;
;             const float zr = stg[tk * 64 + lane] + ba, zi = stg[1024 + tk * 64 + lane] + bi;
;             const float r = sigmoid_f(zr), ig = sigmoid_f(zi);
	v_mfma_f32_16x16x32_bf16 v[0:3], v[32:35], v[80:83], 0
	v_mfma_f32_16x16x32_bf16 v[4:7], v[32:35], v[88:91], 0
	v_mfma_f32_16x16x32_bf16 v[8:11], v[32:35], v[96:99], 0
	v_mfma_f32_16x16x32_bf16 v[12:15], v[32:35], v[104:107], 0
	v_mfma_f32_16x16x32_bf16 v[16:19], v[32:35], v[112:115], 0
	v_mfma_f32_16x16x32_bf16 v[20:23], v[32:35], v[120:123], 0
	v_mfma_f32_16x16x32_bf16 v[24:27], v[32:35], v[128:131], 0
	v_mfma_f32_16x16x32_bf16 v[28:31], v[32:35], v[136:139], 0
	v_mfma_f32_16x16x32_bf16 v[0:3], v[36:39], v[84:87], v[0:3]
	v_mfma_f32_16x16x32_bf16 v[4:7], v[36:39], v[92:95], v[4:7]
	v_mfma_f32_16x16x32_bf16 v[8:11], v[36:39], v[100:103], v[8:11]
	v_mfma_f32_16x16x32_bf16 v[12:15], v[36:39], v[108:111], v[12:15]
	v_mfma_f32_16x16x32_bf16 v[16:19], v[36:39], v[116:119], v[16:19]
	v_mfma_f32_16x16x32_bf16 v[20:23], v[36:39], v[124:127], v[20:23]
	v_mfma_f32_16x16x32_bf16 v[24:27], v[36:39], v[132:135], v[24:27]
	v_mfma_f32_16x16x32_bf16 v[28:31], v[36:39], v[228:231], v[28:31]
	s_nop 3
	ds_write2_b32 v237, v0, v4 offset0:0 offset1:16
	ds_write2_b32 v237, v8, v12 offset0:32 offset1:48
	ds_write2_b32 v237, v1, v5 offset0:64 offset1:80
	ds_write2_b32 v237, v9, v13 offset0:96 offset1:112
	ds_write2_b32 v237, v2, v6 offset0:128 offset1:144
	ds_write2_b32 v237, v10, v14 offset0:160 offset1:176
	ds_write2_b32 v237, v3, v7 offset0:192 offset1:208
	ds_write2_b32 v237, v11, v15 offset0:224 offset1:240
	ds_write2_b32 v238, v16, v20 offset0:0 offset1:16
	ds_write2_b32 v238, v24, v28 offset0:32 offset1:48
	ds_write2_b32 v238, v17, v21 offset0:64 offset1:80
	ds_write2_b32 v238, v25, v29 offset0:96 offset1:112
	ds_write2_b32 v238, v18, v22 offset0:128 offset1:144
	ds_write2_b32 v238, v26, v30 offset0:160 offset1:176
	ds_write2_b32 v238, v19, v23 offset0:192 offset1:208
	ds_write2_b32 v238, v27, v31 offset0:224 offset1:240
	s_waitcnt lgkmcnt(0)
	ds_read2st64_b32 v[0:1], v239 offset0:36 offset1:37
	ds_read2st64_b32 v[2:3], v239 offset0:38 offset1:39
	ds_read2st64_b32 v[4:5], v239 offset0:40 offset1:41
	ds_read2st64_b32 v[6:7], v239 offset0:42 offset1:43
	ds_read2st64_b32 v[8:9], v239 offset0:44 offset1:45
	ds_read2st64_b32 v[10:11], v239 offset0:46 offset1:47
	ds_read2st64_b32 v[12:13], v239 offset0:48 offset1:49
	ds_read2st64_b32 v[14:15], v239 offset0:50 offset1:51
	ds_read2st64_b32 v[16:17], v239 offset0:52 offset1:53
	ds_read2st64_b32 v[18:19], v239 offset0:54 offset1:55
	ds_read2st64_b32 v[20:21], v239 offset0:56 offset1:57
	ds_read2st64_b32 v[22:23], v239 offset0:58 offset1:59
	ds_read2st64_b32 v[24:25], v239 offset0:60 offset1:61
	ds_read2st64_b32 v[26:27], v239 offset0:62 offset1:63
	ds_read2st64_b32 v[28:29], v239 offset0:64 offset1:65
	ds_read2st64_b32 v[30:31], v239 offset0:66 offset1:67
	ds_read_u16 v48, v240 offset:0
	ds_read_u16 v49, v240 offset:144
	ds_read_u16 v50, v240 offset:288
	ds_read_u16 v51, v240 offset:432
	ds_read_u16 v52, v240 offset:576
	ds_read_u16 v53, v240 offset:720
	ds_read_u16 v54, v240 offset:864
	ds_read_u16 v55, v240 offset:1008
	ds_read_u16 v56, v240 offset:1152
	ds_read_u16 v57, v240 offset:1296
	ds_read_u16 v58, v240 offset:1440
	ds_read_u16 v59, v240 offset:1584
	ds_read_u16 v60, v240 offset:1728
	ds_read_u16 v61, v240 offset:1872
	ds_read_u16 v62, v240 offset:2016
	ds_read_u16 v63, v240 offset:2160
	s_waitcnt lgkmcnt(0)
	v_pk_fma_f32 v[0:1], v[0:1], v[248:249], v[242:243]
	v_pk_fma_f32 v[2:3], v[2:3], v[248:249], v[242:243]
	v_pk_fma_f32 v[4:5], v[4:5], v[248:249], v[242:243]
	v_pk_fma_f32 v[6:7], v[6:7], v[248:249], v[242:243]
	v_pk_fma_f32 v[8:9], v[8:9], v[248:249], v[242:243]
	v_pk_fma_f32 v[10:11], v[10:11], v[248:249], v[242:243]
	v_pk_fma_f32 v[12:13], v[12:13], v[248:249], v[242:243]
	v_pk_fma_f32 v[14:15], v[14:15], v[248:249], v[242:243]
	v_pk_fma_f32 v[16:17], v[16:17], v[248:249], v[244:245]
	v_pk_fma_f32 v[18:19], v[18:19], v[248:249], v[244:245]
	v_pk_fma_f32 v[20:21], v[20:21], v[248:249], v[244:245]
	v_pk_fma_f32 v[22:23], v[22:23], v[248:249], v[244:245]
	v_pk_fma_f32 v[24:25], v[24:25], v[248:249], v[244:245]
	v_pk_fma_f32 v[26:27], v[26:27], v[248:249], v[244:245]
	v_pk_fma_f32 v[28:29], v[28:29], v[248:249], v[244:245]
	v_pk_fma_f32 v[30:31], v[30:31], v[248:249], v[244:245]
	v_exp_f32_e32 v0, v0
	v_exp_f32_e32 v1, v1
	v_exp_f32_e32 v2, v2
	v_exp_f32_e32 v3, v3
	v_exp_f32_e32 v4, v4
	v_exp_f32_e32 v5, v5
	v_exp_f32_e32 v6, v6
	v_exp_f32_e32 v7, v7
	v_exp_f32_e32 v8, v8
	v_exp_f32_e32 v9, v9
	v_exp_f32_e32 v10, v10
	v_exp_f32_e32 v11, v11
	v_exp_f32_e32 v12, v12
	v_exp_f32_e32 v13, v13
	v_exp_f32_e32 v14, v14
	v_exp_f32_e32 v15, v15
	v_exp_f32_e32 v16, v16
	v_exp_f32_e32 v17, v17
	v_exp_f32_e32 v18, v18
	v_exp_f32_e32 v19, v19
	v_exp_f32_e32 v20, v20
	v_exp_f32_e32 v21, v21
	v_exp_f32_e32 v22, v22
	v_exp_f32_e32 v23, v23
	v_exp_f32_e32 v24, v24
	v_exp_f32_e32 v25, v25
	v_exp_f32_e32 v26, v26
	v_exp_f32_e32 v27, v27
	v_exp_f32_e32 v28, v28
	v_exp_f32_e32 v29, v29
	v_exp_f32_e32 v30, v30
	v_exp_f32_e32 v31, v31
	v_pk_add_f32 v[0:1], v[0:1], 1.0 op_sel_hi:[1,0]
	v_pk_add_f32 v[2:3], v[2:3], 1.0 op_sel_hi:[1,0]
	v_pk_add_f32 v[4:5], v[4:5], 1.0 op_sel_hi:[1,0]
	v_pk_add_f32 v[6:7], v[6:7], 1.0 op_sel_hi:[1,0]
	v_pk_add_f32 v[8:9], v[8:9], 1.0 op_sel_hi:[1,0]
	v_pk_add_f32 v[10:11], v[10:11], 1.0 op_sel_hi:[1,0]
	v_pk_add_f32 v[12:13], v[12:13], 1.0 op_sel_hi:[1,0]
	v_pk_add_f32 v[14:15], v[14:15], 1.0 op_sel_hi:[1,0]
	v_pk_add_f32 v[16:17], v[16:17], 1.0 op_sel_hi:[1,0]
	v_pk_add_f32 v[18:19], v[18:19], 1.0 op_sel_hi:[1,0]
	v_pk_add_f32 v[20:21], v[20:21], 1.0 op_sel_hi:[1,0]
	v_pk_add_f32 v[22:23], v[22:23], 1.0 op_sel_hi:[1,0]
	v_pk_add_f32 v[24:25], v[24:25], 1.0 op_sel_hi:[1,0]
; #define LAS __attribute__((address_space(3)))
; #define WAVE_SYNC() asm volatile("s_waitcnt lgkmcnt(0)" ::: "memory")
; __device__ __forceinline__ unsigned f2bf(float f) { unsigned r; asm("v_cvt_pk_bf16_f32 %0, %1, %1" : "=v"(r) : "v"(f)); return r & 0xffffu; }
; __device__ __forceinline__ float sigmoid_f(float x) { return rcpf_(1.f + __expf(-x)); }
; __device__ __forceinline__ float gelu_tanh_f(float x) { const float y = 0.7978845608028654f * (x + 0.044715f * x * x * x); return x * sigmoid_f(2.f * y); }
; template <bool FINAL, int D>
; __device__ __forceinline__ void rg_dir(PREF p, int l, int h, int ch, int sidx, int rowbase  , LAS bf16_t* sXc, LAS float* stg, int lane) {
;     ...
;         const bf16x8 A0 = *(const LAS bf16x8*)(sXc + (mt * 16 + (lane & 15)) * 72 + (lane >> 4) * 8), A1 = *(const LAS bf16x8*)(sXc + (mt * 16 + (lane & 15)) * 72 + 32 + (lane >> 4) * 8);
;         f32x4 ar[4], ai[4];
; #pragma unroll
;         for (int nt = 0; nt < 4; ++nt) { const f32x4 z = {0.f, 0.f, 0.f, 0.f};
;             ar[nt] = mfma16(A0, Br[nt][0], z); ar[nt] = mfma16(A1, Br[nt][1], ar[nt]); ai[nt] = mfma16(A0, Bi[nt][0], z); ai[nt] = mfma16(A1, Bi[nt][1], ai[nt]); }
;         WAVE_SYNC();
; #pragma unroll
;         for (int nt = 0; nt < 4; ++nt)
; #pragma unroll
;             for (int j = 0; j < 4; ++j) { const int o = ((lane >> 4) * 4 + j) * 64 + nt * 16 + (lane & 15); stg[o] = ar[nt][j]; stg[1024 + o] = ai[nt][j]; }
;     ...
;         for (int ti = 0; ti < 16; ++ti) { const int tk = D ? 15 - ti : ti;
;             const float zr = stg[tk * 64 + lane] + ba, zi = stg[1024 + tk * 64 + lane] + bi;
;             const float r = sigmoid_f(zr), ig = sigmoid_f(zi);
;             const float a = __builtin_amdgcn_exp2f(r * sp8);
;             const float xc = bf2f(sXc[(mt * 16 + tk) * 72 + lane]);
;             av[ti] = a; iv[ti] = __builtin_amdgcn_sqrtf(fmaxf(1.f - a * a, 0.f)) * ig * xc;
;             if (FINAL && D == 1) grv[ti] = gelu_tanh_f(grv[ti]);
;         }
; #pragma unroll
;         for (int ti = 0; ti < 16; ++ti) { const int tk = D ? 15 - ti : ti;
;             hc = av[ti] * hc + iv[ti]; Ap *= av[ti];
;             if (FINAL) { const size_t row = (size_t)(rowbase + mt * 16 + tk);
;                 if (D == 0) TMP[row * 512 + ch] = (bf16_t)f2bf(hc);
;                 else MIX[row * DM + ch] = (bf16_t)f2bf(grv[ti] * (hfv[ti] + hc)); }
;         }
	v_pk_add_f32 v[26:27], v[26:27], 1.0 op_sel_hi:[1,0]
	v_pk_add_f32 v[28:29], v[28:29], 1.0 op_sel_hi:[1,0]
	v_pk_add_f32 v[30:31], v[30:31], 1.0 op_sel_hi:[1,0]
	v_rcp_f32_e32 v0, v0
	v_rcp_f32_e32 v1, v1
	v_rcp_f32_e32 v2, v2
	v_rcp_f32_e32 v3, v3
	v_rcp_f32_e32 v4, v4
	v_rcp_f32_e32 v5, v5
	v_rcp_f32_e32 v6, v6
	v_rcp_f32_e32 v7, v7
	v_rcp_f32_e32 v8, v8
	v_rcp_f32_e32 v9, v9
	v_rcp_f32_e32 v10, v10
	v_rcp_f32_e32 v11, v11
	v_rcp_f32_e32 v12, v12
	v_rcp_f32_e32 v13, v13
	v_rcp_f32_e32 v14, v14
	v_rcp_f32_e32 v15, v15
	v_rcp_f32_e32 v16, v16
	v_rcp_f32_e32 v17, v17
	v_rcp_f32_e32 v18, v18
	v_rcp_f32_e32 v19, v19
	v_rcp_f32_e32 v20, v20
	v_rcp_f32_e32 v21, v21
	v_rcp_f32_e32 v22, v22
	v_rcp_f32_e32 v23, v23
	v_rcp_f32_e32 v24, v24
	v_rcp_f32_e32 v25, v25
	v_rcp_f32_e32 v26, v26
	v_rcp_f32_e32 v27, v27
	v_rcp_f32_e32 v28, v28
	v_rcp_f32_e32 v29, v29
	v_rcp_f32_e32 v30, v30
	v_rcp_f32_e32 v31, v31
	v_pk_mul_f32 v[0:1], v[246:247], v[0:1]
	v_pk_mul_f32 v[2:3], v[246:247], v[2:3]
	v_pk_mul_f32 v[4:5], v[246:247], v[4:5]
	v_pk_mul_f32 v[6:7], v[246:247], v[6:7]
	v_pk_mul_f32 v[8:9], v[246:247], v[8:9]
	v_pk_mul_f32 v[10:11], v[246:247], v[10:11]
	v_pk_mul_f32 v[12:13], v[246:247], v[12:13]
	v_pk_mul_f32 v[14:15], v[246:247], v[14:15]
	v_lshlrev_b32_e32 v48, 16, v48
	v_lshlrev_b32_e32 v49, 16, v49
	v_lshlrev_b32_e32 v50, 16, v50
	v_lshlrev_b32_e32 v51, 16, v51
	v_lshlrev_b32_e32 v52, 16, v52
	v_lshlrev_b32_e32 v53, 16, v53
	v_lshlrev_b32_e32 v54, 16, v54
	v_lshlrev_b32_e32 v55, 16, v55
	v_lshlrev_b32_e32 v56, 16, v56
	v_lshlrev_b32_e32 v57, 16, v57
	v_lshlrev_b32_e32 v58, 16, v58
	v_lshlrev_b32_e32 v59, 16, v59
	v_lshlrev_b32_e32 v60, 16, v60
	v_lshlrev_b32_e32 v61, 16, v61
	v_lshlrev_b32_e32 v62, 16, v62
	v_lshlrev_b32_e32 v63, 16, v63
	v_exp_f32_e32 v0, v0
	v_exp_f32_e32 v1, v1
	v_exp_f32_e32 v2, v2
	v_exp_f32_e32 v3, v3
	v_exp_f32_e32 v4, v4
	v_exp_f32_e32 v5, v5
	v_exp_f32_e32 v6, v6
	v_exp_f32_e32 v7, v7
	v_exp_f32_e32 v8, v8
	v_exp_f32_e32 v9, v9
	v_exp_f32_e32 v10, v10
	v_exp_f32_e32 v11, v11
	v_exp_f32_e32 v12, v12
	v_exp_f32_e32 v13, v13
	v_exp_f32_e32 v14, v14
	v_exp_f32_e32 v15, v15
	v_fma_f32 v32, -v0, v0, 1.0 clamp
	v_fma_f32 v33, -v1, v1, 1.0 clamp
	v_fma_f32 v34, -v2, v2, 1.0 clamp
	v_fma_f32 v35, -v3, v3, 1.0 clamp
	v_fma_f32 v36, -v4, v4, 1.0 clamp
	v_fma_f32 v37, -v5, v5, 1.0 clamp
	v_fma_f32 v38, -v6, v6, 1.0 clamp
	v_fma_f32 v39, -v7, v7, 1.0 clamp
	v_fma_f32 v40, -v8, v8, 1.0 clamp
	v_fma_f32 v41, -v9, v9, 1.0 clamp
	v_fma_f32 v42, -v10, v10, 1.0 clamp
	v_fma_f32 v43, -v11, v11, 1.0 clamp
	v_fma_f32 v44, -v12, v12, 1.0 clamp
	v_fma_f32 v45, -v13, v13, 1.0 clamp
	v_fma_f32 v46, -v14, v14, 1.0 clamp
	v_fma_f32 v47, -v15, v15, 1.0 clamp
	v_sqrt_f32_e32 v32, v32
	v_sqrt_f32_e32 v33, v33
	v_sqrt_f32_e32 v34, v34
	v_sqrt_f32_e32 v35, v35
	v_sqrt_f32_e32 v36, v36
	v_sqrt_f32_e32 v37, v37
	v_sqrt_f32_e32 v38, v38
	v_sqrt_f32_e32 v39, v39
	v_sqrt_f32_e32 v40, v40
	v_sqrt_f32_e32 v41, v41
	v_sqrt_f32_e32 v42, v42
	v_sqrt_f32_e32 v43, v43
	v_sqrt_f32_e32 v44, v44
	v_sqrt_f32_e32 v45, v45
	v_sqrt_f32_e32 v46, v46
	v_sqrt_f32_e32 v47, v47
	s_nop 0
	v_pk_mul_f32 v[16:17], v[16:17], v[32:33]
	v_pk_mul_f32 v[18:19], v[18:19], v[34:35]
	v_pk_mul_f32 v[20:21], v[20:21], v[36:37]
	v_pk_mul_f32 v[22:23], v[22:23], v[38:39]
	v_pk_mul_f32 v[24:25], v[24:25], v[40:41]
	v_pk_mul_f32 v[26:27], v[26:27], v[42:43]
	v_pk_mul_f32 v[28:29], v[28:29], v[44:45]
	v_pk_mul_f32 v[30:31], v[30:31], v[46:47]
	v_pk_mul_f32 v[16:17], v[16:17], v[48:49]
	v_pk_mul_f32 v[18:19], v[18:19], v[50:51]
	v_pk_mul_f32 v[20:21], v[20:21], v[52:53]
	v_pk_mul_f32 v[22:23], v[22:23], v[54:55]
	v_pk_mul_f32 v[24:25], v[24:25], v[56:57]
	v_pk_mul_f32 v[26:27], v[26:27], v[58:59]
	v_pk_mul_f32 v[28:29], v[28:29], v[60:61]
	v_pk_mul_f32 v[30:31], v[30:31], v[62:63]
	v_fma_f32 v32, v0, v250, v16
	v_fma_f32 v250, v1, v32, v17
	v_cvt_pk_bf16_f32 v158, v32, v250
	v_fma_f32 v32, v2, v250, v18
	v_fma_f32 v250, v3, v32, v19
	v_cvt_pk_bf16_f32 v159, v32, v250
	v_fma_f32 v32, v4, v250, v20
	v_fma_f32 v250, v5, v32, v21
	v_cvt_pk_bf16_f32 v160, v32, v250
	v_fma_f32 v32, v6, v250, v22
	v_fma_f32 v250, v7, v32, v23
	v_cvt_pk_bf16_f32 v161, v32, v250
	v_fma_f32 v32, v8, v250, v24
	v_fma_f32 v250, v9, v32, v25
	v_cvt_pk_bf16_f32 v162, v32, v250
	v_fma_f32 v32, v10, v250, v26
	v_fma_f32 v250, v11, v32, v27
	v_cvt_pk_bf16_f32 v163, v32, v250
	v_fma_f32 v32, v12, v250, v28
	v_fma_f32 v250, v13, v32, v29
	v_cvt_pk_bf16_f32 v164, v32, v250
	v_fma_f32 v32, v14, v250, v30
	v_fma_f32 v250, v15, v32, v31
	v_cvt_pk_bf16_f32 v165, v32, v250
	ds_read_b128 v[32:35], v236 offset:2304
	ds_read_b128 v[36:39], v236 offset:2368
	s_waitcnt lgkmcnt(0)
	v_mfma_f32_16x16x32_bf16 v[0:3], v[32:35], v[80:83], 0
	v_mfma_f32_16x16x32_bf16 v[4:7], v[32:35], v[88:91], 0
	v_mfma_f32_16x16x32_bf16 v[8:11], v[32:35], v[96:99], 0
	v_mfma_f32_16x16x32_bf16 v[12:15], v[32:35], v[104:107], 0
	v_mfma_f32_16x16x32_bf16 v[16:19], v[32:35], v[112:115], 0
	v_mfma_f32_16x16x32_bf16 v[20:23], v[32:35], v[120:123], 0
	v_mfma_f32_16x16x32_bf16 v[24:27], v[32:35], v[128:131], 0
	v_mfma_f32_16x16x32_bf16 v[28:31], v[32:35], v[136:139], 0
	v_mfma_f32_16x16x32_bf16 v[0:3], v[36:39], v[84:87], v[0:3]
	v_mfma_f32_16x16x32_bf16 v[4:7], v[36:39], v[92:95], v[4:7]
	v_mfma_f32_16x16x32_bf16 v[8:11], v[36:39], v[100:103], v[8:11]
	v_mfma_f32_16x16x32_bf16 v[12:15], v[36:39], v[108:111], v[12:15]
	v_mfma_f32_16x16x32_bf16 v[16:19], v[36:39], v[116:119], v[16:19]
	v_mfma_f32_16x16x32_bf16 v[20:23], v[36:39], v[124:127], v[20:23]
	v_mfma_f32_16x16x32_bf16 v[24:27], v[36:39], v[132:135], v[24:27]
	v_mfma_f32_16x16x32_bf16 v[28:31], v[36:39], v[228:231], v[28:31]
	s_nop 3
	ds_write2_b32 v237, v0, v4 offset0:0 offset1:16
	ds_write2_b32 v237, v8, v12 offset0:32 offset1:48
	ds_write2_b32 v237, v1, v5 offset0:64 offset1:80
	ds_write2_b32 v237, v9, v13 offset0:96 offset1:112
	ds_write2_b32 v237, v2, v6 offset0:128 offset1:144
	ds_write2_b32 v237, v10, v14 offset0:160 offset1:176
	ds_write2_b32 v237, v3, v7 offset0:192 offset1:208
	ds_write2_b32 v237, v11, v15 offset0:224 offset1:240
	ds_write2_b32 v238, v16, v20 offset0:0 offset1:16
	ds_write2_b32 v238, v24, v28 offset0:32 offset1:48
	ds_write2_b32 v238, v17, v21 offset0:64 offset1:80
	ds_write2_b32 v238, v25, v29 offset0:96 offset1:112
	ds_write2_b32 v238, v18, v22 offset0:128 offset1:144
	ds_write2_b32 v238, v26, v30 offset0:160 offset1:176
	ds_write2_b32 v238, v19, v23 offset0:192 offset1:208
	ds_write2_b32 v238, v27, v31 offset0:224 offset1:240
	s_waitcnt lgkmcnt(0)
; #define WAVE_SYNC() asm volatile("s_waitcnt lgkmcnt(0)" ::: "memory")
; __device__ __forceinline__ float sigmoid_f(float x) { return rcpf_(1.f + __expf(-x)); }
; template <bool FINAL, int D>
; __device__ __forceinline__ void rg_dir(PREF p, int l, int h, int ch, int sidx, int rowbase  , LAS bf16_t* sXc, LAS float* stg, int lane) {
;     ...
;             for (int j = 0; j < 4; ++j) { const int o = ((lane >> 4) * 4 + j) * 64 + nt * 16 + (lane & 15); stg[o] = ar[nt][j]; stg[1024 + o] = ai[nt][j]; }
;         WAVE_SYNC();
;         float av[16], iv[16];
; #pragma unroll
;         for (int ti = 0; ti < 16; ++ti) { const int tk = D ? 15 - ti : ti;
;             const float zr = stg[tk * 64 + lane] + ba, zi = stg[1024 + tk * 64 + lane] + bi;
;             const float r = sigmoid_f(zr), ig = sigmoid_f(zi);
;             const float a = __builtin_amdgcn_exp2f(r * sp8);
;             const float xc = bf2f(sXc[(mt * 16 + tk) * 72 + lane]);
;             av[ti] = a; iv[ti] = __builtin_amdgcn_sqrtf(fmaxf(1.f - a * a, 0.f)) * ig * xc;
	ds_read2st64_b32 v[0:1], v239 offset0:36 offset1:37
	ds_read2st64_b32 v[2:3], v239 offset0:38 offset1:39
	ds_read2st64_b32 v[4:5], v239 offset0:40 offset1:41
	ds_read2st64_b32 v[6:7], v239 offset0:42 offset1:43
	ds_read2st64_b32 v[8:9], v239 offset0:44 offset1:45
	ds_read2st64_b32 v[10:11], v239 offset0:46 offset1:47
	ds_read2st64_b32 v[12:13], v239 offset0:48 offset1:49
	ds_read2st64_b32 v[14:15], v239 offset0:50 offset1:51
	ds_read2st64_b32 v[16:17], v239 offset0:52 offset1:53
	ds_read2st64_b32 v[18:19], v239 offset0:54 offset1:55
	ds_read2st64_b32 v[20:21], v239 offset0:56 offset1:57
	ds_read2st64_b32 v[22:23], v239 offset0:58 offset1:59
	ds_read2st64_b32 v[24:25], v239 offset0:60 offset1:61
	ds_read2st64_b32 v[26:27], v239 offset0:62 offset1:63
	ds_read2st64_b32 v[28:29], v239 offset0:64 offset1:65
	ds_read2st64_b32 v[30:31], v239 offset0:66 offset1:67
	ds_read_u16_d16_hi v48, v240 offset:2304
	ds_read_u16_d16_hi v49, v240 offset:2448
	ds_read_u16_d16_hi v50, v240 offset:2592
	ds_read_u16_d16_hi v51, v240 offset:2736
	ds_read_u16_d16_hi v52, v240 offset:2880
	ds_read_u16_d16_hi v53, v240 offset:3024
	ds_read_u16_d16_hi v54, v240 offset:3168
	ds_read_u16_d16_hi v55, v240 offset:3312
	ds_read_u16_d16_hi v56, v240 offset:3456
	ds_read_u16_d16_hi v57, v240 offset:3600
	ds_read_u16_d16_hi v58, v240 offset:3744
	ds_read_u16_d16_hi v59, v240 offset:3888
	ds_read_u16_d16_hi v60, v240 offset:4032
	ds_read_u16_d16_hi v61, v240 offset:4176
	ds_read_u16_d16_hi v62, v240 offset:4320
	ds_read_u16_d16_hi v63, v240 offset:4464
	s_waitcnt lgkmcnt(0)
	v_pk_fma_f32 v[0:1], v[0:1], v[248:249], v[242:243]
	v_pk_fma_f32 v[2:3], v[2:3], v[248:249], v[242:243]
	v_pk_fma_f32 v[4:5], v[4:5], v[248:249], v[242:243]
	v_pk_fma_f32 v[6:7], v[6:7], v[248:249], v[242:243]
	v_pk_fma_f32 v[8:9], v[8:9], v[248:249], v[242:243]
	v_pk_fma_f32 v[10:11], v[10:11], v[248:249], v[242:243]
	v_pk_fma_f32 v[12:13], v[12:13], v[248:249], v[242:243]
	v_pk_fma_f32 v[14:15], v[14:15], v[248:249], v[242:243]
	v_pk_fma_f32 v[16:17], v[16:17], v[248:249], v[244:245]
	v_pk_fma_f32 v[18:19], v[18:19], v[248:249], v[244:245]
	v_pk_fma_f32 v[20:21], v[20:21], v[248:249], v[244:245]
	v_pk_fma_f32 v[22:23], v[22:23], v[248:249], v[244:245]
	v_pk_fma_f32 v[24:25], v[24:25], v[248:249], v[244:245]
	v_pk_fma_f32 v[26:27], v[26:27], v[248:249], v[244:245]
	v_pk_fma_f32 v[28:29], v[28:29], v[248:249], v[244:245]
	v_pk_fma_f32 v[30:31], v[30:31], v[248:249], v[244:245]
	v_exp_f32_e32 v0, v0
	v_exp_f32_e32 v1, v1
	v_exp_f32_e32 v2, v2
	v_exp_f32_e32 v3, v3
	v_exp_f32_e32 v4, v4
	v_exp_f32_e32 v5, v5
	v_exp_f32_e32 v6, v6
	v_exp_f32_e32 v7, v7
	v_exp_f32_e32 v8, v8
	v_exp_f32_e32 v9, v9
	v_exp_f32_e32 v10, v10
	v_exp_f32_e32 v11, v11
	v_exp_f32_e32 v12, v12
	v_exp_f32_e32 v13, v13
	v_exp_f32_e32 v14, v14
	v_exp_f32_e32 v15, v15
	v_exp_f32_e32 v16, v16
	v_exp_f32_e32 v17, v17
	v_exp_f32_e32 v18, v18
	v_exp_f32_e32 v19, v19
	v_exp_f32_e32 v20, v20
	v_exp_f32_e32 v21, v21
	v_exp_f32_e32 v22, v22
	v_exp_f32_e32 v23, v23
	v_exp_f32_e32 v24, v24
	v_exp_f32_e32 v25, v25
	v_exp_f32_e32 v26, v26
	v_exp_f32_e32 v27, v27
	v_exp_f32_e32 v28, v28
	v_exp_f32_e32 v29, v29
	v_exp_f32_e32 v30, v30
	v_exp_f32_e32 v31, v31
	v_pk_add_f32 v[0:1], v[0:1], 1.0 op_sel_hi:[1,0]
	v_pk_add_f32 v[2:3], v[2:3], 1.0 op_sel_hi:[1,0]
	v_pk_add_f32 v[4:5], v[4:5], 1.0 op_sel_hi:[1,0]
	v_pk_add_f32 v[6:7], v[6:7], 1.0 op_sel_hi:[1,0]
	v_pk_add_f32 v[8:9], v[8:9], 1.0 op_sel_hi:[1,0]
	v_pk_add_f32 v[10:11], v[10:11], 1.0 op_sel_hi:[1,0]
	v_pk_add_f32 v[12:13], v[12:13], 1.0 op_sel_hi:[1,0]
	v_pk_add_f32 v[14:15], v[14:15], 1.0 op_sel_hi:[1,0]
	v_pk_add_f32 v[16:17], v[16:17], 1.0 op_sel_hi:[1,0]
	v_pk_add_f32 v[18:19], v[18:19], 1.0 op_sel_hi:[1,0]
	v_pk_add_f32 v[20:21], v[20:21], 1.0 op_sel_hi:[1,0]
	v_pk_add_f32 v[22:23], v[22:23], 1.0 op_sel_hi:[1,0]
	v_pk_add_f32 v[24:25], v[24:25], 1.0 op_sel_hi:[1,0]
	v_pk_add_f32 v[26:27], v[26:27], 1.0 op_sel_hi:[1,0]
	v_pk_add_f32 v[28:29], v[28:29], 1.0 op_sel_hi:[1,0]
	v_pk_add_f32 v[30:31], v[30:31], 1.0 op_sel_hi:[1,0]
	v_rcp_f32_e32 v0, v0
	v_rcp_f32_e32 v1, v1
	v_rcp_f32_e32 v2, v2
	v_rcp_f32_e32 v3, v3
	v_rcp_f32_e32 v4, v4
	v_rcp_f32_e32 v5, v5
	v_rcp_f32_e32 v6, v6
	v_rcp_f32_e32 v7, v7
	v_rcp_f32_e32 v8, v8
	v_rcp_f32_e32 v9, v9
	v_rcp_f32_e32 v10, v10
	v_rcp_f32_e32 v11, v11
	v_rcp_f32_e32 v12, v12
	v_rcp_f32_e32 v13, v13
	v_rcp_f32_e32 v14, v14
	v_rcp_f32_e32 v15, v15
	v_rcp_f32_e32 v16, v16
	v_rcp_f32_e32 v17, v17
	v_rcp_f32_e32 v18, v18
	v_rcp_f32_e32 v19, v19
	v_rcp_f32_e32 v20, v20
	v_rcp_f32_e32 v21, v21
	v_rcp_f32_e32 v22, v22
	v_rcp_f32_e32 v23, v23
	v_rcp_f32_e32 v24, v24
	v_rcp_f32_e32 v25, v25
	v_rcp_f32_e32 v26, v26
	v_rcp_f32_e32 v27, v27
	v_rcp_f32_e32 v28, v28
	v_rcp_f32_e32 v29, v29
	v_rcp_f32_e32 v30, v30
	v_rcp_f32_e32 v31, v31
	v_pk_mul_f32 v[0:1], v[246:247], v[0:1]
	v_pk_mul_f32 v[2:3], v[246:247], v[2:3]
	v_pk_mul_f32 v[4:5], v[246:247], v[4:5]
	v_pk_mul_f32 v[6:7], v[246:247], v[6:7]
	v_pk_mul_f32 v[8:9], v[246:247], v[8:9]
	v_pk_mul_f32 v[10:11], v[246:247], v[10:11]
	v_pk_mul_f32 v[12:13], v[246:247], v[12:13]
	v_pk_mul_f32 v[14:15], v[246:247], v[14:15]
	v_exp_f32_e32 v0, v0
	v_exp_f32_e32 v1, v1
	v_exp_f32_e32 v2, v2
	v_exp_f32_e32 v3, v3
	v_exp_f32_e32 v4, v4
	v_exp_f32_e32 v5, v5
	v_exp_f32_e32 v6, v6
	v_exp_f32_e32 v7, v7
	v_exp_f32_e32 v8, v8
	v_exp_f32_e32 v9, v9
	v_exp_f32_e32 v10, v10
	v_exp_f32_e32 v11, v11
	v_exp_f32_e32 v12, v12
	v_exp_f32_e32 v13, v13
	v_exp_f32_e32 v14, v14
	v_exp_f32_e32 v15, v15
	v_fma_f32 v32, -v0, v0, 1.0 clamp
	v_fma_f32 v33, -v1, v1, 1.0 clamp
	v_fma_f32 v34, -v2, v2, 1.0 clamp
	v_fma_f32 v35, -v3, v3, 1.0 clamp
; #define LAS __attribute__((address_space(3)))
; #define WAVE_SYNC() asm volatile("s_waitcnt lgkmcnt(0)" ::: "memory")
; __device__ __forceinline__ unsigned f2bf(float f) { unsigned r; asm("v_cvt_pk_bf16_f32 %0, %1, %1" : "=v"(r) : "v"(f)); return r & 0xffffu; }
; __device__ __forceinline__ float gelu_tanh_f(float x) { const float y = 0.7978845608028654f * (x + 0.044715f * x * x * x); return x * sigmoid_f(2.f * y); }
; __device__ __forceinline__ f32x4 mfma16(bf16x8 a, bf16x8 b, f32x4 c) { return __builtin_amdgcn_mfma_f32_16x16x32_bf16(a, b, c, 0, 0, 0); }
; template <bool FINAL, int D>
; __device__ __forceinline__ void rg_dir(PREF p, int l, int h, int ch, int sidx, int rowbase  , LAS bf16_t* sXc, LAS float* stg, int lane) {
;     ...
;         const bf16x8 A0 = *(const LAS bf16x8*)(sXc + (mt * 16 + (lane & 15)) * 72 + (lane >> 4) * 8), A1 = *(const LAS bf16x8*)(sXc + (mt * 16 + (lane & 15)) * 72 + 32 + (lane >> 4) * 8);
;         f32x4 ar[4], ai[4];
; #pragma unroll
;         for (int nt = 0; nt < 4; ++nt) { const f32x4 z = {0.f, 0.f, 0.f, 0.f};
;             ar[nt] = mfma16(A0, Br[nt][0], z); ar[nt] = mfma16(A1, Br[nt][1], ar[nt]); ai[nt] = mfma16(A0, Bi[nt][0], z); ai[nt] = mfma16(A1, Bi[nt][1], ai[nt]); }
;         WAVE_SYNC();
; #pragma unroll
;         for (int nt = 0; nt < 4; ++nt)
; #pragma unroll
;             for (int j = 0; j < 4; ++j) { const int o = ((lane >> 4) * 4 + j) * 64 + nt * 16 + (lane & 15); stg[o] = ar[nt][j]; stg[1024 + o] = ai[nt][j]; }
;     ...
;             av[ti] = a; iv[ti] = __builtin_amdgcn_sqrtf(fmaxf(1.f - a * a, 0.f)) * ig * xc;
;             if (FINAL && D == 1) grv[ti] = gelu_tanh_f(grv[ti]);
;         }
; #pragma unroll
;         for (int ti = 0; ti < 16; ++ti) { const int tk = D ? 15 - ti : ti;
;             hc = av[ti] * hc + iv[ti]; Ap *= av[ti];
;             if (FINAL) { const size_t row = (size_t)(rowbase + mt * 16 + tk);
;                 if (D == 0) TMP[row * 512 + ch] = (bf16_t)f2bf(hc);
;                 else MIX[row * DM + ch] = (bf16_t)f2bf(grv[ti] * (hfv[ti] + hc)); }
;         }
	v_fma_f32 v36, -v4, v4, 1.0 clamp
	v_fma_f32 v37, -v5, v5, 1.0 clamp
	v_fma_f32 v38, -v6, v6, 1.0 clamp
	v_fma_f32 v39, -v7, v7, 1.0 clamp
	v_fma_f32 v40, -v8, v8, 1.0 clamp
	v_fma_f32 v41, -v9, v9, 1.0 clamp
	v_fma_f32 v42, -v10, v10, 1.0 clamp
	v_fma_f32 v43, -v11, v11, 1.0 clamp
	v_fma_f32 v44, -v12, v12, 1.0 clamp
	v_fma_f32 v45, -v13, v13, 1.0 clamp
	v_fma_f32 v46, -v14, v14, 1.0 clamp
	v_fma_f32 v47, -v15, v15, 1.0 clamp
	v_sqrt_f32_e32 v32, v32
	v_sqrt_f32_e32 v33, v33
	v_sqrt_f32_e32 v34, v34
	v_sqrt_f32_e32 v35, v35
	v_sqrt_f32_e32 v36, v36
	v_sqrt_f32_e32 v37, v37
	v_sqrt_f32_e32 v38, v38
	v_sqrt_f32_e32 v39, v39
	v_sqrt_f32_e32 v40, v40
	v_sqrt_f32_e32 v41, v41
	v_sqrt_f32_e32 v42, v42
	v_sqrt_f32_e32 v43, v43
	v_sqrt_f32_e32 v44, v44
	v_sqrt_f32_e32 v45, v45
	v_sqrt_f32_e32 v46, v46
	v_sqrt_f32_e32 v47, v47
	s_nop 0
	v_pk_mul_f32 v[16:17], v[16:17], v[32:33]
	v_pk_mul_f32 v[18:19], v[18:19], v[34:35]
	v_pk_mul_f32 v[20:21], v[20:21], v[36:37]
	v_pk_mul_f32 v[22:23], v[22:23], v[38:39]
	v_pk_mul_f32 v[24:25], v[24:25], v[40:41]
	v_pk_mul_f32 v[26:27], v[26:27], v[42:43]
	v_pk_mul_f32 v[28:29], v[28:29], v[44:45]
	v_pk_mul_f32 v[30:31], v[30:31], v[46:47]
	v_pk_mul_f32 v[16:17], v[16:17], v[48:49]
	v_pk_mul_f32 v[18:19], v[18:19], v[50:51]
	v_pk_mul_f32 v[20:21], v[20:21], v[52:53]
	v_pk_mul_f32 v[22:23], v[22:23], v[54:55]
	v_pk_mul_f32 v[24:25], v[24:25], v[56:57]
	v_pk_mul_f32 v[26:27], v[26:27], v[58:59]
	v_pk_mul_f32 v[28:29], v[28:29], v[60:61]
	v_pk_mul_f32 v[30:31], v[30:31], v[62:63]
	v_fma_f32 v32, v0, v250, v16
	v_fma_f32 v250, v1, v32, v17
	v_cvt_pk_bf16_f32 v166, v32, v250
	v_fma_f32 v32, v2, v250, v18
	v_fma_f32 v250, v3, v32, v19
	v_cvt_pk_bf16_f32 v167, v32, v250
	v_fma_f32 v32, v4, v250, v20
	v_fma_f32 v250, v5, v32, v21
	v_cvt_pk_bf16_f32 v168, v32, v250
	v_fma_f32 v32, v6, v250, v22
	v_fma_f32 v250, v7, v32, v23
	v_cvt_pk_bf16_f32 v169, v32, v250
	v_fma_f32 v32, v8, v250, v24
	v_fma_f32 v250, v9, v32, v25
	v_cvt_pk_bf16_f32 v170, v32, v250
	v_fma_f32 v32, v10, v250, v26
	v_fma_f32 v250, v11, v32, v27
	v_cvt_pk_bf16_f32 v171, v32, v250
	v_fma_f32 v32, v12, v250, v28
	v_fma_f32 v250, v13, v32, v29
	v_cvt_pk_bf16_f32 v172, v32, v250
	v_fma_f32 v32, v14, v250, v30
	v_fma_f32 v250, v15, v32, v31
	v_cvt_pk_bf16_f32 v173, v32, v250
	ds_read_b128 v[32:35], v236 offset:4608
	ds_read_b128 v[36:39], v236 offset:4672
	s_waitcnt lgkmcnt(0)
	v_mfma_f32_16x16x32_bf16 v[0:3], v[32:35], v[80:83], 0
	v_mfma_f32_16x16x32_bf16 v[4:7], v[32:35], v[88:91], 0
	v_mfma_f32_16x16x32_bf16 v[8:11], v[32:35], v[96:99], 0
	v_mfma_f32_16x16x32_bf16 v[12:15], v[32:35], v[104:107], 0
	v_mfma_f32_16x16x32_bf16 v[16:19], v[32:35], v[112:115], 0
	v_mfma_f32_16x16x32_bf16 v[20:23], v[32:35], v[120:123], 0
	v_mfma_f32_16x16x32_bf16 v[24:27], v[32:35], v[128:131], 0
	v_mfma_f32_16x16x32_bf16 v[28:31], v[32:35], v[136:139], 0
	v_mfma_f32_16x16x32_bf16 v[0:3], v[36:39], v[84:87], v[0:3]
	v_mfma_f32_16x16x32_bf16 v[4:7], v[36:39], v[92:95], v[4:7]
	v_mfma_f32_16x16x32_bf16 v[8:11], v[36:39], v[100:103], v[8:11]
	v_mfma_f32_16x16x32_bf16 v[12:15], v[36:39], v[108:111], v[12:15]
	v_mfma_f32_16x16x32_bf16 v[16:19], v[36:39], v[116:119], v[16:19]
	v_mfma_f32_16x16x32_bf16 v[20:23], v[36:39], v[124:127], v[20:23]
	v_mfma_f32_16x16x32_bf16 v[24:27], v[36:39], v[132:135], v[24:27]
	v_mfma_f32_16x16x32_bf16 v[28:31], v[36:39], v[228:231], v[28:31]
	s_nop 3
	ds_write2_b32 v237, v0, v4 offset0:0 offset1:16
	ds_write2_b32 v237, v8, v12 offset0:32 offset1:48
	ds_write2_b32 v237, v1, v5 offset0:64 offset1:80
	ds_write2_b32 v237, v9, v13 offset0:96 offset1:112
	ds_write2_b32 v237, v2, v6 offset0:128 offset1:144
	ds_write2_b32 v237, v10, v14 offset0:160 offset1:176
	ds_write2_b32 v237, v3, v7 offset0:192 offset1:208
	ds_write2_b32 v237, v11, v15 offset0:224 offset1:240
	ds_write2_b32 v238, v16, v20 offset0:0 offset1:16
	ds_write2_b32 v238, v24, v28 offset0:32 offset1:48
	ds_write2_b32 v238, v17, v21 offset0:64 offset1:80
	ds_write2_b32 v238, v25, v29 offset0:96 offset1:112
	ds_write2_b32 v238, v18, v22 offset0:128 offset1:144
	ds_write2_b32 v238, v26, v30 offset0:160 offset1:176
	ds_write2_b32 v238, v19, v23 offset0:192 offset1:208
	ds_write2_b32 v238, v27, v31 offset0:224 offset1:240
	s_waitcnt lgkmcnt(0)
	ds_read2st64_b32 v[0:1], v239 offset0:36 offset1:37
	ds_read2st64_b32 v[2:3], v239 offset0:38 offset1:39
	ds_read2st64_b32 v[4:5], v239 offset0:40 offset1:41
	ds_read2st64_b32 v[6:7], v239 offset0:42 offset1:43
	ds_read2st64_b32 v[8:9], v239 offset0:44 offset1:45
	ds_read2st64_b32 v[10:11], v239 offset0:46 offset1:47
	ds_read2st64_b32 v[12:13], v239 offset0:48 offset1:49
	ds_read2st64_b32 v[14:15], v239 offset0:50 offset1:51
	ds_read2st64_b32 v[16:17], v239 offset0:52 offset1:53
	ds_read2st64_b32 v[18:19], v239 offset0:54 offset1:55
	ds_read2st64_b32 v[20:21], v239 offset0:56 offset1:57
	ds_read2st64_b32 v[22:23], v239 offset0:58 offset1:59
	ds_read2st64_b32 v[24:25], v239 offset0:60 offset1:61
	ds_read2st64_b32 v[26:27], v239 offset0:62 offset1:63
	ds_read2st64_b32 v[28:29], v239 offset0:64 offset1:65
	ds_read2st64_b32 v[30:31], v239 offset0:66 offset1:67
	ds_read_u16_d16_hi v48, v240 offset:4608
	ds_read_u16_d16_hi v49, v240 offset:4752
	ds_read_u16_d16_hi v50, v240 offset:4896
	ds_read_u16_d16_hi v51, v240 offset:5040
	ds_read_u16_d16_hi v52, v240 offset:5184
	ds_read_u16_d16_hi v53, v240 offset:5328
	ds_read_u16_d16_hi v54, v240 offset:5472
	ds_read_u16_d16_hi v55, v240 offset:5616
	ds_read_u16_d16_hi v56, v240 offset:5760
	ds_read_u16_d16_hi v57, v240 offset:5904
	ds_read_u16_d16_hi v58, v240 offset:6048
	ds_read_u16_d16_hi v59, v240 offset:6192
	ds_read_u16_d16_hi v60, v240 offset:6336
	ds_read_u16_d16_hi v61, v240 offset:6480
	ds_read_u16_d16_hi v62, v240 offset:6624
	ds_read_u16_d16_hi v63, v240 offset:6768
	s_waitcnt lgkmcnt(0)
; __device__ __forceinline__ unsigned f2bf(float f) { unsigned r; asm("v_cvt_pk_bf16_f32 %0, %1, %1" : "=v"(r) : "v"(f)); return r & 0xffffu; }
; __device__ __forceinline__ float sigmoid_f(float x) { return rcpf_(1.f + __expf(-x)); }
; __device__ __forceinline__ float gelu_tanh_f(float x) { const float y = 0.7978845608028654f * (x + 0.044715f * x * x * x); return x * sigmoid_f(2.f * y); }
; template <bool FINAL, int D>
; __device__ __forceinline__ void rg_dir(PREF p, int l, int h, int ch, int sidx, int rowbase  , LAS bf16_t* sXc, LAS float* stg, int lane) {
;     ...
;         for (int ti = 0; ti < 16; ++ti) { const int tk = D ? 15 - ti : ti;
;             const float zr = stg[tk * 64 + lane] + ba, zi = stg[1024 + tk * 64 + lane] + bi;
;             const float r = sigmoid_f(zr), ig = sigmoid_f(zi);
;             const float a = __builtin_amdgcn_exp2f(r * sp8);
;             const float xc = bf2f(sXc[(mt * 16 + tk) * 72 + lane]);
;             av[ti] = a; iv[ti] = __builtin_amdgcn_sqrtf(fmaxf(1.f - a * a, 0.f)) * ig * xc;
;             if (FINAL && D == 1) grv[ti] = gelu_tanh_f(grv[ti]);
;         }
; #pragma unroll
;         for (int ti = 0; ti < 16; ++ti) { const int tk = D ? 15 - ti : ti;
;             hc = av[ti] * hc + iv[ti]; Ap *= av[ti];
;             if (FINAL) { const size_t row = (size_t)(rowbase + mt * 16 + tk);
;                 if (D == 0) TMP[row * 512 + ch] = (bf16_t)f2bf(hc);
;                 else MIX[row * DM + ch] = (bf16_t)f2bf(grv[ti] * (hfv[ti] + hc)); }
;         }
	v_pk_fma_f32 v[0:1], v[0:1], v[248:249], v[242:243]
	v_pk_fma_f32 v[2:3], v[2:3], v[248:249], v[242:243]
	v_pk_fma_f32 v[4:5], v[4:5], v[248:249], v[242:243]
	v_pk_fma_f32 v[6:7], v[6:7], v[248:249], v[242:243]
	v_pk_fma_f32 v[8:9], v[8:9], v[248:249], v[242:243]
	v_pk_fma_f32 v[10:11], v[10:11], v[248:249], v[242:243]
	v_pk_fma_f32 v[12:13], v[12:13], v[248:249], v[242:243]
	v_pk_fma_f32 v[14:15], v[14:15], v[248:249], v[242:243]
	v_pk_fma_f32 v[16:17], v[16:17], v[248:249], v[244:245]
	v_pk_fma_f32 v[18:19], v[18:19], v[248:249], v[244:245]
	v_pk_fma_f32 v[20:21], v[20:21], v[248:249], v[244:245]
	v_pk_fma_f32 v[22:23], v[22:23], v[248:249], v[244:245]
	v_pk_fma_f32 v[24:25], v[24:25], v[248:249], v[244:245]
	v_pk_fma_f32 v[26:27], v[26:27], v[248:249], v[244:245]
	v_pk_fma_f32 v[28:29], v[28:29], v[248:249], v[244:245]
	v_pk_fma_f32 v[30:31], v[30:31], v[248:249], v[244:245]
	v_exp_f32_e32 v0, v0
	v_exp_f32_e32 v1, v1
	v_exp_f32_e32 v2, v2
	v_exp_f32_e32 v3, v3
	v_exp_f32_e32 v4, v4
	v_exp_f32_e32 v5, v5
	v_exp_f32_e32 v6, v6
	v_exp_f32_e32 v7, v7
	v_exp_f32_e32 v8, v8
	v_exp_f32_e32 v9, v9
	v_exp_f32_e32 v10, v10
	v_exp_f32_e32 v11, v11
	v_exp_f32_e32 v12, v12
	v_exp_f32_e32 v13, v13
	v_exp_f32_e32 v14, v14
	v_exp_f32_e32 v15, v15
	v_exp_f32_e32 v16, v16
	v_exp_f32_e32 v17, v17
	v_exp_f32_e32 v18, v18
	v_exp_f32_e32 v19, v19
	v_exp_f32_e32 v20, v20
	v_exp_f32_e32 v21, v21
	v_exp_f32_e32 v22, v22
	v_exp_f32_e32 v23, v23
	v_exp_f32_e32 v24, v24
	v_exp_f32_e32 v25, v25
	v_exp_f32_e32 v26, v26
	v_exp_f32_e32 v27, v27
	v_exp_f32_e32 v28, v28
	v_exp_f32_e32 v29, v29
	v_exp_f32_e32 v30, v30
	v_exp_f32_e32 v31, v31
	v_pk_add_f32 v[0:1], v[0:1], 1.0 op_sel_hi:[1,0]
	v_pk_add_f32 v[2:3], v[2:3], 1.0 op_sel_hi:[1,0]
	v_pk_add_f32 v[4:5], v[4:5], 1.0 op_sel_hi:[1,0]
	v_pk_add_f32 v[6:7], v[6:7], 1.0 op_sel_hi:[1,0]
	v_pk_add_f32 v[8:9], v[8:9], 1.0 op_sel_hi:[1,0]
	v_pk_add_f32 v[10:11], v[10:11], 1.0 op_sel_hi:[1,0]
	v_pk_add_f32 v[12:13], v[12:13], 1.0 op_sel_hi:[1,0]
	v_pk_add_f32 v[14:15], v[14:15], 1.0 op_sel_hi:[1,0]
	v_pk_add_f32 v[16:17], v[16:17], 1.0 op_sel_hi:[1,0]
	v_pk_add_f32 v[18:19], v[18:19], 1.0 op_sel_hi:[1,0]
	v_pk_add_f32 v[20:21], v[20:21], 1.0 op_sel_hi:[1,0]
	v_pk_add_f32 v[22:23], v[22:23], 1.0 op_sel_hi:[1,0]
	v_pk_add_f32 v[24:25], v[24:25], 1.0 op_sel_hi:[1,0]
	v_pk_add_f32 v[26:27], v[26:27], 1.0 op_sel_hi:[1,0]
	v_pk_add_f32 v[28:29], v[28:29], 1.0 op_sel_hi:[1,0]
	v_pk_add_f32 v[30:31], v[30:31], 1.0 op_sel_hi:[1,0]
	v_rcp_f32_e32 v0, v0
	v_rcp_f32_e32 v1, v1
	v_rcp_f32_e32 v2, v2
	v_rcp_f32_e32 v3, v3
	v_rcp_f32_e32 v4, v4
	v_rcp_f32_e32 v5, v5
	v_rcp_f32_e32 v6, v6
	v_rcp_f32_e32 v7, v7
	v_rcp_f32_e32 v8, v8
	v_rcp_f32_e32 v9, v9
	v_rcp_f32_e32 v10, v10
	v_rcp_f32_e32 v11, v11
	v_rcp_f32_e32 v12, v12
	v_rcp_f32_e32 v13, v13
	v_rcp_f32_e32 v14, v14
	v_rcp_f32_e32 v15, v15
	v_rcp_f32_e32 v16, v16
	v_rcp_f32_e32 v17, v17
	v_rcp_f32_e32 v18, v18
	v_rcp_f32_e32 v19, v19
	v_rcp_f32_e32 v20, v20
	v_rcp_f32_e32 v21, v21
	v_rcp_f32_e32 v22, v22
	v_rcp_f32_e32 v23, v23
	v_rcp_f32_e32 v24, v24
	v_rcp_f32_e32 v25, v25
	v_rcp_f32_e32 v26, v26
	v_rcp_f32_e32 v27, v27
	v_rcp_f32_e32 v28, v28
	v_rcp_f32_e32 v29, v29
	v_rcp_f32_e32 v30, v30
	v_rcp_f32_e32 v31, v31
	v_pk_mul_f32 v[0:1], v[246:247], v[0:1]
	v_pk_mul_f32 v[2:3], v[246:247], v[2:3]
	v_pk_mul_f32 v[4:5], v[246:247], v[4:5]
	v_pk_mul_f32 v[6:7], v[246:247], v[6:7]
	v_pk_mul_f32 v[8:9], v[246:247], v[8:9]
	v_pk_mul_f32 v[10:11], v[246:247], v[10:11]
	v_pk_mul_f32 v[12:13], v[246:247], v[12:13]
	v_pk_mul_f32 v[14:15], v[246:247], v[14:15]
	v_exp_f32_e32 v0, v0
	v_exp_f32_e32 v1, v1
	v_exp_f32_e32 v2, v2
	v_exp_f32_e32 v3, v3
	v_exp_f32_e32 v4, v4
	v_exp_f32_e32 v5, v5
	v_exp_f32_e32 v6, v6
	v_exp_f32_e32 v7, v7
	v_exp_f32_e32 v8, v8
	v_exp_f32_e32 v9, v9
	v_exp_f32_e32 v10, v10
	v_exp_f32_e32 v11, v11
	v_exp_f32_e32 v12, v12
	v_exp_f32_e32 v13, v13
	v_exp_f32_e32 v14, v14
	v_exp_f32_e32 v15, v15
	v_fma_f32 v32, -v0, v0, 1.0 clamp
	v_fma_f32 v33, -v1, v1, 1.0 clamp
	v_fma_f32 v34, -v2, v2, 1.0 clamp
	v_fma_f32 v35, -v3, v3, 1.0 clamp
	v_fma_f32 v36, -v4, v4, 1.0 clamp
	v_fma_f32 v37, -v5, v5, 1.0 clamp
	v_fma_f32 v38, -v6, v6, 1.0 clamp
	v_fma_f32 v39, -v7, v7, 1.0 clamp
	v_fma_f32 v40, -v8, v8, 1.0 clamp
	v_fma_f32 v41, -v9, v9, 1.0 clamp
	v_fma_f32 v42, -v10, v10, 1.0 clamp
	v_fma_f32 v43, -v11, v11, 1.0 clamp
	v_fma_f32 v44, -v12, v12, 1.0 clamp
	v_fma_f32 v45, -v13, v13, 1.0 clamp
	v_fma_f32 v46, -v14, v14, 1.0 clamp
	v_fma_f32 v47, -v15, v15, 1.0 clamp
	v_sqrt_f32_e32 v32, v32
	v_sqrt_f32_e32 v33, v33
	v_sqrt_f32_e32 v34, v34
	v_sqrt_f32_e32 v35, v35
	v_sqrt_f32_e32 v36, v36
	v_sqrt_f32_e32 v37, v37
	v_sqrt_f32_e32 v38, v38
	v_sqrt_f32_e32 v39, v39
	v_sqrt_f32_e32 v40, v40
	v_sqrt_f32_e32 v41, v41
	v_sqrt_f32_e32 v42, v42
	v_sqrt_f32_e32 v43, v43
	v_sqrt_f32_e32 v44, v44
	v_sqrt_f32_e32 v45, v45
	v_sqrt_f32_e32 v46, v46
	v_sqrt_f32_e32 v47, v47
	s_nop 0
	v_pk_mul_f32 v[16:17], v[16:17], v[32:33]
	v_pk_mul_f32 v[18:19], v[18:19], v[34:35]
	v_pk_mul_f32 v[20:21], v[20:21], v[36:37]
	v_pk_mul_f32 v[22:23], v[22:23], v[38:39]
	v_pk_mul_f32 v[24:25], v[24:25], v[40:41]
	v_pk_mul_f32 v[26:27], v[26:27], v[42:43]
	v_pk_mul_f32 v[28:29], v[28:29], v[44:45]
	v_pk_mul_f32 v[30:31], v[30:31], v[46:47]
	v_pk_mul_f32 v[16:17], v[16:17], v[48:49]
	v_pk_mul_f32 v[18:19], v[18:19], v[50:51]
	v_pk_mul_f32 v[20:21], v[20:21], v[52:53]
	v_pk_mul_f32 v[22:23], v[22:23], v[54:55]
	v_pk_mul_f32 v[24:25], v[24:25], v[56:57]
	v_pk_mul_f32 v[26:27], v[26:27], v[58:59]
	v_pk_mul_f32 v[28:29], v[28:29], v[60:61]
	v_pk_mul_f32 v[30:31], v[30:31], v[62:63]
	v_fma_f32 v32, v0, v250, v16
	v_fma_f32 v250, v1, v32, v17
	v_cvt_pk_bf16_f32 v174, v32, v250
	v_fma_f32 v32, v2, v250, v18
	v_fma_f32 v250, v3, v32, v19
	v_cvt_pk_bf16_f32 v175, v32, v250
	v_fma_f32 v32, v4, v250, v20
	v_fma_f32 v250, v5, v32, v21
	v_cvt_pk_bf16_f32 v176, v32, v250
	v_fma_f32 v32, v6, v250, v22
	v_fma_f32 v250, v7, v32, v23
	v_cvt_pk_bf16_f32 v177, v32, v250
	v_fma_f32 v32, v8, v250, v24
	v_fma_f32 v250, v9, v32, v25
	v_cvt_pk_bf16_f32 v178, v32, v250
	v_fma_f32 v32, v10, v250, v26
	v_fma_f32 v250, v11, v32, v27
	v_cvt_pk_bf16_f32 v179, v32, v250
	v_fma_f32 v32, v12, v250, v28
	v_fma_f32 v250, v13, v32, v29
	v_cvt_pk_bf16_f32 v180, v32, v250
	v_fma_f32 v32, v14, v250, v30
	v_fma_f32 v250, v15, v32, v31
	v_cvt_pk_bf16_f32 v181, v32, v250
	ds_read_b128 v[32:35], v236 offset:6912
	ds_read_b128 v[36:39], v236 offset:6976
	s_waitcnt lgkmcnt(0)
; #define LAS __attribute__((address_space(3)))
; #define WAVE_SYNC() asm volatile("s_waitcnt lgkmcnt(0)" ::: "memory")
; __device__ __forceinline__ f32x4 mfma16(bf16x8 a, bf16x8 b, f32x4 c) { return __builtin_amdgcn_mfma_f32_16x16x32_bf16(a, b, c, 0, 0, 0); }
; template <bool FINAL, int D>
; __device__ __forceinline__ void rg_dir(PREF p, int l, int h, int ch, int sidx, int rowbase  , LAS bf16_t* sXc, LAS float* stg, int lane) {
;     ...
;     for (int nt = 0; nt < 4; ++nt) { const int o0 = (nt * 16 + (lane & 15)) * 64 + (lane >> 4) * 8;
;         Br[nt][0] = *(const bf16x8*)(wr_ + o0); Br[nt][1] = *(const bf16x8*)(wr_ + o0 + 32); Bi[nt][0] = *(const bf16x8*)(wi_ + o0); Bi[nt][1] = *(const bf16x8*)(wi_ + o0 + 32); }
;     ...
;         const bf16x8 A0 = *(const LAS bf16x8*)(sXc + (mt * 16 + (lane & 15)) * 72 + (lane >> 4) * 8), A1 = *(const LAS bf16x8*)(sXc + (mt * 16 + (lane & 15)) * 72 + 32 + (lane >> 4) * 8);
;         f32x4 ar[4], ai[4];
; #pragma unroll
;         for (int nt = 0; nt < 4; ++nt) { const f32x4 z = {0.f, 0.f, 0.f, 0.f};
;             ar[nt] = mfma16(A0, Br[nt][0], z); ar[nt] = mfma16(A1, Br[nt][1], ar[nt]); ai[nt] = mfma16(A0, Bi[nt][0], z); ai[nt] = mfma16(A1, Bi[nt][1], ai[nt]); }
;         WAVE_SYNC();
; #pragma unroll
;         for (int nt = 0; nt < 4; ++nt)
; #pragma unroll
;             for (int j = 0; j < 4; ++j) { const int o = ((lane >> 4) * 4 + j) * 64 + nt * 16 + (lane & 15); stg[o] = ar[nt][j]; stg[1024 + o] = ai[nt][j]; }
;         WAVE_SYNC();
	v_mfma_f32_16x16x32_bf16 v[0:3], v[32:35], v[80:83], 0
	v_mfma_f32_16x16x32_bf16 v[4:7], v[32:35], v[88:91], 0
	v_mfma_f32_16x16x32_bf16 v[8:11], v[32:35], v[96:99], 0
	v_mfma_f32_16x16x32_bf16 v[12:15], v[32:35], v[104:107], 0
	v_mfma_f32_16x16x32_bf16 v[16:19], v[32:35], v[112:115], 0
	v_mfma_f32_16x16x32_bf16 v[20:23], v[32:35], v[120:123], 0
	v_mfma_f32_16x16x32_bf16 v[24:27], v[32:35], v[128:131], 0
	v_mfma_f32_16x16x32_bf16 v[28:31], v[32:35], v[136:139], 0
	v_mfma_f32_16x16x32_bf16 v[0:3], v[36:39], v[84:87], v[0:3]
	v_mfma_f32_16x16x32_bf16 v[4:7], v[36:39], v[92:95], v[4:7]
	v_mfma_f32_16x16x32_bf16 v[8:11], v[36:39], v[100:103], v[8:11]
	v_mfma_f32_16x16x32_bf16 v[12:15], v[36:39], v[108:111], v[12:15]
	v_mfma_f32_16x16x32_bf16 v[16:19], v[36:39], v[116:119], v[16:19]
	v_mfma_f32_16x16x32_bf16 v[20:23], v[36:39], v[124:127], v[20:23]
	v_mfma_f32_16x16x32_bf16 v[24:27], v[36:39], v[132:135], v[24:27]
	v_mfma_f32_16x16x32_bf16 v[28:31], v[36:39], v[228:231], v[28:31]
	s_nop 3
	ds_write2_b32 v237, v0, v4 offset0:0 offset1:16
	ds_write2_b32 v237, v8, v12 offset0:32 offset1:48
	ds_write2_b32 v237, v1, v5 offset0:64 offset1:80
	ds_write2_b32 v237, v9, v13 offset0:96 offset1:112
	ds_write2_b32 v237, v2, v6 offset0:128 offset1:144
	ds_write2_b32 v237, v10, v14 offset0:160 offset1:176
	ds_write2_b32 v237, v3, v7 offset0:192 offset1:208
	ds_write2_b32 v237, v11, v15 offset0:224 offset1:240
	ds_write2_b32 v238, v16, v20 offset0:0 offset1:16
	ds_write2_b32 v238, v24, v28 offset0:32 offset1:48
	ds_write2_b32 v238, v17, v21 offset0:64 offset1:80
	ds_write2_b32 v238, v25, v29 offset0:96 offset1:112
	ds_write2_b32 v238, v18, v22 offset0:128 offset1:144
	ds_write2_b32 v238, v26, v30 offset0:160 offset1:176
	ds_write2_b32 v238, v19, v23 offset0:192 offset1:208
	ds_write2_b32 v238, v27, v31 offset0:224 offset1:240
	s_waitcnt lgkmcnt(0)
	ds_read2st64_b32 v[0:1], v239 offset0:36 offset1:37
	ds_read2st64_b32 v[2:3], v239 offset0:38 offset1:39
	ds_read2st64_b32 v[4:5], v239 offset0:40 offset1:41
	ds_read2st64_b32 v[6:7], v239 offset0:42 offset1:43
	ds_read2st64_b32 v[8:9], v239 offset0:44 offset1:45
	ds_read2st64_b32 v[10:11], v239 offset0:46 offset1:47
	ds_read2st64_b32 v[12:13], v239 offset0:48 offset1:49
	ds_read2st64_b32 v[14:15], v239 offset0:50 offset1:51
	ds_read2st64_b32 v[16:17], v239 offset0:52 offset1:53
	ds_read2st64_b32 v[18:19], v239 offset0:54 offset1:55
	ds_read2st64_b32 v[20:21], v239 offset0:56 offset1:57
	ds_read2st64_b32 v[22:23], v239 offset0:58 offset1:59
	ds_read2st64_b32 v[24:25], v239 offset0:60 offset1:61
	ds_read2st64_b32 v[26:27], v239 offset0:62 offset1:63
	ds_read2st64_b32 v[28:29], v239 offset0:64 offset1:65
	ds_read2st64_b32 v[30:31], v239 offset0:66 offset1:67
	ds_read_u16_d16_hi v48, v240 offset:6912
	ds_read_u16_d16_hi v49, v240 offset:7056
	ds_read_u16_d16_hi v50, v240 offset:7200
	ds_read_u16_d16_hi v51, v240 offset:7344
	ds_read_u16_d16_hi v52, v240 offset:7488
	ds_read_u16_d16_hi v53, v240 offset:7632
	ds_read_u16_d16_hi v54, v240 offset:7776
	ds_read_u16_d16_hi v55, v240 offset:7920
	ds_read_u16_d16_hi v56, v240 offset:8064
	ds_read_u16_d16_hi v57, v240 offset:8208
	ds_read_u16_d16_hi v58, v240 offset:8352
	ds_read_u16_d16_hi v59, v240 offset:8496
	ds_read_u16_d16_hi v60, v240 offset:8640
	ds_read_u16_d16_hi v61, v240 offset:8784
	ds_read_u16_d16_hi v62, v240 offset:8928
	ds_read_u16_d16_hi v63, v240 offset:9072
	s_add_u32 s90, s92, 0x20000
	s_addc_u32 s91, s93, 0
	global_load_dwordx4 v[80:83], v241, s[90:91]
	global_load_dwordx4 v[84:87], v241, s[90:91] offset:64
	global_load_dwordx4 v[88:91], v241, s[90:91] offset:2048
	global_load_dwordx4 v[92:95], v241, s[90:91] offset:2112
	s_add_u32 s90, s92, 0x21000
	s_addc_u32 s91, s93, 0
	global_load_dwordx4 v[96:99], v241, s[90:91]
	global_load_dwordx4 v[100:103], v241, s[90:91] offset:64
	global_load_dwordx4 v[104:107], v241, s[90:91] offset:2048
	global_load_dwordx4 v[108:111], v241, s[90:91] offset:2112
	s_add_u32 s90, s92, 0x30000
	s_addc_u32 s91, s93, 0
	global_load_dwordx4 v[112:115], v241, s[90:91]
	global_load_dwordx4 v[116:119], v241, s[90:91] offset:64
	global_load_dwordx4 v[120:123], v241, s[90:91] offset:2048
	global_load_dwordx4 v[124:127], v241, s[90:91] offset:2112
	s_add_u32 s90, s92, 0x31000
	s_addc_u32 s91, s93, 0
	global_load_dwordx4 v[128:131], v241, s[90:91]
	global_load_dwordx4 v[132:135], v241, s[90:91] offset:64
	global_load_dwordx4 v[136:139], v241, s[90:91] offset:2048
	global_load_dwordx4 v[228:231], v241, s[90:91] offset:2112
	s_waitcnt lgkmcnt(0)
; __device__ __forceinline__ unsigned f2bf(float f) { unsigned r; asm("v_cvt_pk_bf16_f32 %0, %1, %1" : "=v"(r) : "v"(f)); return r & 0xffffu; }
; __device__ __forceinline__ float rcpf_(float x) { return __builtin_amdgcn_rcpf(x); }
; __device__ __forceinline__ float sigmoid_f(float x) { return rcpf_(1.f + __expf(-x)); }
; __device__ __forceinline__ float gelu_tanh_f(float x) { const float y = 0.7978845608028654f * (x + 0.044715f * x * x * x); return x * sigmoid_f(2.f * y); }
; template <bool FINAL, int D>
; __device__ __forceinline__ void rg_dir(PREF p, int l, int h, int ch, int sidx, int rowbase  , LAS bf16_t* sXc, LAS float* stg, int lane) {
;     ...
;     const float ba = p.rg_ba[(l * 2 + D) * 512 + ch], bi = p.rg_bi[(l * 2 + D) * 512 + ch], lam = p.rg_lam[(l * 2 + D) * 512 + ch];
;     const float e_ = __expf(-lam), u_ = 1.f + e_;
;     const float l1p = (u_ == 1.f) ? e_ : __logf(u_) * e_ * rcpf_(u_ - 1.f);
;     const float sp8 = -8.f * 1.4426950408889634f * l1p;
;     float hc = FINAL ? RGC[sidx] : 0.f, Ap = 1.f;
;     ...
;         for (int ti = 0; ti < 16; ++ti) { const int tk = D ? 15 - ti : ti;
;             const float zr = stg[tk * 64 + lane] + ba, zi = stg[1024 + tk * 64 + lane] + bi;
;             const float r = sigmoid_f(zr), ig = sigmoid_f(zi);
;             const float a = __builtin_amdgcn_exp2f(r * sp8);
;             const float xc = bf2f(sXc[(mt * 16 + tk) * 72 + lane]);
;             av[ti] = a; iv[ti] = __builtin_amdgcn_sqrtf(fmaxf(1.f - a * a, 0.f)) * ig * xc;
;             if (FINAL && D == 1) grv[ti] = gelu_tanh_f(grv[ti]);
;         }
; #pragma unroll
;         for (int ti = 0; ti < 16; ++ti) { const int tk = D ? 15 - ti : ti;
;             hc = av[ti] * hc + iv[ti]; Ap *= av[ti];
;             if (FINAL) { const size_t row = (size_t)(rowbase + mt * 16 + tk);
;                 if (D == 0) TMP[row * 512 + ch] = (bf16_t)f2bf(hc);
;                 else MIX[row * DM + ch] = (bf16_t)f2bf(grv[ti] * (hfv[ti] + hc)); }
;         }
;     }
;     if (!FINAL) { RGA[sidx] = Ap; RGH[sidx] = hc; }
	v_pk_fma_f32 v[0:1], v[0:1], v[248:249], v[242:243]
	v_pk_fma_f32 v[2:3], v[2:3], v[248:249], v[242:243]
	v_pk_fma_f32 v[4:5], v[4:5], v[248:249], v[242:243]
	v_pk_fma_f32 v[6:7], v[6:7], v[248:249], v[242:243]
	v_pk_fma_f32 v[8:9], v[8:9], v[248:249], v[242:243]
	v_pk_fma_f32 v[10:11], v[10:11], v[248:249], v[242:243]
	v_pk_fma_f32 v[12:13], v[12:13], v[248:249], v[242:243]
	v_pk_fma_f32 v[14:15], v[14:15], v[248:249], v[242:243]
	v_pk_fma_f32 v[16:17], v[16:17], v[248:249], v[244:245]
	v_pk_fma_f32 v[18:19], v[18:19], v[248:249], v[244:245]
	v_pk_fma_f32 v[20:21], v[20:21], v[248:249], v[244:245]
	v_pk_fma_f32 v[22:23], v[22:23], v[248:249], v[244:245]
	v_pk_fma_f32 v[24:25], v[24:25], v[248:249], v[244:245]
	v_pk_fma_f32 v[26:27], v[26:27], v[248:249], v[244:245]
	v_pk_fma_f32 v[28:29], v[28:29], v[248:249], v[244:245]
	v_pk_fma_f32 v[30:31], v[30:31], v[248:249], v[244:245]
	v_exp_f32_e32 v0, v0
	v_exp_f32_e32 v1, v1
	v_exp_f32_e32 v2, v2
	v_exp_f32_e32 v3, v3
	v_exp_f32_e32 v4, v4
	v_exp_f32_e32 v5, v5
	v_exp_f32_e32 v6, v6
	v_exp_f32_e32 v7, v7
	v_exp_f32_e32 v8, v8
	v_exp_f32_e32 v9, v9
	v_exp_f32_e32 v10, v10
	v_exp_f32_e32 v11, v11
	v_exp_f32_e32 v12, v12
	v_exp_f32_e32 v13, v13
	v_exp_f32_e32 v14, v14
	v_exp_f32_e32 v15, v15
	v_exp_f32_e32 v16, v16
	v_exp_f32_e32 v17, v17
	v_exp_f32_e32 v18, v18
	v_exp_f32_e32 v19, v19
	v_exp_f32_e32 v20, v20
	v_exp_f32_e32 v21, v21
	v_exp_f32_e32 v22, v22
	v_exp_f32_e32 v23, v23
	v_exp_f32_e32 v24, v24
	v_exp_f32_e32 v25, v25
	v_exp_f32_e32 v26, v26
	v_exp_f32_e32 v27, v27
	v_exp_f32_e32 v28, v28
	v_exp_f32_e32 v29, v29
	v_exp_f32_e32 v30, v30
	v_exp_f32_e32 v31, v31
	v_pk_add_f32 v[0:1], v[0:1], 1.0 op_sel_hi:[1,0]
	v_pk_add_f32 v[2:3], v[2:3], 1.0 op_sel_hi:[1,0]
	v_pk_add_f32 v[4:5], v[4:5], 1.0 op_sel_hi:[1,0]
	v_pk_add_f32 v[6:7], v[6:7], 1.0 op_sel_hi:[1,0]
	v_pk_add_f32 v[8:9], v[8:9], 1.0 op_sel_hi:[1,0]
	v_pk_add_f32 v[10:11], v[10:11], 1.0 op_sel_hi:[1,0]
	v_pk_add_f32 v[12:13], v[12:13], 1.0 op_sel_hi:[1,0]
	v_pk_add_f32 v[14:15], v[14:15], 1.0 op_sel_hi:[1,0]
	v_pk_add_f32 v[16:17], v[16:17], 1.0 op_sel_hi:[1,0]
	v_pk_add_f32 v[18:19], v[18:19], 1.0 op_sel_hi:[1,0]
	v_pk_add_f32 v[20:21], v[20:21], 1.0 op_sel_hi:[1,0]
	v_pk_add_f32 v[22:23], v[22:23], 1.0 op_sel_hi:[1,0]
	v_pk_add_f32 v[24:25], v[24:25], 1.0 op_sel_hi:[1,0]
	v_pk_add_f32 v[26:27], v[26:27], 1.0 op_sel_hi:[1,0]
	v_pk_add_f32 v[28:29], v[28:29], 1.0 op_sel_hi:[1,0]
	v_pk_add_f32 v[30:31], v[30:31], 1.0 op_sel_hi:[1,0]
	v_rcp_f32_e32 v0, v0
	v_rcp_f32_e32 v1, v1
	v_rcp_f32_e32 v2, v2
	v_rcp_f32_e32 v3, v3
	v_rcp_f32_e32 v4, v4
	v_rcp_f32_e32 v5, v5
	v_rcp_f32_e32 v6, v6
	v_rcp_f32_e32 v7, v7
	v_rcp_f32_e32 v8, v8
	v_rcp_f32_e32 v9, v9
	v_rcp_f32_e32 v10, v10
	v_rcp_f32_e32 v11, v11
	v_rcp_f32_e32 v12, v12
	v_rcp_f32_e32 v13, v13
	v_rcp_f32_e32 v14, v14
	v_rcp_f32_e32 v15, v15
	v_rcp_f32_e32 v16, v16
	v_rcp_f32_e32 v17, v17
	v_rcp_f32_e32 v18, v18
	v_rcp_f32_e32 v19, v19
	v_rcp_f32_e32 v20, v20
	v_rcp_f32_e32 v21, v21
	v_rcp_f32_e32 v22, v22
	v_rcp_f32_e32 v23, v23
	v_rcp_f32_e32 v24, v24
	v_rcp_f32_e32 v25, v25
	v_rcp_f32_e32 v26, v26
	v_rcp_f32_e32 v27, v27
	v_rcp_f32_e32 v28, v28
	v_rcp_f32_e32 v29, v29
	v_rcp_f32_e32 v30, v30
	v_rcp_f32_e32 v31, v31
	v_pk_mul_f32 v[0:1], v[246:247], v[0:1]
	v_pk_mul_f32 v[2:3], v[246:247], v[2:3]
	v_pk_mul_f32 v[4:5], v[246:247], v[4:5]
	v_pk_mul_f32 v[6:7], v[246:247], v[6:7]
	v_pk_mul_f32 v[8:9], v[246:247], v[8:9]
	v_pk_mul_f32 v[10:11], v[246:247], v[10:11]
	v_pk_mul_f32 v[12:13], v[246:247], v[12:13]
	v_pk_mul_f32 v[14:15], v[246:247], v[14:15]
	v_exp_f32_e32 v0, v0
	v_exp_f32_e32 v1, v1
	v_exp_f32_e32 v2, v2
	v_exp_f32_e32 v3, v3
	v_exp_f32_e32 v4, v4
	v_exp_f32_e32 v5, v5
	v_exp_f32_e32 v6, v6
	v_exp_f32_e32 v7, v7
	v_exp_f32_e32 v8, v8
	v_exp_f32_e32 v9, v9
	v_exp_f32_e32 v10, v10
	v_exp_f32_e32 v11, v11
	v_exp_f32_e32 v12, v12
	v_exp_f32_e32 v13, v13
	v_exp_f32_e32 v14, v14
	v_exp_f32_e32 v15, v15
	v_fma_f32 v32, -v0, v0, 1.0 clamp
	v_fma_f32 v33, -v1, v1, 1.0 clamp
	v_fma_f32 v34, -v2, v2, 1.0 clamp
	v_fma_f32 v35, -v3, v3, 1.0 clamp
	v_fma_f32 v36, -v4, v4, 1.0 clamp
	v_fma_f32 v37, -v5, v5, 1.0 clamp
	v_fma_f32 v38, -v6, v6, 1.0 clamp
	v_fma_f32 v39, -v7, v7, 1.0 clamp
	v_fma_f32 v40, -v8, v8, 1.0 clamp
	v_fma_f32 v41, -v9, v9, 1.0 clamp
	v_fma_f32 v42, -v10, v10, 1.0 clamp
	v_fma_f32 v43, -v11, v11, 1.0 clamp
	v_fma_f32 v44, -v12, v12, 1.0 clamp
	v_fma_f32 v45, -v13, v13, 1.0 clamp
	v_fma_f32 v46, -v14, v14, 1.0 clamp
	v_fma_f32 v47, -v15, v15, 1.0 clamp
	v_sqrt_f32_e32 v32, v32
	v_sqrt_f32_e32 v33, v33
	v_sqrt_f32_e32 v34, v34
	v_sqrt_f32_e32 v35, v35
	v_sqrt_f32_e32 v36, v36
	v_sqrt_f32_e32 v37, v37
	v_sqrt_f32_e32 v38, v38
	v_sqrt_f32_e32 v39, v39
	v_sqrt_f32_e32 v40, v40
	v_sqrt_f32_e32 v41, v41
	v_sqrt_f32_e32 v42, v42
	v_sqrt_f32_e32 v43, v43
	v_sqrt_f32_e32 v44, v44
	v_sqrt_f32_e32 v45, v45
	v_sqrt_f32_e32 v46, v46
	v_sqrt_f32_e32 v47, v47
	s_nop 0
	v_pk_mul_f32 v[16:17], v[16:17], v[32:33]
	v_pk_mul_f32 v[18:19], v[18:19], v[34:35]
	v_pk_mul_f32 v[20:21], v[20:21], v[36:37]
	v_pk_mul_f32 v[22:23], v[22:23], v[38:39]
	v_pk_mul_f32 v[24:25], v[24:25], v[40:41]
	v_pk_mul_f32 v[26:27], v[26:27], v[42:43]
	v_pk_mul_f32 v[28:29], v[28:29], v[44:45]
	v_pk_mul_f32 v[30:31], v[30:31], v[46:47]
	v_pk_mul_f32 v[16:17], v[16:17], v[48:49]
	v_pk_mul_f32 v[18:19], v[18:19], v[50:51]
	v_pk_mul_f32 v[20:21], v[20:21], v[52:53]
	v_pk_mul_f32 v[22:23], v[22:23], v[54:55]
	v_pk_mul_f32 v[24:25], v[24:25], v[56:57]
	v_pk_mul_f32 v[26:27], v[26:27], v[58:59]
	v_pk_mul_f32 v[28:29], v[28:29], v[60:61]
	v_pk_mul_f32 v[30:31], v[30:31], v[62:63]
	global_load_dword v45, v235, s[76:77] offset:2048
	global_load_dword v46, v235, s[78:79] offset:2048
	global_load_dword v47, v235, s[80:81] offset:2048
	global_load_dword v251, v235, s[96:97] offset:2048
	v_fma_f32 v32, v0, v250, v16
	v_fma_f32 v250, v1, v32, v17
	v_cvt_pk_bf16_f32 v182, v32, v250
	v_fma_f32 v32, v2, v250, v18
	v_fma_f32 v250, v3, v32, v19
	v_cvt_pk_bf16_f32 v183, v32, v250
	v_fma_f32 v32, v4, v250, v20
	v_fma_f32 v250, v5, v32, v21
	v_cvt_pk_bf16_f32 v184, v32, v250
	v_fma_f32 v32, v6, v250, v22
	v_fma_f32 v250, v7, v32, v23
	v_cvt_pk_bf16_f32 v185, v32, v250
	v_fma_f32 v32, v8, v250, v24
	v_fma_f32 v250, v9, v32, v25
	v_cvt_pk_bf16_f32 v186, v32, v250
	v_fma_f32 v32, v10, v250, v26
	v_fma_f32 v250, v11, v32, v27
	v_cvt_pk_bf16_f32 v187, v32, v250
	v_fma_f32 v32, v12, v250, v28
	v_fma_f32 v250, v13, v32, v29
	v_cvt_pk_bf16_f32 v188, v32, v250
	v_fma_f32 v32, v14, v250, v30
	v_fma_f32 v250, v15, v32, v31
	v_cvt_pk_bf16_f32 v189, v32, v250
	s_waitcnt vmcnt(0)
; #define LAS __attribute__((address_space(3)))
; #define WAVE_SYNC() asm volatile("s_waitcnt lgkmcnt(0)" ::: "memory")
; __device__ __forceinline__ float rcpf_(float x) { return __builtin_amdgcn_rcpf(x); }
; __device__ __forceinline__ float sigmoid_f(float x) { return rcpf_(1.f + __expf(-x)); }
; __device__ __forceinline__ float gelu_tanh_f(float x) { const float y = 0.7978845608028654f * (x + 0.044715f * x * x * x); return x * sigmoid_f(2.f * y); }
; __device__ __forceinline__ f32x4 mfma16(bf16x8 a, bf16x8 b, f32x4 c) { return __builtin_amdgcn_mfma_f32_16x16x32_bf16(a, b, c, 0, 0, 0); }
; template <bool FINAL, int D>
; __device__ __forceinline__ void rg_dir(PREF p, int l, int h, int ch, int sidx, int rowbase  , LAS bf16_t* sXc, LAS float* stg, int lane) {
;     ...
;     const float e_ = __expf(-lam), u_ = 1.f + e_;
;     const float l1p = (u_ == 1.f) ? e_ : __logf(u_) * e_ * rcpf_(u_ - 1.f);
;     const float sp8 = -8.f * 1.4426950408889634f * l1p;
;     float hc = FINAL ? RGC[sidx] : 0.f, Ap = 1.f;
;     ...
;         const bf16x8 A0 = *(const LAS bf16x8*)(sXc + (mt * 16 + (lane & 15)) * 72 + (lane >> 4) * 8), A1 = *(const LAS bf16x8*)(sXc + (mt * 16 + (lane & 15)) * 72 + 32 + (lane >> 4) * 8);
;         f32x4 ar[4], ai[4];
; #pragma unroll
;         for (int nt = 0; nt < 4; ++nt) { const f32x4 z = {0.f, 0.f, 0.f, 0.f};
;             ar[nt] = mfma16(A0, Br[nt][0], z); ar[nt] = mfma16(A1, Br[nt][1], ar[nt]); ai[nt] = mfma16(A0, Bi[nt][0], z); ai[nt] = mfma16(A1, Bi[nt][1], ai[nt]); }
;         WAVE_SYNC();
; #pragma unroll
;         for (int nt = 0; nt < 4; ++nt)
; #pragma unroll
;             for (int j = 0; j < 4; ++j) { const int o = ((lane >> 4) * 4 + j) * 64 + nt * 16 + (lane & 15); stg[o] = ar[nt][j]; stg[1024 + o] = ai[nt][j]; }
;         WAVE_SYNC();
;         float av[16], iv[16];
; #pragma unroll
;         for (int ti = 0; ti < 16; ++ti) { const int tk = D ? 15 - ti : ti;
;             const float zr = stg[tk * 64 + lane] + ba, zi = stg[1024 + tk * 64 + lane] + bi;
;             const float r = sigmoid_f(zr), ig = sigmoid_f(zi);
;             const float a = __builtin_amdgcn_exp2f(r * sp8);
;             const float xc = bf2f(sXc[(mt * 16 + tk) * 72 + lane]);
;             av[ti] = a; iv[ti] = __builtin_amdgcn_sqrtf(fmaxf(1.f - a * a, 0.f)) * ig * xc;
;             if (FINAL && D == 1) grv[ti] = gelu_tanh_f(grv[ti]);
	s_mov_b32 s8, 0x800000
	s_mov_b32 s9, 0x3f317217
	s_mov_b32 s14, 0x7f800000
	v_mul_f32_e32 v32, 0xbfb8aa3b, v45
	v_exp_f32_e32 v32, v32
	s_nop 0
	v_add_f32_e32 v33, 1.0, v32
	v_cmp_gt_f32_e32 vcc, s8, v33
	s_nop 1
	v_cndmask_b32_e64 v34, 0, 32, vcc
	v_ldexp_f32 v34, v33, v34
	v_log_f32_e32 v34, v34
	v_cndmask_b32_e32 v36, 0, v226, vcc
	v_cmp_eq_f32_e32 vcc, 1.0, v33
	v_mul_f32_e32 v35, 0x3f317217, v34
	v_fma_f32 v35, v34, s9, -v35
	v_fmac_f32_e32 v35, 0x3377d1cf, v34
	v_fmac_f32_e32 v35, 0x3f317217, v34
	v_cmp_lt_f32_e64 s[10:11], |v34|, s14
	s_nop 1
	v_cndmask_b32_e64 v34, v34, v35, s[10:11]
	v_add_f32_e32 v35, -1.0, v33
	v_rcp_f32_e32 v35, v35
	v_sub_f32_e32 v34, v34, v36
	v_mul_f32_e32 v34, v32, v34
	v_mul_f32_e32 v34, v34, v35
	v_cndmask_b32_e32 v32, v34, v32, vcc
	v_mul_f32_e32 v246, 0xc138aa3b, v32
	v_mov_b32_e32 v247, v246
	v_mul_f32_e32 v242, 0xbfb8aa3b, v46
	v_mul_f32_e32 v244, 0xbfb8aa3b, v47
	v_mov_b32_e32 v243, v242
	v_mov_b32_e32 v245, v244
	v_mov_b32_e32 v250, v251
	ds_read_b128 v[32:35], v236 offset:6912
	ds_read_b128 v[36:39], v236 offset:6976
	s_waitcnt lgkmcnt(0)
	v_mfma_f32_16x16x32_bf16 v[0:3], v[32:35], v[80:83], 0
	v_mfma_f32_16x16x32_bf16 v[4:7], v[32:35], v[88:91], 0
	v_mfma_f32_16x16x32_bf16 v[8:11], v[32:35], v[96:99], 0
	v_mfma_f32_16x16x32_bf16 v[12:15], v[32:35], v[104:107], 0
	v_mfma_f32_16x16x32_bf16 v[16:19], v[32:35], v[112:115], 0
	v_mfma_f32_16x16x32_bf16 v[20:23], v[32:35], v[120:123], 0
	v_mfma_f32_16x16x32_bf16 v[24:27], v[32:35], v[128:131], 0
	v_mfma_f32_16x16x32_bf16 v[28:31], v[32:35], v[136:139], 0
	v_mfma_f32_16x16x32_bf16 v[0:3], v[36:39], v[84:87], v[0:3]
	v_mfma_f32_16x16x32_bf16 v[4:7], v[36:39], v[92:95], v[4:7]
	v_mfma_f32_16x16x32_bf16 v[8:11], v[36:39], v[100:103], v[8:11]
	v_mfma_f32_16x16x32_bf16 v[12:15], v[36:39], v[108:111], v[12:15]
	v_mfma_f32_16x16x32_bf16 v[16:19], v[36:39], v[116:119], v[16:19]
	v_mfma_f32_16x16x32_bf16 v[20:23], v[36:39], v[124:127], v[20:23]
	v_mfma_f32_16x16x32_bf16 v[24:27], v[36:39], v[132:135], v[24:27]
	v_mfma_f32_16x16x32_bf16 v[28:31], v[36:39], v[228:231], v[28:31]
	s_nop 3
	ds_write2_b32 v237, v0, v4 offset0:0 offset1:16
	ds_write2_b32 v237, v8, v12 offset0:32 offset1:48
	ds_write2_b32 v237, v1, v5 offset0:64 offset1:80
	ds_write2_b32 v237, v9, v13 offset0:96 offset1:112
	ds_write2_b32 v237, v2, v6 offset0:128 offset1:144
	ds_write2_b32 v237, v10, v14 offset0:160 offset1:176
	ds_write2_b32 v237, v3, v7 offset0:192 offset1:208
	ds_write2_b32 v237, v11, v15 offset0:224 offset1:240
	ds_write2_b32 v238, v16, v20 offset0:0 offset1:16
	ds_write2_b32 v238, v24, v28 offset0:32 offset1:48
	ds_write2_b32 v238, v17, v21 offset0:64 offset1:80
	ds_write2_b32 v238, v25, v29 offset0:96 offset1:112
	ds_write2_b32 v238, v18, v22 offset0:128 offset1:144
	ds_write2_b32 v238, v26, v30 offset0:160 offset1:176
	ds_write2_b32 v238, v19, v23 offset0:192 offset1:208
	ds_write2_b32 v238, v27, v31 offset0:224 offset1:240
	s_waitcnt lgkmcnt(0)
	ds_read2st64_b32 v[0:1], v239 offset0:36 offset1:37
	ds_read2st64_b32 v[2:3], v239 offset0:38 offset1:39
	ds_read2st64_b32 v[4:5], v239 offset0:40 offset1:41
	ds_read2st64_b32 v[6:7], v239 offset0:42 offset1:43
	ds_read2st64_b32 v[8:9], v239 offset0:44 offset1:45
	ds_read2st64_b32 v[10:11], v239 offset0:46 offset1:47
	ds_read2st64_b32 v[12:13], v239 offset0:48 offset1:49
	ds_read2st64_b32 v[14:15], v239 offset0:50 offset1:51
	ds_read2st64_b32 v[16:17], v239 offset0:52 offset1:53
	ds_read2st64_b32 v[18:19], v239 offset0:54 offset1:55
	ds_read2st64_b32 v[20:21], v239 offset0:56 offset1:57
	ds_read2st64_b32 v[22:23], v239 offset0:58 offset1:59
	ds_read2st64_b32 v[24:25], v239 offset0:60 offset1:61
	ds_read2st64_b32 v[26:27], v239 offset0:62 offset1:63
	ds_read2st64_b32 v[28:29], v239 offset0:64 offset1:65
	ds_read2st64_b32 v[30:31], v239 offset0:66 offset1:67
	ds_read_u16_d16_hi v48, v240 offset:6912
	ds_read_u16_d16_hi v49, v240 offset:7056
	ds_read_u16_d16_hi v50, v240 offset:7200
	ds_read_u16_d16_hi v51, v240 offset:7344
	ds_read_u16_d16_hi v52, v240 offset:7488
	ds_read_u16_d16_hi v53, v240 offset:7632
	ds_read_u16_d16_hi v54, v240 offset:7776
	ds_read_u16_d16_hi v55, v240 offset:7920
	ds_read_u16_d16_hi v56, v240 offset:8064
	ds_read_u16_d16_hi v57, v240 offset:8208
	ds_read_u16_d16_hi v58, v240 offset:8352
	ds_read_u16_d16_hi v59, v240 offset:8496
	ds_read_u16_d16_hi v60, v240 offset:8640
	ds_read_u16_d16_hi v61, v240 offset:8784
	ds_read_u16_d16_hi v62, v240 offset:8928
	ds_read_u16_d16_hi v63, v240 offset:9072
	v_lshlrev_b32_e32 v206, 16, v190
	v_lshlrev_b32_e32 v207, 16, v191
	v_lshlrev_b32_e32 v208, 16, v192
	v_lshlrev_b32_e32 v209, 16, v193
	v_lshlrev_b32_e32 v210, 16, v194
	v_lshlrev_b32_e32 v211, 16, v195
	v_lshlrev_b32_e32 v212, 16, v196
	v_lshlrev_b32_e32 v213, 16, v197
	v_lshlrev_b32_e32 v214, 16, v198
	v_lshlrev_b32_e32 v215, 16, v199
	v_lshlrev_b32_e32 v216, 16, v200
	v_lshlrev_b32_e32 v217, 16, v201
	v_lshlrev_b32_e32 v218, 16, v202
	v_lshlrev_b32_e32 v219, 16, v203
	v_lshlrev_b32_e32 v222, 16, v204
	v_lshlrev_b32_e32 v223, 16, v205
	v_pk_mul_f32 v[32:33], v[140:141], v[206:207]
	v_pk_mul_f32 v[34:35], v[140:141], v[208:209]
	v_pk_mul_f32 v[36:37], v[140:141], v[210:211]
	v_pk_mul_f32 v[38:39], v[140:141], v[212:213]
	v_pk_mul_f32 v[40:41], v[140:141], v[214:215]
	v_pk_mul_f32 v[42:43], v[140:141], v[216:217]
	v_pk_mul_f32 v[44:45], v[140:141], v[218:219]
	v_pk_mul_f32 v[46:47], v[140:141], v[222:223]
	v_pk_mul_f32 v[32:33], v[32:33], v[206:207]
	v_pk_mul_f32 v[34:35], v[34:35], v[208:209]
	v_pk_mul_f32 v[36:37], v[36:37], v[210:211]
	v_pk_mul_f32 v[38:39], v[38:39], v[212:213]
	v_pk_mul_f32 v[40:41], v[40:41], v[214:215]
; __device__ __forceinline__ float gelu_tanh_f(float x) { const float y = 0.7978845608028654f * (x + 0.044715f * x * x * x); return x * sigmoid_f(2.f * y); }
; template <bool FINAL, int D>
; __device__ __forceinline__ void rg_dir(PREF p, int l, int h, int ch, int sidx, int rowbase  , LAS bf16_t* sXc, LAS float* stg, int lane) {
;     ...
;             for (int ti = 0; ti < 16; ++ti) { const size_t row = (size_t)(rowbase + mt * 16 + 15 - ti); grv[ti] = __builtin_bit_cast(float, (unsigned)P[row * PW + 512 + ch]); hfv[ti] = __builtin_bit_cast(float, (unsigned)TMP[row * 512 + ch]); }
;     ...
;             if (FINAL && D == 1) grv[ti] = gelu_tanh_f(grv[ti]);
	v_pk_mul_f32 v[42:43], v[42:43], v[216:217]
	v_pk_mul_f32 v[44:45], v[44:45], v[218:219]
	v_pk_mul_f32 v[46:47], v[46:47], v[222:223]
	v_fma_f32 v32, v32, v206, v206
	v_fma_f32 v33, v33, v207, v207
	v_fma_f32 v34, v34, v208, v208
	v_fma_f32 v35, v35, v209, v209
	v_fma_f32 v36, v36, v210, v210
	v_fma_f32 v37, v37, v211, v211
	v_fma_f32 v38, v38, v212, v212
	v_fma_f32 v39, v39, v213, v213
	v_fma_f32 v40, v40, v214, v214
	v_fma_f32 v41, v41, v215, v215
	v_fma_f32 v42, v42, v216, v216
	v_fma_f32 v43, v43, v217, v217
	v_fma_f32 v44, v44, v218, v218
	v_fma_f32 v45, v45, v219, v219
	v_fma_f32 v46, v46, v222, v222
	v_fma_f32 v47, v47, v223, v223
	s_mov_b32 s98, 0xc0135761
	v_pk_mul_f32 v[32:33], v[32:33], s[98:99] op_sel_hi:[1,0]
	v_pk_mul_f32 v[34:35], v[34:35], s[98:99] op_sel_hi:[1,0]
	v_pk_mul_f32 v[36:37], v[36:37], s[98:99] op_sel_hi:[1,0]
	v_pk_mul_f32 v[38:39], v[38:39], s[98:99] op_sel_hi:[1,0]
	v_pk_mul_f32 v[40:41], v[40:41], s[98:99] op_sel_hi:[1,0]
	v_pk_mul_f32 v[42:43], v[42:43], s[98:99] op_sel_hi:[1,0]
	v_pk_mul_f32 v[44:45], v[44:45], s[98:99] op_sel_hi:[1,0]
	v_pk_mul_f32 v[46:47], v[46:47], s[98:99] op_sel_hi:[1,0]
	v_exp_f32_e32 v32, v32
	v_exp_f32_e32 v33, v33
	v_exp_f32_e32 v34, v34
	v_exp_f32_e32 v35, v35
	v_exp_f32_e32 v36, v36
	v_exp_f32_e32 v37, v37
	v_exp_f32_e32 v38, v38
	v_exp_f32_e32 v39, v39
	v_exp_f32_e32 v40, v40
	v_exp_f32_e32 v41, v41
	v_exp_f32_e32 v42, v42
	v_exp_f32_e32 v43, v43
	v_exp_f32_e32 v44, v44
	v_exp_f32_e32 v45, v45
	v_exp_f32_e32 v46, v46
	v_exp_f32_e32 v47, v47
	v_pk_add_f32 v[32:33], v[32:33], 1.0 op_sel_hi:[1,0]
	v_pk_add_f32 v[34:35], v[34:35], 1.0 op_sel_hi:[1,0]
	v_pk_add_f32 v[36:37], v[36:37], 1.0 op_sel_hi:[1,0]
	v_pk_add_f32 v[38:39], v[38:39], 1.0 op_sel_hi:[1,0]
	v_pk_add_f32 v[40:41], v[40:41], 1.0 op_sel_hi:[1,0]
	v_pk_add_f32 v[42:43], v[42:43], 1.0 op_sel_hi:[1,0]
	v_pk_add_f32 v[44:45], v[44:45], 1.0 op_sel_hi:[1,0]
	v_pk_add_f32 v[46:47], v[46:47], 1.0 op_sel_hi:[1,0]
	v_rcp_f32_e32 v32, v32
	v_rcp_f32_e32 v33, v33
	v_rcp_f32_e32 v34, v34
	v_rcp_f32_e32 v35, v35
	v_rcp_f32_e32 v36, v36
	v_rcp_f32_e32 v37, v37
	v_rcp_f32_e32 v38, v38
	v_rcp_f32_e32 v39, v39
	v_rcp_f32_e32 v40, v40
	v_rcp_f32_e32 v41, v41
	v_rcp_f32_e32 v42, v42
	v_rcp_f32_e32 v43, v43
	v_rcp_f32_e32 v44, v44
	v_rcp_f32_e32 v45, v45
	v_rcp_f32_e32 v46, v46
	v_rcp_f32_e32 v47, v47
	s_nop 0
	v_pk_mul_f32 v[206:207], v[32:33], v[206:207]
	v_pk_mul_f32 v[208:209], v[34:35], v[208:209]
	v_pk_mul_f32 v[210:211], v[36:37], v[210:211]
	v_pk_mul_f32 v[212:213], v[38:39], v[212:213]
	v_pk_mul_f32 v[214:215], v[40:41], v[214:215]
	v_pk_mul_f32 v[216:217], v[42:43], v[216:217]
	v_pk_mul_f32 v[218:219], v[44:45], v[218:219]
	v_pk_mul_f32 v[222:223], v[46:47], v[222:223]
	s_add_i32 s39, s15, 32
	s_mul_hi_u32 s83, s39, 0x1600
	s_mul_i32 s82, s39, 0x1600
	s_add_u32 s82, s82, s0
	s_addc_u32 s83, s83, s1
	s_add_u32 s82, s82, 0xbc00400
	s_addc_u32 s83, s83, 0
	global_load_ushort v190, v234, s[82:83]
	s_add_u32 s82, s82, 0x1600
	s_addc_u32 s83, s83, 0
	global_load_ushort v191, v234, s[82:83]
	s_add_u32 s82, s82, 0x1600
	s_addc_u32 s83, s83, 0
	global_load_ushort v192, v234, s[82:83]
	s_add_u32 s82, s82, 0x1600
	s_addc_u32 s83, s83, 0
	global_load_ushort v193, v234, s[82:83]
	s_add_u32 s82, s82, 0x1600
	s_addc_u32 s83, s83, 0
	global_load_ushort v194, v234, s[82:83]
	s_add_u32 s82, s82, 0x1600
	s_addc_u32 s83, s83, 0
	global_load_ushort v195, v234, s[82:83]
	s_add_u32 s82, s82, 0x1600
	s_addc_u32 s83, s83, 0
	global_load_ushort v196, v234, s[82:83]
	s_add_u32 s82, s82, 0x1600
	s_addc_u32 s83, s83, 0
	global_load_ushort v197, v234, s[82:83]
	s_add_u32 s82, s82, 0x1600
	s_addc_u32 s83, s83, 0
	global_load_ushort v198, v234, s[82:83]
	s_add_u32 s82, s82, 0x1600
	s_addc_u32 s83, s83, 0
	global_load_ushort v199, v234, s[82:83]
	s_add_u32 s82, s82, 0x1600
	s_addc_u32 s83, s83, 0
	global_load_ushort v200, v234, s[82:83]
	s_add_u32 s82, s82, 0x1600
	s_addc_u32 s83, s83, 0
	global_load_ushort v201, v234, s[82:83]
	s_add_u32 s82, s82, 0x1600
	s_addc_u32 s83, s83, 0
	global_load_ushort v202, v234, s[82:83]
	s_add_u32 s82, s82, 0x1600
	s_addc_u32 s83, s83, 0
	global_load_ushort v203, v234, s[82:83]
	s_add_u32 s82, s82, 0x1600
	s_addc_u32 s83, s83, 0
	global_load_ushort v204, v234, s[82:83]
	s_add_u32 s82, s82, 0x1600
	s_addc_u32 s83, s83, 0
	global_load_ushort v205, v234, s[82:83]
	s_waitcnt lgkmcnt(0)
; __device__ __forceinline__ float sigmoid_f(float x) { return rcpf_(1.f + __expf(-x)); }
; template <bool FINAL, int D>
; __device__ __forceinline__ void rg_dir(PREF p, int l, int h, int ch, int sidx, int rowbase  , LAS bf16_t* sXc, LAS float* stg, int lane) {
;     ...
;         for (int ti = 0; ti < 16; ++ti) { const int tk = D ? 15 - ti : ti;
;             const float zr = stg[tk * 64 + lane] + ba, zi = stg[1024 + tk * 64 + lane] + bi;
;             const float r = sigmoid_f(zr), ig = sigmoid_f(zi);
;             const float a = __builtin_amdgcn_exp2f(r * sp8);
;             const float xc = bf2f(sXc[(mt * 16 + tk) * 72 + lane]);
;             av[ti] = a; iv[ti] = __builtin_amdgcn_sqrtf(fmaxf(1.f - a * a, 0.f)) * ig * xc;
	v_pk_fma_f32 v[0:1], v[0:1], v[248:249], v[242:243]
	v_pk_fma_f32 v[2:3], v[2:3], v[248:249], v[242:243]
	v_pk_fma_f32 v[4:5], v[4:5], v[248:249], v[242:243]
	v_pk_fma_f32 v[6:7], v[6:7], v[248:249], v[242:243]
	v_pk_fma_f32 v[8:9], v[8:9], v[248:249], v[242:243]
	v_pk_fma_f32 v[10:11], v[10:11], v[248:249], v[242:243]
	v_pk_fma_f32 v[12:13], v[12:13], v[248:249], v[242:243]
	v_pk_fma_f32 v[14:15], v[14:15], v[248:249], v[242:243]
	v_pk_fma_f32 v[16:17], v[16:17], v[248:249], v[244:245]
	v_pk_fma_f32 v[18:19], v[18:19], v[248:249], v[244:245]
	v_pk_fma_f32 v[20:21], v[20:21], v[248:249], v[244:245]
	v_pk_fma_f32 v[22:23], v[22:23], v[248:249], v[244:245]
	v_pk_fma_f32 v[24:25], v[24:25], v[248:249], v[244:245]
	v_pk_fma_f32 v[26:27], v[26:27], v[248:249], v[244:245]
	v_pk_fma_f32 v[28:29], v[28:29], v[248:249], v[244:245]
	v_pk_fma_f32 v[30:31], v[30:31], v[248:249], v[244:245]
	v_exp_f32_e32 v0, v0
	v_exp_f32_e32 v1, v1
	v_exp_f32_e32 v2, v2
	v_exp_f32_e32 v3, v3
	v_exp_f32_e32 v4, v4
	v_exp_f32_e32 v5, v5
	v_exp_f32_e32 v6, v6
	v_exp_f32_e32 v7, v7
	v_exp_f32_e32 v8, v8
	v_exp_f32_e32 v9, v9
	v_exp_f32_e32 v10, v10
	v_exp_f32_e32 v11, v11
	v_exp_f32_e32 v12, v12
	v_exp_f32_e32 v13, v13
	v_exp_f32_e32 v14, v14
	v_exp_f32_e32 v15, v15
	v_exp_f32_e32 v16, v16
	v_exp_f32_e32 v17, v17
	v_exp_f32_e32 v18, v18
	v_exp_f32_e32 v19, v19
	v_exp_f32_e32 v20, v20
	v_exp_f32_e32 v21, v21
	v_exp_f32_e32 v22, v22
	v_exp_f32_e32 v23, v23
	v_exp_f32_e32 v24, v24
	v_exp_f32_e32 v25, v25
	v_exp_f32_e32 v26, v26
	v_exp_f32_e32 v27, v27
	v_exp_f32_e32 v28, v28
	v_exp_f32_e32 v29, v29
	v_exp_f32_e32 v30, v30
	v_exp_f32_e32 v31, v31
	v_pk_add_f32 v[0:1], v[0:1], 1.0 op_sel_hi:[1,0]
	v_pk_add_f32 v[2:3], v[2:3], 1.0 op_sel_hi:[1,0]
	v_pk_add_f32 v[4:5], v[4:5], 1.0 op_sel_hi:[1,0]
	v_pk_add_f32 v[6:7], v[6:7], 1.0 op_sel_hi:[1,0]
	v_pk_add_f32 v[8:9], v[8:9], 1.0 op_sel_hi:[1,0]
	v_pk_add_f32 v[10:11], v[10:11], 1.0 op_sel_hi:[1,0]
	v_pk_add_f32 v[12:13], v[12:13], 1.0 op_sel_hi:[1,0]
	v_pk_add_f32 v[14:15], v[14:15], 1.0 op_sel_hi:[1,0]
	v_pk_add_f32 v[16:17], v[16:17], 1.0 op_sel_hi:[1,0]
	v_pk_add_f32 v[18:19], v[18:19], 1.0 op_sel_hi:[1,0]
	v_pk_add_f32 v[20:21], v[20:21], 1.0 op_sel_hi:[1,0]
	v_pk_add_f32 v[22:23], v[22:23], 1.0 op_sel_hi:[1,0]
	v_pk_add_f32 v[24:25], v[24:25], 1.0 op_sel_hi:[1,0]
	v_pk_add_f32 v[26:27], v[26:27], 1.0 op_sel_hi:[1,0]
	v_pk_add_f32 v[28:29], v[28:29], 1.0 op_sel_hi:[1,0]
	v_pk_add_f32 v[30:31], v[30:31], 1.0 op_sel_hi:[1,0]
	v_rcp_f32_e32 v0, v0
	v_rcp_f32_e32 v1, v1
	v_rcp_f32_e32 v2, v2
	v_rcp_f32_e32 v3, v3
	v_rcp_f32_e32 v4, v4
	v_rcp_f32_e32 v5, v5
	v_rcp_f32_e32 v6, v6
	v_rcp_f32_e32 v7, v7
	v_rcp_f32_e32 v8, v8
	v_rcp_f32_e32 v9, v9
	v_rcp_f32_e32 v10, v10
	v_rcp_f32_e32 v11, v11
	v_rcp_f32_e32 v12, v12
	v_rcp_f32_e32 v13, v13
	v_rcp_f32_e32 v14, v14
	v_rcp_f32_e32 v15, v15
	v_rcp_f32_e32 v16, v16
	v_rcp_f32_e32 v17, v17
	v_rcp_f32_e32 v18, v18
	v_rcp_f32_e32 v19, v19
	v_rcp_f32_e32 v20, v20
	v_rcp_f32_e32 v21, v21
	v_rcp_f32_e32 v22, v22
	v_rcp_f32_e32 v23, v23
	v_rcp_f32_e32 v24, v24
	v_rcp_f32_e32 v25, v25
	v_rcp_f32_e32 v26, v26
	v_rcp_f32_e32 v27, v27
	v_rcp_f32_e32 v28, v28
	v_rcp_f32_e32 v29, v29
	v_rcp_f32_e32 v30, v30
	v_rcp_f32_e32 v31, v31
	v_pk_mul_f32 v[0:1], v[246:247], v[0:1]
	v_pk_mul_f32 v[2:3], v[246:247], v[2:3]
	v_pk_mul_f32 v[4:5], v[246:247], v[4:5]
	v_pk_mul_f32 v[6:7], v[246:247], v[6:7]
	v_pk_mul_f32 v[8:9], v[246:247], v[8:9]
	v_pk_mul_f32 v[10:11], v[246:247], v[10:11]
	v_pk_mul_f32 v[12:13], v[246:247], v[12:13]
	v_pk_mul_f32 v[14:15], v[246:247], v[14:15]
	v_exp_f32_e32 v0, v0
	v_exp_f32_e32 v1, v1
	v_exp_f32_e32 v2, v2
	v_exp_f32_e32 v3, v3
	v_exp_f32_e32 v4, v4
	v_exp_f32_e32 v5, v5
	v_exp_f32_e32 v6, v6
	v_exp_f32_e32 v7, v7
	v_exp_f32_e32 v8, v8
	v_exp_f32_e32 v9, v9
	v_exp_f32_e32 v10, v10
	v_exp_f32_e32 v11, v11
	v_exp_f32_e32 v12, v12
	v_exp_f32_e32 v13, v13
	v_exp_f32_e32 v14, v14
	v_exp_f32_e32 v15, v15
	v_fma_f32 v32, -v0, v0, 1.0 clamp
	v_fma_f32 v33, -v1, v1, 1.0 clamp
	v_fma_f32 v34, -v2, v2, 1.0 clamp
	v_fma_f32 v35, -v3, v3, 1.0 clamp
	v_fma_f32 v36, -v4, v4, 1.0 clamp
	v_fma_f32 v37, -v5, v5, 1.0 clamp
	v_fma_f32 v38, -v6, v6, 1.0 clamp
	v_fma_f32 v39, -v7, v7, 1.0 clamp
	v_fma_f32 v40, -v8, v8, 1.0 clamp
	v_fma_f32 v41, -v9, v9, 1.0 clamp
	v_fma_f32 v42, -v10, v10, 1.0 clamp
	v_fma_f32 v43, -v11, v11, 1.0 clamp
	v_fma_f32 v44, -v12, v12, 1.0 clamp
	v_fma_f32 v45, -v13, v13, 1.0 clamp
	v_fma_f32 v46, -v14, v14, 1.0 clamp
	v_fma_f32 v47, -v15, v15, 1.0 clamp
	v_sqrt_f32_e32 v32, v32
	v_sqrt_f32_e32 v33, v33
	v_sqrt_f32_e32 v34, v34
	v_sqrt_f32_e32 v35, v35
	v_sqrt_f32_e32 v36, v36
	v_sqrt_f32_e32 v37, v37
	v_sqrt_f32_e32 v38, v38
	v_sqrt_f32_e32 v39, v39
	v_sqrt_f32_e32 v40, v40
	v_sqrt_f32_e32 v41, v41
	v_sqrt_f32_e32 v42, v42
	v_sqrt_f32_e32 v43, v43
	v_sqrt_f32_e32 v44, v44
	v_sqrt_f32_e32 v45, v45
	v_sqrt_f32_e32 v46, v46
	v_sqrt_f32_e32 v47, v47
	s_nop 0
	v_pk_mul_f32 v[16:17], v[16:17], v[32:33]
	v_pk_mul_f32 v[18:19], v[18:19], v[34:35]
	v_pk_mul_f32 v[20:21], v[20:21], v[36:37]
	v_pk_mul_f32 v[22:23], v[22:23], v[38:39]
	v_pk_mul_f32 v[24:25], v[24:25], v[40:41]
	v_pk_mul_f32 v[26:27], v[26:27], v[42:43]
	v_pk_mul_f32 v[28:29], v[28:29], v[44:45]
	v_pk_mul_f32 v[30:31], v[30:31], v[46:47]
	v_pk_mul_f32 v[16:17], v[16:17], v[48:49]
	v_pk_mul_f32 v[18:19], v[18:19], v[50:51]
	v_pk_mul_f32 v[20:21], v[20:21], v[52:53]
	v_pk_mul_f32 v[22:23], v[22:23], v[54:55]
	v_pk_mul_f32 v[24:25], v[24:25], v[56:57]
	v_pk_mul_f32 v[26:27], v[26:27], v[58:59]
	v_pk_mul_f32 v[28:29], v[28:29], v[60:61]
	v_pk_mul_f32 v[30:31], v[30:31], v[62:63]
	s_add_i32 s39, s15, 62
; #define LAS __attribute__((address_space(3)))
; #define WAVE_SYNC() asm volatile("s_waitcnt lgkmcnt(0)" ::: "memory")
; __device__ __forceinline__ unsigned f2bf(float f) { unsigned r; asm("v_cvt_pk_bf16_f32 %0, %1, %1" : "=v"(r) : "v"(f)); return r & 0xffffu; }
; __device__ __forceinline__ f32x4 mfma16(bf16x8 a, bf16x8 b, f32x4 c) { return __builtin_amdgcn_mfma_f32_16x16x32_bf16(a, b, c, 0, 0, 0); }
; template <bool FINAL, int D>
; __device__ __forceinline__ void rg_dir(PREF p, int l, int h, int ch, int sidx, int rowbase  , LAS bf16_t* sXc, LAS float* stg, int lane) {
;     ...
;         const bf16x8 A0 = *(const LAS bf16x8*)(sXc + (mt * 16 + (lane & 15)) * 72 + (lane >> 4) * 8), A1 = *(const LAS bf16x8*)(sXc + (mt * 16 + (lane & 15)) * 72 + 32 + (lane >> 4) * 8);
;         f32x4 ar[4], ai[4];
; #pragma unroll
;         for (int nt = 0; nt < 4; ++nt) { const f32x4 z = {0.f, 0.f, 0.f, 0.f};
;             ar[nt] = mfma16(A0, Br[nt][0], z); ar[nt] = mfma16(A1, Br[nt][1], ar[nt]); ai[nt] = mfma16(A0, Bi[nt][0], z); ai[nt] = mfma16(A1, Bi[nt][1], ai[nt]); }
;         WAVE_SYNC();
; #pragma unroll
;         for (int nt = 0; nt < 4; ++nt)
; #pragma unroll
;             for (int j = 0; j < 4; ++j) { const int o = ((lane >> 4) * 4 + j) * 64 + nt * 16 + (lane & 15); stg[o] = ar[nt][j]; stg[1024 + o] = ai[nt][j]; }
;     ...
;         for (int ti = 0; ti < 16; ++ti) { const int tk = D ? 15 - ti : ti;
;             hc = av[ti] * hc + iv[ti]; Ap *= av[ti];
;             if (FINAL) { const size_t row = (size_t)(rowbase + mt * 16 + tk);
;                 if (D == 0) TMP[row * 512 + ch] = (bf16_t)f2bf(hc);
;                 else MIX[row * DM + ch] = (bf16_t)f2bf(grv[ti] * (hfv[ti] + hc)); }
	s_lshl_b32 s39, s39, 11
	s_add_u32 s90, s0, 0x7b00000
	s_addc_u32 s91, s1, 0
	s_add_u32 s90, s90, s39
	s_addc_u32 s91, s91, 0
	v_lshlrev_b32_e32 v48, 16, v182
	v_and_b32_e32 v49, 0xffff0000, v182
	v_lshlrev_b32_e32 v50, 16, v183
	v_and_b32_e32 v51, 0xffff0000, v183
	v_lshlrev_b32_e32 v52, 16, v184
	v_and_b32_e32 v53, 0xffff0000, v184
	v_lshlrev_b32_e32 v54, 16, v185
	v_and_b32_e32 v55, 0xffff0000, v185
	v_lshlrev_b32_e32 v56, 16, v186
	v_and_b32_e32 v57, 0xffff0000, v186
	v_lshlrev_b32_e32 v58, 16, v187
	v_and_b32_e32 v59, 0xffff0000, v187
	v_lshlrev_b32_e32 v60, 16, v188
	v_and_b32_e32 v61, 0xffff0000, v188
	v_lshlrev_b32_e32 v62, 16, v189
	v_and_b32_e32 v63, 0xffff0000, v189
	v_fma_f32 v47, v15, v250, v31
	v_fma_f32 v46, v14, v47, v30
	v_fma_f32 v45, v13, v46, v29
	v_fma_f32 v44, v12, v45, v28
	v_fma_f32 v43, v11, v44, v27
	v_fma_f32 v42, v10, v43, v26
	v_fma_f32 v41, v9, v42, v25
	v_fma_f32 v40, v8, v41, v24
	v_fma_f32 v39, v7, v40, v23
	v_fma_f32 v38, v6, v39, v22
	v_fma_f32 v37, v5, v38, v21
	v_fma_f32 v36, v4, v37, v20
	v_fma_f32 v35, v3, v36, v19
	v_fma_f32 v34, v2, v35, v18
	v_fma_f32 v33, v1, v34, v17
	v_fma_f32 v32, v0, v33, v16
	v_mov_b32_e32 v250, v32
	v_pk_add_f32 v[48:49], v[48:49], v[32:33]
	v_pk_add_f32 v[50:51], v[50:51], v[34:35]
	v_pk_add_f32 v[52:53], v[52:53], v[36:37]
	v_pk_add_f32 v[54:55], v[54:55], v[38:39]
	v_pk_add_f32 v[56:57], v[56:57], v[40:41]
	v_pk_add_f32 v[58:59], v[58:59], v[42:43]
	v_pk_add_f32 v[60:61], v[60:61], v[44:45]
	v_pk_add_f32 v[62:63], v[62:63], v[46:47]
	v_pk_mul_f32 v[48:49], v[206:207], v[48:49]
	v_pk_mul_f32 v[50:51], v[208:209], v[50:51]
	v_pk_mul_f32 v[52:53], v[210:211], v[52:53]
	v_pk_mul_f32 v[54:55], v[212:213], v[54:55]
	v_pk_mul_f32 v[56:57], v[214:215], v[56:57]
	v_pk_mul_f32 v[58:59], v[216:217], v[58:59]
	v_pk_mul_f32 v[60:61], v[218:219], v[60:61]
	v_pk_mul_f32 v[62:63], v[222:223], v[62:63]
	v_cvt_pk_bf16_f32 v48, v48, v49
	v_cvt_pk_bf16_f32 v50, v50, v51
	v_cvt_pk_bf16_f32 v52, v52, v53
	v_cvt_pk_bf16_f32 v54, v54, v55
	v_cvt_pk_bf16_f32 v56, v56, v57
	v_cvt_pk_bf16_f32 v58, v58, v59
	v_cvt_pk_bf16_f32 v60, v60, v61
	v_cvt_pk_bf16_f32 v62, v62, v63
	global_store_short_d16_hi v234, v62, s[90:91] offset:2048
	global_store_short v234, v62, s[90:91]
	s_sub_u32 s90, s90, 0x1000
	s_subb_u32 s91, s91, 0
	global_store_short_d16_hi v234, v60, s[90:91] offset:2048
	global_store_short v234, v60, s[90:91]
	s_sub_u32 s90, s90, 0x1000
	s_subb_u32 s91, s91, 0
	global_store_short_d16_hi v234, v58, s[90:91] offset:2048
	global_store_short v234, v58, s[90:91]
	s_sub_u32 s90, s90, 0x1000
	s_subb_u32 s91, s91, 0
	global_store_short_d16_hi v234, v56, s[90:91] offset:2048
	global_store_short v234, v56, s[90:91]
	s_sub_u32 s90, s90, 0x1000
	s_subb_u32 s91, s91, 0
	global_store_short_d16_hi v234, v54, s[90:91] offset:2048
	global_store_short v234, v54, s[90:91]
	s_sub_u32 s90, s90, 0x1000
	s_subb_u32 s91, s91, 0
	global_store_short_d16_hi v234, v52, s[90:91] offset:2048
	global_store_short v234, v52, s[90:91]
	s_sub_u32 s90, s90, 0x1000
	s_subb_u32 s91, s91, 0
	global_store_short_d16_hi v234, v50, s[90:91] offset:2048
	global_store_short v234, v50, s[90:91]
	s_sub_u32 s90, s90, 0x1000
	s_subb_u32 s91, s91, 0
	global_store_short_d16_hi v234, v48, s[90:91] offset:2048
	global_store_short v234, v48, s[90:91]
	ds_read_b128 v[32:35], v236 offset:4608
	ds_read_b128 v[36:39], v236 offset:4672
	s_waitcnt lgkmcnt(0)
	v_mfma_f32_16x16x32_bf16 v[0:3], v[32:35], v[80:83], 0
	v_mfma_f32_16x16x32_bf16 v[4:7], v[32:35], v[88:91], 0
	v_mfma_f32_16x16x32_bf16 v[8:11], v[32:35], v[96:99], 0
	v_mfma_f32_16x16x32_bf16 v[12:15], v[32:35], v[104:107], 0
	v_mfma_f32_16x16x32_bf16 v[16:19], v[32:35], v[112:115], 0
	v_mfma_f32_16x16x32_bf16 v[20:23], v[32:35], v[120:123], 0
	v_mfma_f32_16x16x32_bf16 v[24:27], v[32:35], v[128:131], 0
	v_mfma_f32_16x16x32_bf16 v[28:31], v[32:35], v[136:139], 0
	v_mfma_f32_16x16x32_bf16 v[0:3], v[36:39], v[84:87], v[0:3]
	v_mfma_f32_16x16x32_bf16 v[4:7], v[36:39], v[92:95], v[4:7]
	v_mfma_f32_16x16x32_bf16 v[8:11], v[36:39], v[100:103], v[8:11]
	v_mfma_f32_16x16x32_bf16 v[12:15], v[36:39], v[108:111], v[12:15]
	v_mfma_f32_16x16x32_bf16 v[16:19], v[36:39], v[116:119], v[16:19]
	v_mfma_f32_16x16x32_bf16 v[20:23], v[36:39], v[124:127], v[20:23]
	v_mfma_f32_16x16x32_bf16 v[24:27], v[36:39], v[132:135], v[24:27]
	v_mfma_f32_16x16x32_bf16 v[28:31], v[36:39], v[228:231], v[28:31]
	s_nop 3
	ds_write2_b32 v237, v0, v4 offset0:0 offset1:16
	ds_write2_b32 v237, v8, v12 offset0:32 offset1:48
	ds_write2_b32 v237, v1, v5 offset0:64 offset1:80
	ds_write2_b32 v237, v9, v13 offset0:96 offset1:112
	ds_write2_b32 v237, v2, v6 offset0:128 offset1:144
	ds_write2_b32 v237, v10, v14 offset0:160 offset1:176
	ds_write2_b32 v237, v3, v7 offset0:192 offset1:208
	ds_write2_b32 v237, v11, v15 offset0:224 offset1:240
	ds_write2_b32 v238, v16, v20 offset0:0 offset1:16
	ds_write2_b32 v238, v24, v28 offset0:32 offset1:48
	ds_write2_b32 v238, v17, v21 offset0:64 offset1:80
	ds_write2_b32 v238, v25, v29 offset0:96 offset1:112
	ds_write2_b32 v238, v18, v22 offset0:128 offset1:144
	ds_write2_b32 v238, v26, v30 offset0:160 offset1:176
	ds_write2_b32 v238, v19, v23 offset0:192 offset1:208
	ds_write2_b32 v238, v27, v31 offset0:224 offset1:240
	s_waitcnt lgkmcnt(0)
; #define WAVE_SYNC() asm volatile("s_waitcnt lgkmcnt(0)" ::: "memory")
; __device__ __forceinline__ float sigmoid_f(float x) { return rcpf_(1.f + __expf(-x)); }
; __device__ __forceinline__ float gelu_tanh_f(float x) { const float y = 0.7978845608028654f * (x + 0.044715f * x * x * x); return x * sigmoid_f(2.f * y); }
; template <bool FINAL, int D>
; __device__ __forceinline__ void rg_dir(PREF p, int l, int h, int ch, int sidx, int rowbase  , LAS bf16_t* sXc, LAS float* stg, int lane) {
;     ...
;             for (int ti = 0; ti < 16; ++ti) { const size_t row = (size_t)(rowbase + mt * 16 + 15 - ti); grv[ti] = __builtin_bit_cast(float, (unsigned)P[row * PW + 512 + ch]); hfv[ti] = __builtin_bit_cast(float, (unsigned)TMP[row * 512 + ch]); }
;     ...
;             for (int j = 0; j < 4; ++j) { const int o = ((lane >> 4) * 4 + j) * 64 + nt * 16 + (lane & 15); stg[o] = ar[nt][j]; stg[1024 + o] = ai[nt][j]; }
;         WAVE_SYNC();
;         float av[16], iv[16];
; #pragma unroll
;         for (int ti = 0; ti < 16; ++ti) { const int tk = D ? 15 - ti : ti;
;             const float zr = stg[tk * 64 + lane] + ba, zi = stg[1024 + tk * 64 + lane] + bi;
;             const float r = sigmoid_f(zr), ig = sigmoid_f(zi);
;             const float a = __builtin_amdgcn_exp2f(r * sp8);
;             const float xc = bf2f(sXc[(mt * 16 + tk) * 72 + lane]);
;             av[ti] = a; iv[ti] = __builtin_amdgcn_sqrtf(fmaxf(1.f - a * a, 0.f)) * ig * xc;
;             if (FINAL && D == 1) grv[ti] = gelu_tanh_f(grv[ti]);
	ds_read2st64_b32 v[0:1], v239 offset0:36 offset1:37
	ds_read2st64_b32 v[2:3], v239 offset0:38 offset1:39
	ds_read2st64_b32 v[4:5], v239 offset0:40 offset1:41
	ds_read2st64_b32 v[6:7], v239 offset0:42 offset1:43
	ds_read2st64_b32 v[8:9], v239 offset0:44 offset1:45
	ds_read2st64_b32 v[10:11], v239 offset0:46 offset1:47
	ds_read2st64_b32 v[12:13], v239 offset0:48 offset1:49
	ds_read2st64_b32 v[14:15], v239 offset0:50 offset1:51
	ds_read2st64_b32 v[16:17], v239 offset0:52 offset1:53
	ds_read2st64_b32 v[18:19], v239 offset0:54 offset1:55
	ds_read2st64_b32 v[20:21], v239 offset0:56 offset1:57
	ds_read2st64_b32 v[22:23], v239 offset0:58 offset1:59
	ds_read2st64_b32 v[24:25], v239 offset0:60 offset1:61
	ds_read2st64_b32 v[26:27], v239 offset0:62 offset1:63
	ds_read2st64_b32 v[28:29], v239 offset0:64 offset1:65
	ds_read2st64_b32 v[30:31], v239 offset0:66 offset1:67
	ds_read_u16 v48, v240 offset:4608
	ds_read_u16 v49, v240 offset:4752
	ds_read_u16 v50, v240 offset:4896
	ds_read_u16 v51, v240 offset:5040
	ds_read_u16 v52, v240 offset:5184
	ds_read_u16 v53, v240 offset:5328
	ds_read_u16 v54, v240 offset:5472
	ds_read_u16 v55, v240 offset:5616
	ds_read_u16 v56, v240 offset:5760
	ds_read_u16 v57, v240 offset:5904
	ds_read_u16 v58, v240 offset:6048
	ds_read_u16 v59, v240 offset:6192
	ds_read_u16 v60, v240 offset:6336
	ds_read_u16 v61, v240 offset:6480
	ds_read_u16 v62, v240 offset:6624
	ds_read_u16 v63, v240 offset:6768
	s_waitcnt vmcnt(16)
	v_lshlrev_b32_e32 v206, 16, v190
	v_lshlrev_b32_e32 v207, 16, v191
	v_lshlrev_b32_e32 v208, 16, v192
	v_lshlrev_b32_e32 v209, 16, v193
	v_lshlrev_b32_e32 v210, 16, v194
	v_lshlrev_b32_e32 v211, 16, v195
	v_lshlrev_b32_e32 v212, 16, v196
	v_lshlrev_b32_e32 v213, 16, v197
	v_lshlrev_b32_e32 v214, 16, v198
	v_lshlrev_b32_e32 v215, 16, v199
	v_lshlrev_b32_e32 v216, 16, v200
	v_lshlrev_b32_e32 v217, 16, v201
	v_lshlrev_b32_e32 v218, 16, v202
	v_lshlrev_b32_e32 v219, 16, v203
	v_lshlrev_b32_e32 v222, 16, v204
	v_lshlrev_b32_e32 v223, 16, v205
	v_pk_mul_f32 v[32:33], v[140:141], v[206:207]
	v_pk_mul_f32 v[34:35], v[140:141], v[208:209]
	v_pk_mul_f32 v[36:37], v[140:141], v[210:211]
	v_pk_mul_f32 v[38:39], v[140:141], v[212:213]
	v_pk_mul_f32 v[40:41], v[140:141], v[214:215]
	v_pk_mul_f32 v[42:43], v[140:141], v[216:217]
	v_pk_mul_f32 v[44:45], v[140:141], v[218:219]
	v_pk_mul_f32 v[46:47], v[140:141], v[222:223]
	v_pk_mul_f32 v[32:33], v[32:33], v[206:207]
	v_pk_mul_f32 v[34:35], v[34:35], v[208:209]
	v_pk_mul_f32 v[36:37], v[36:37], v[210:211]
	v_pk_mul_f32 v[38:39], v[38:39], v[212:213]
	v_pk_mul_f32 v[40:41], v[40:41], v[214:215]
	v_pk_mul_f32 v[42:43], v[42:43], v[216:217]
	v_pk_mul_f32 v[44:45], v[44:45], v[218:219]
	v_pk_mul_f32 v[46:47], v[46:47], v[222:223]
	v_fma_f32 v32, v32, v206, v206
	v_fma_f32 v33, v33, v207, v207
	v_fma_f32 v34, v34, v208, v208
	v_fma_f32 v35, v35, v209, v209
	v_fma_f32 v36, v36, v210, v210
	v_fma_f32 v37, v37, v211, v211
	v_fma_f32 v38, v38, v212, v212
	v_fma_f32 v39, v39, v213, v213
	v_fma_f32 v40, v40, v214, v214
	v_fma_f32 v41, v41, v215, v215
	v_fma_f32 v42, v42, v216, v216
	v_fma_f32 v43, v43, v217, v217
	v_fma_f32 v44, v44, v218, v218
	v_fma_f32 v45, v45, v219, v219
	v_fma_f32 v46, v46, v222, v222
	v_fma_f32 v47, v47, v223, v223
	s_mov_b32 s98, 0xc0135761
	v_pk_mul_f32 v[32:33], v[32:33], s[98:99] op_sel_hi:[1,0]
	v_pk_mul_f32 v[34:35], v[34:35], s[98:99] op_sel_hi:[1,0]
	v_pk_mul_f32 v[36:37], v[36:37], s[98:99] op_sel_hi:[1,0]
	v_pk_mul_f32 v[38:39], v[38:39], s[98:99] op_sel_hi:[1,0]
	v_pk_mul_f32 v[40:41], v[40:41], s[98:99] op_sel_hi:[1,0]
	v_pk_mul_f32 v[42:43], v[42:43], s[98:99] op_sel_hi:[1,0]
	v_pk_mul_f32 v[44:45], v[44:45], s[98:99] op_sel_hi:[1,0]
	v_pk_mul_f32 v[46:47], v[46:47], s[98:99] op_sel_hi:[1,0]
	v_exp_f32_e32 v32, v32
	v_exp_f32_e32 v33, v33
	v_exp_f32_e32 v34, v34
	v_exp_f32_e32 v35, v35
	v_exp_f32_e32 v36, v36
	v_exp_f32_e32 v37, v37
	v_exp_f32_e32 v38, v38
	v_exp_f32_e32 v39, v39
	v_exp_f32_e32 v40, v40
	v_exp_f32_e32 v41, v41
	v_exp_f32_e32 v42, v42
	v_exp_f32_e32 v43, v43
	v_exp_f32_e32 v44, v44
	v_exp_f32_e32 v45, v45
	v_exp_f32_e32 v46, v46
	v_exp_f32_e32 v47, v47
	v_pk_add_f32 v[32:33], v[32:33], 1.0 op_sel_hi:[1,0]
	v_pk_add_f32 v[34:35], v[34:35], 1.0 op_sel_hi:[1,0]
	v_pk_add_f32 v[36:37], v[36:37], 1.0 op_sel_hi:[1,0]
	v_pk_add_f32 v[38:39], v[38:39], 1.0 op_sel_hi:[1,0]
	v_pk_add_f32 v[40:41], v[40:41], 1.0 op_sel_hi:[1,0]
	v_pk_add_f32 v[42:43], v[42:43], 1.0 op_sel_hi:[1,0]
	v_pk_add_f32 v[44:45], v[44:45], 1.0 op_sel_hi:[1,0]
	v_pk_add_f32 v[46:47], v[46:47], 1.0 op_sel_hi:[1,0]
	v_rcp_f32_e32 v32, v32
	v_rcp_f32_e32 v33, v33
	v_rcp_f32_e32 v34, v34
	v_rcp_f32_e32 v35, v35
	v_rcp_f32_e32 v36, v36
	v_rcp_f32_e32 v37, v37
	v_rcp_f32_e32 v38, v38
	v_rcp_f32_e32 v39, v39
	v_rcp_f32_e32 v40, v40
	v_rcp_f32_e32 v41, v41
	v_rcp_f32_e32 v42, v42
	v_rcp_f32_e32 v43, v43
	v_rcp_f32_e32 v44, v44
	v_rcp_f32_e32 v45, v45
	v_rcp_f32_e32 v46, v46
	v_rcp_f32_e32 v47, v47
	s_nop 0
	v_pk_mul_f32 v[206:207], v[32:33], v[206:207]
	v_pk_mul_f32 v[208:209], v[34:35], v[208:209]
	v_pk_mul_f32 v[210:211], v[36:37], v[210:211]
	v_pk_mul_f32 v[212:213], v[38:39], v[212:213]
	v_pk_mul_f32 v[214:215], v[40:41], v[214:215]
	v_pk_mul_f32 v[216:217], v[42:43], v[216:217]
	v_pk_mul_f32 v[218:219], v[44:45], v[218:219]
	v_pk_mul_f32 v[222:223], v[46:47], v[222:223]
	s_add_i32 s39, s15, 16
	s_mul_hi_u32 s83, s39, 0x1600
	s_mul_i32 s82, s39, 0x1600
	s_add_u32 s82, s82, s0
	s_addc_u32 s83, s83, s1
	s_add_u32 s82, s82, 0xbc00400
	s_addc_u32 s83, s83, 0
	global_load_ushort v190, v234, s[82:83]
	s_add_u32 s82, s82, 0x1600
	s_addc_u32 s83, s83, 0
	global_load_ushort v191, v234, s[82:83]
	s_add_u32 s82, s82, 0x1600
	s_addc_u32 s83, s83, 0
	global_load_ushort v192, v234, s[82:83]
	s_add_u32 s82, s82, 0x1600
	s_addc_u32 s83, s83, 0
	global_load_ushort v193, v234, s[82:83]
	s_add_u32 s82, s82, 0x1600
	s_addc_u32 s83, s83, 0
	global_load_ushort v194, v234, s[82:83]
	s_add_u32 s82, s82, 0x1600
	s_addc_u32 s83, s83, 0
	global_load_ushort v195, v234, s[82:83]
	s_add_u32 s82, s82, 0x1600
	s_addc_u32 s83, s83, 0
	global_load_ushort v196, v234, s[82:83]
	s_add_u32 s82, s82, 0x1600
	s_addc_u32 s83, s83, 0
	global_load_ushort v197, v234, s[82:83]
	s_add_u32 s82, s82, 0x1600
	s_addc_u32 s83, s83, 0
	global_load_ushort v198, v234, s[82:83]
	s_add_u32 s82, s82, 0x1600
	s_addc_u32 s83, s83, 0
	global_load_ushort v199, v234, s[82:83]
	s_add_u32 s82, s82, 0x1600
	s_addc_u32 s83, s83, 0
	global_load_ushort v200, v234, s[82:83]
	s_add_u32 s82, s82, 0x1600
	s_addc_u32 s83, s83, 0
	global_load_ushort v201, v234, s[82:83]
	s_add_u32 s82, s82, 0x1600
	s_addc_u32 s83, s83, 0
	global_load_ushort v202, v234, s[82:83]
	s_add_u32 s82, s82, 0x1600
	s_addc_u32 s83, s83, 0
	global_load_ushort v203, v234, s[82:83]
	s_add_u32 s82, s82, 0x1600
	s_addc_u32 s83, s83, 0
	global_load_ushort v204, v234, s[82:83]
	s_add_u32 s82, s82, 0x1600
	s_addc_u32 s83, s83, 0
	global_load_ushort v205, v234, s[82:83]
	s_waitcnt lgkmcnt(0)
; __device__ __forceinline__ float sigmoid_f(float x) { return rcpf_(1.f + __expf(-x)); }
; template <bool FINAL, int D>
; __device__ __forceinline__ void rg_dir(PREF p, int l, int h, int ch, int sidx, int rowbase  , LAS bf16_t* sXc, LAS float* stg, int lane) {
;     ...
;         for (int ti = 0; ti < 16; ++ti) { const int tk = D ? 15 - ti : ti;
;             const float zr = stg[tk * 64 + lane] + ba, zi = stg[1024 + tk * 64 + lane] + bi;
;             const float r = sigmoid_f(zr), ig = sigmoid_f(zi);
;             const float a = __builtin_amdgcn_exp2f(r * sp8);
;             const float xc = bf2f(sXc[(mt * 16 + tk) * 72 + lane]);
;             av[ti] = a; iv[ti] = __builtin_amdgcn_sqrtf(fmaxf(1.f - a * a, 0.f)) * ig * xc;
	v_pk_fma_f32 v[0:1], v[0:1], v[248:249], v[242:243]
	v_pk_fma_f32 v[2:3], v[2:3], v[248:249], v[242:243]
	v_pk_fma_f32 v[4:5], v[4:5], v[248:249], v[242:243]
	v_pk_fma_f32 v[6:7], v[6:7], v[248:249], v[242:243]
	v_pk_fma_f32 v[8:9], v[8:9], v[248:249], v[242:243]
	v_pk_fma_f32 v[10:11], v[10:11], v[248:249], v[242:243]
	v_pk_fma_f32 v[12:13], v[12:13], v[248:249], v[242:243]
	v_pk_fma_f32 v[14:15], v[14:15], v[248:249], v[242:243]
	v_pk_fma_f32 v[16:17], v[16:17], v[248:249], v[244:245]
	v_pk_fma_f32 v[18:19], v[18:19], v[248:249], v[244:245]
	v_pk_fma_f32 v[20:21], v[20:21], v[248:249], v[244:245]
	v_pk_fma_f32 v[22:23], v[22:23], v[248:249], v[244:245]
	v_pk_fma_f32 v[24:25], v[24:25], v[248:249], v[244:245]
	v_pk_fma_f32 v[26:27], v[26:27], v[248:249], v[244:245]
	v_pk_fma_f32 v[28:29], v[28:29], v[248:249], v[244:245]
	v_pk_fma_f32 v[30:31], v[30:31], v[248:249], v[244:245]
	v_exp_f32_e32 v0, v0
	v_exp_f32_e32 v1, v1
	v_exp_f32_e32 v2, v2
	v_exp_f32_e32 v3, v3
	v_exp_f32_e32 v4, v4
	v_exp_f32_e32 v5, v5
	v_exp_f32_e32 v6, v6
	v_exp_f32_e32 v7, v7
	v_exp_f32_e32 v8, v8
	v_exp_f32_e32 v9, v9
	v_exp_f32_e32 v10, v10
	v_exp_f32_e32 v11, v11
	v_exp_f32_e32 v12, v12
	v_exp_f32_e32 v13, v13
	v_exp_f32_e32 v14, v14
	v_exp_f32_e32 v15, v15
	v_exp_f32_e32 v16, v16
	v_exp_f32_e32 v17, v17
	v_exp_f32_e32 v18, v18
	v_exp_f32_e32 v19, v19
	v_exp_f32_e32 v20, v20
	v_exp_f32_e32 v21, v21
	v_exp_f32_e32 v22, v22
	v_exp_f32_e32 v23, v23
	v_exp_f32_e32 v24, v24
	v_exp_f32_e32 v25, v25
	v_exp_f32_e32 v26, v26
	v_exp_f32_e32 v27, v27
	v_exp_f32_e32 v28, v28
	v_exp_f32_e32 v29, v29
	v_exp_f32_e32 v30, v30
	v_exp_f32_e32 v31, v31
	v_pk_add_f32 v[0:1], v[0:1], 1.0 op_sel_hi:[1,0]
	v_pk_add_f32 v[2:3], v[2:3], 1.0 op_sel_hi:[1,0]
	v_pk_add_f32 v[4:5], v[4:5], 1.0 op_sel_hi:[1,0]
	v_pk_add_f32 v[6:7], v[6:7], 1.0 op_sel_hi:[1,0]
	v_pk_add_f32 v[8:9], v[8:9], 1.0 op_sel_hi:[1,0]
	v_pk_add_f32 v[10:11], v[10:11], 1.0 op_sel_hi:[1,0]
	v_pk_add_f32 v[12:13], v[12:13], 1.0 op_sel_hi:[1,0]
	v_pk_add_f32 v[14:15], v[14:15], 1.0 op_sel_hi:[1,0]
	v_pk_add_f32 v[16:17], v[16:17], 1.0 op_sel_hi:[1,0]
	v_pk_add_f32 v[18:19], v[18:19], 1.0 op_sel_hi:[1,0]
	v_pk_add_f32 v[20:21], v[20:21], 1.0 op_sel_hi:[1,0]
	v_pk_add_f32 v[22:23], v[22:23], 1.0 op_sel_hi:[1,0]
	v_pk_add_f32 v[24:25], v[24:25], 1.0 op_sel_hi:[1,0]
	v_pk_add_f32 v[26:27], v[26:27], 1.0 op_sel_hi:[1,0]
	v_pk_add_f32 v[28:29], v[28:29], 1.0 op_sel_hi:[1,0]
	v_pk_add_f32 v[30:31], v[30:31], 1.0 op_sel_hi:[1,0]
	v_rcp_f32_e32 v0, v0
	v_rcp_f32_e32 v1, v1
	v_rcp_f32_e32 v2, v2
	v_rcp_f32_e32 v3, v3
	v_rcp_f32_e32 v4, v4
	v_rcp_f32_e32 v5, v5
	v_rcp_f32_e32 v6, v6
	v_rcp_f32_e32 v7, v7
	v_rcp_f32_e32 v8, v8
	v_rcp_f32_e32 v9, v9
	v_rcp_f32_e32 v10, v10
	v_rcp_f32_e32 v11, v11
	v_rcp_f32_e32 v12, v12
	v_rcp_f32_e32 v13, v13
	v_rcp_f32_e32 v14, v14
	v_rcp_f32_e32 v15, v15
	v_rcp_f32_e32 v16, v16
	v_rcp_f32_e32 v17, v17
	v_rcp_f32_e32 v18, v18
	v_rcp_f32_e32 v19, v19
	v_rcp_f32_e32 v20, v20
	v_rcp_f32_e32 v21, v21
	v_rcp_f32_e32 v22, v22
	v_rcp_f32_e32 v23, v23
	v_rcp_f32_e32 v24, v24
	v_rcp_f32_e32 v25, v25
	v_rcp_f32_e32 v26, v26
	v_rcp_f32_e32 v27, v27
	v_rcp_f32_e32 v28, v28
	v_rcp_f32_e32 v29, v29
	v_rcp_f32_e32 v30, v30
	v_rcp_f32_e32 v31, v31
	v_pk_mul_f32 v[0:1], v[246:247], v[0:1]
	v_pk_mul_f32 v[2:3], v[246:247], v[2:3]
	v_pk_mul_f32 v[4:5], v[246:247], v[4:5]
	v_pk_mul_f32 v[6:7], v[246:247], v[6:7]
	v_pk_mul_f32 v[8:9], v[246:247], v[8:9]
	v_pk_mul_f32 v[10:11], v[246:247], v[10:11]
	v_pk_mul_f32 v[12:13], v[246:247], v[12:13]
	v_pk_mul_f32 v[14:15], v[246:247], v[14:15]
	v_lshlrev_b32_e32 v48, 16, v48
	v_lshlrev_b32_e32 v49, 16, v49
	v_lshlrev_b32_e32 v50, 16, v50
	v_lshlrev_b32_e32 v51, 16, v51
	v_lshlrev_b32_e32 v52, 16, v52
	v_lshlrev_b32_e32 v53, 16, v53
	v_lshlrev_b32_e32 v54, 16, v54
	v_lshlrev_b32_e32 v55, 16, v55
	v_lshlrev_b32_e32 v56, 16, v56
	v_lshlrev_b32_e32 v57, 16, v57
	v_lshlrev_b32_e32 v58, 16, v58
	v_lshlrev_b32_e32 v59, 16, v59
	v_lshlrev_b32_e32 v60, 16, v60
	v_lshlrev_b32_e32 v61, 16, v61
	v_lshlrev_b32_e32 v62, 16, v62
	v_lshlrev_b32_e32 v63, 16, v63
	v_exp_f32_e32 v0, v0
	v_exp_f32_e32 v1, v1
	v_exp_f32_e32 v2, v2
	v_exp_f32_e32 v3, v3
	v_exp_f32_e32 v4, v4
	v_exp_f32_e32 v5, v5
	v_exp_f32_e32 v6, v6
	v_exp_f32_e32 v7, v7
	v_exp_f32_e32 v8, v8
	v_exp_f32_e32 v9, v9
	v_exp_f32_e32 v10, v10
	v_exp_f32_e32 v11, v11
	v_exp_f32_e32 v12, v12
	v_exp_f32_e32 v13, v13
	v_exp_f32_e32 v14, v14
	v_exp_f32_e32 v15, v15
	v_fma_f32 v32, -v0, v0, 1.0 clamp
	v_fma_f32 v33, -v1, v1, 1.0 clamp
	v_fma_f32 v34, -v2, v2, 1.0 clamp
	v_fma_f32 v35, -v3, v3, 1.0 clamp
	v_fma_f32 v36, -v4, v4, 1.0 clamp
	v_fma_f32 v37, -v5, v5, 1.0 clamp
	v_fma_f32 v38, -v6, v6, 1.0 clamp
	v_fma_f32 v39, -v7, v7, 1.0 clamp
	v_fma_f32 v40, -v8, v8, 1.0 clamp
	v_fma_f32 v41, -v9, v9, 1.0 clamp
	v_fma_f32 v42, -v10, v10, 1.0 clamp
	v_fma_f32 v43, -v11, v11, 1.0 clamp
	v_fma_f32 v44, -v12, v12, 1.0 clamp
	v_fma_f32 v45, -v13, v13, 1.0 clamp
	v_fma_f32 v46, -v14, v14, 1.0 clamp
	v_fma_f32 v47, -v15, v15, 1.0 clamp
	v_sqrt_f32_e32 v32, v32
	v_sqrt_f32_e32 v33, v33
	v_sqrt_f32_e32 v34, v34
	v_sqrt_f32_e32 v35, v35
	v_sqrt_f32_e32 v36, v36
	v_sqrt_f32_e32 v37, v37
	v_sqrt_f32_e32 v38, v38
	v_sqrt_f32_e32 v39, v39
	v_sqrt_f32_e32 v40, v40
	v_sqrt_f32_e32 v41, v41
	v_sqrt_f32_e32 v42, v42
	v_sqrt_f32_e32 v43, v43
	v_sqrt_f32_e32 v44, v44
	v_sqrt_f32_e32 v45, v45
	v_sqrt_f32_e32 v46, v46
	v_sqrt_f32_e32 v47, v47
	s_nop 0
	v_pk_mul_f32 v[16:17], v[16:17], v[32:33]
	v_pk_mul_f32 v[18:19], v[18:19], v[34:35]
	v_pk_mul_f32 v[20:21], v[20:21], v[36:37]
	v_pk_mul_f32 v[22:23], v[22:23], v[38:39]
	v_pk_mul_f32 v[24:25], v[24:25], v[40:41]
; #define LAS __attribute__((address_space(3)))
; #define WAVE_SYNC() asm volatile("s_waitcnt lgkmcnt(0)" ::: "memory")
; __device__ __forceinline__ unsigned f2bf(float f) { unsigned r; asm("v_cvt_pk_bf16_f32 %0, %1, %1" : "=v"(r) : "v"(f)); return r & 0xffffu; }
; __device__ __forceinline__ f32x4 mfma16(bf16x8 a, bf16x8 b, f32x4 c) { return __builtin_amdgcn_mfma_f32_16x16x32_bf16(a, b, c, 0, 0, 0); }
; template <bool FINAL, int D>
; __device__ __forceinline__ void rg_dir(PREF p, int l, int h, int ch, int sidx, int rowbase  , LAS bf16_t* sXc, LAS float* stg, int lane) {
;     ...
;         const bf16x8 A0 = *(const LAS bf16x8*)(sXc + (mt * 16 + (lane & 15)) * 72 + (lane >> 4) * 8), A1 = *(const LAS bf16x8*)(sXc + (mt * 16 + (lane & 15)) * 72 + 32 + (lane >> 4) * 8);
;         f32x4 ar[4], ai[4];
; #pragma unroll
;         for (int nt = 0; nt < 4; ++nt) { const f32x4 z = {0.f, 0.f, 0.f, 0.f};
;             ar[nt] = mfma16(A0, Br[nt][0], z); ar[nt] = mfma16(A1, Br[nt][1], ar[nt]); ai[nt] = mfma16(A0, Bi[nt][0], z); ai[nt] = mfma16(A1, Bi[nt][1], ai[nt]); }
;         WAVE_SYNC();
; #pragma unroll
;         for (int nt = 0; nt < 4; ++nt)
; #pragma unroll
;             for (int j = 0; j < 4; ++j) { const int o = ((lane >> 4) * 4 + j) * 64 + nt * 16 + (lane & 15); stg[o] = ar[nt][j]; stg[1024 + o] = ai[nt][j]; }
;     ...
;         for (int ti = 0; ti < 16; ++ti) { const int tk = D ? 15 - ti : ti;
;             hc = av[ti] * hc + iv[ti]; Ap *= av[ti];
;             if (FINAL) { const size_t row = (size_t)(rowbase + mt * 16 + tk);
;                 if (D == 0) TMP[row * 512 + ch] = (bf16_t)f2bf(hc);
;                 else MIX[row * DM + ch] = (bf16_t)f2bf(grv[ti] * (hfv[ti] + hc)); }
	v_pk_mul_f32 v[26:27], v[26:27], v[42:43]
	v_pk_mul_f32 v[28:29], v[28:29], v[44:45]
	v_pk_mul_f32 v[30:31], v[30:31], v[46:47]
	v_pk_mul_f32 v[16:17], v[16:17], v[48:49]
	v_pk_mul_f32 v[18:19], v[18:19], v[50:51]
	v_pk_mul_f32 v[20:21], v[20:21], v[52:53]
	v_pk_mul_f32 v[22:23], v[22:23], v[54:55]
	v_pk_mul_f32 v[24:25], v[24:25], v[56:57]
	v_pk_mul_f32 v[26:27], v[26:27], v[58:59]
	v_pk_mul_f32 v[28:29], v[28:29], v[60:61]
	v_pk_mul_f32 v[30:31], v[30:31], v[62:63]
	s_add_i32 s39, s15, 46
	s_lshl_b32 s39, s39, 11
	s_add_u32 s90, s0, 0x7b00000
	s_addc_u32 s91, s1, 0
	s_add_u32 s90, s90, s39
	s_addc_u32 s91, s91, 0
	v_lshlrev_b32_e32 v48, 16, v174
	v_and_b32_e32 v49, 0xffff0000, v174
	v_lshlrev_b32_e32 v50, 16, v175
	v_and_b32_e32 v51, 0xffff0000, v175
	v_lshlrev_b32_e32 v52, 16, v176
	v_and_b32_e32 v53, 0xffff0000, v176
	v_lshlrev_b32_e32 v54, 16, v177
	v_and_b32_e32 v55, 0xffff0000, v177
	v_lshlrev_b32_e32 v56, 16, v178
	v_and_b32_e32 v57, 0xffff0000, v178
	v_lshlrev_b32_e32 v58, 16, v179
	v_and_b32_e32 v59, 0xffff0000, v179
	v_lshlrev_b32_e32 v60, 16, v180
	v_and_b32_e32 v61, 0xffff0000, v180
	v_lshlrev_b32_e32 v62, 16, v181
	v_and_b32_e32 v63, 0xffff0000, v181
	v_fma_f32 v47, v15, v250, v31
	v_fma_f32 v46, v14, v47, v30
	v_fma_f32 v45, v13, v46, v29
	v_fma_f32 v44, v12, v45, v28
	v_fma_f32 v43, v11, v44, v27
	v_fma_f32 v42, v10, v43, v26
	v_fma_f32 v41, v9, v42, v25
	v_fma_f32 v40, v8, v41, v24
	v_fma_f32 v39, v7, v40, v23
	v_fma_f32 v38, v6, v39, v22
	v_fma_f32 v37, v5, v38, v21
	v_fma_f32 v36, v4, v37, v20
	v_fma_f32 v35, v3, v36, v19
	v_fma_f32 v34, v2, v35, v18
	v_fma_f32 v33, v1, v34, v17
	v_fma_f32 v32, v0, v33, v16
	v_mov_b32_e32 v250, v32
	v_pk_add_f32 v[48:49], v[48:49], v[32:33]
	v_pk_add_f32 v[50:51], v[50:51], v[34:35]
	v_pk_add_f32 v[52:53], v[52:53], v[36:37]
	v_pk_add_f32 v[54:55], v[54:55], v[38:39]
	v_pk_add_f32 v[56:57], v[56:57], v[40:41]
	v_pk_add_f32 v[58:59], v[58:59], v[42:43]
	v_pk_add_f32 v[60:61], v[60:61], v[44:45]
	v_pk_add_f32 v[62:63], v[62:63], v[46:47]
	v_pk_mul_f32 v[48:49], v[206:207], v[48:49]
	v_pk_mul_f32 v[50:51], v[208:209], v[50:51]
	v_pk_mul_f32 v[52:53], v[210:211], v[52:53]
	v_pk_mul_f32 v[54:55], v[212:213], v[54:55]
	v_pk_mul_f32 v[56:57], v[214:215], v[56:57]
	v_pk_mul_f32 v[58:59], v[216:217], v[58:59]
	v_pk_mul_f32 v[60:61], v[218:219], v[60:61]
	v_pk_mul_f32 v[62:63], v[222:223], v[62:63]
	v_cvt_pk_bf16_f32 v48, v48, v49
	v_cvt_pk_bf16_f32 v50, v50, v51
	v_cvt_pk_bf16_f32 v52, v52, v53
	v_cvt_pk_bf16_f32 v54, v54, v55
	v_cvt_pk_bf16_f32 v56, v56, v57
	v_cvt_pk_bf16_f32 v58, v58, v59
	v_cvt_pk_bf16_f32 v60, v60, v61
	v_cvt_pk_bf16_f32 v62, v62, v63
	global_store_short_d16_hi v234, v62, s[90:91] offset:2048
	global_store_short v234, v62, s[90:91]
	s_sub_u32 s90, s90, 0x1000
	s_subb_u32 s91, s91, 0
	global_store_short_d16_hi v234, v60, s[90:91] offset:2048
	global_store_short v234, v60, s[90:91]
	s_sub_u32 s90, s90, 0x1000
	s_subb_u32 s91, s91, 0
	global_store_short_d16_hi v234, v58, s[90:91] offset:2048
	global_store_short v234, v58, s[90:91]
	s_sub_u32 s90, s90, 0x1000
	s_subb_u32 s91, s91, 0
	global_store_short_d16_hi v234, v56, s[90:91] offset:2048
	global_store_short v234, v56, s[90:91]
	s_sub_u32 s90, s90, 0x1000
	s_subb_u32 s91, s91, 0
	global_store_short_d16_hi v234, v54, s[90:91] offset:2048
	global_store_short v234, v54, s[90:91]
	s_sub_u32 s90, s90, 0x1000
	s_subb_u32 s91, s91, 0
	global_store_short_d16_hi v234, v52, s[90:91] offset:2048
	global_store_short v234, v52, s[90:91]
	s_sub_u32 s90, s90, 0x1000
	s_subb_u32 s91, s91, 0
	global_store_short_d16_hi v234, v50, s[90:91] offset:2048
	global_store_short v234, v50, s[90:91]
	s_sub_u32 s90, s90, 0x1000
	s_subb_u32 s91, s91, 0
	global_store_short_d16_hi v234, v48, s[90:91] offset:2048
	global_store_short v234, v48, s[90:91]
	ds_read_b128 v[32:35], v236 offset:2304
	ds_read_b128 v[36:39], v236 offset:2368
	s_waitcnt lgkmcnt(0)
	v_mfma_f32_16x16x32_bf16 v[0:3], v[32:35], v[80:83], 0
	v_mfma_f32_16x16x32_bf16 v[4:7], v[32:35], v[88:91], 0
	v_mfma_f32_16x16x32_bf16 v[8:11], v[32:35], v[96:99], 0
	v_mfma_f32_16x16x32_bf16 v[12:15], v[32:35], v[104:107], 0
	v_mfma_f32_16x16x32_bf16 v[16:19], v[32:35], v[112:115], 0
	v_mfma_f32_16x16x32_bf16 v[20:23], v[32:35], v[120:123], 0
	v_mfma_f32_16x16x32_bf16 v[24:27], v[32:35], v[128:131], 0
	v_mfma_f32_16x16x32_bf16 v[28:31], v[32:35], v[136:139], 0
	v_mfma_f32_16x16x32_bf16 v[0:3], v[36:39], v[84:87], v[0:3]
	v_mfma_f32_16x16x32_bf16 v[4:7], v[36:39], v[92:95], v[4:7]
	v_mfma_f32_16x16x32_bf16 v[8:11], v[36:39], v[100:103], v[8:11]
	v_mfma_f32_16x16x32_bf16 v[12:15], v[36:39], v[108:111], v[12:15]
	v_mfma_f32_16x16x32_bf16 v[16:19], v[36:39], v[116:119], v[16:19]
	v_mfma_f32_16x16x32_bf16 v[20:23], v[36:39], v[124:127], v[20:23]
	v_mfma_f32_16x16x32_bf16 v[24:27], v[36:39], v[132:135], v[24:27]
	v_mfma_f32_16x16x32_bf16 v[28:31], v[36:39], v[228:231], v[28:31]
	s_nop 3
	ds_write2_b32 v237, v0, v4 offset0:0 offset1:16
	ds_write2_b32 v237, v8, v12 offset0:32 offset1:48
	ds_write2_b32 v237, v1, v5 offset0:64 offset1:80
	ds_write2_b32 v237, v9, v13 offset0:96 offset1:112
	ds_write2_b32 v237, v2, v6 offset0:128 offset1:144
	ds_write2_b32 v237, v10, v14 offset0:160 offset1:176
	ds_write2_b32 v237, v3, v7 offset0:192 offset1:208
	ds_write2_b32 v237, v11, v15 offset0:224 offset1:240
	ds_write2_b32 v238, v16, v20 offset0:0 offset1:16
	ds_write2_b32 v238, v24, v28 offset0:32 offset1:48
	ds_write2_b32 v238, v17, v21 offset0:64 offset1:80
	ds_write2_b32 v238, v25, v29 offset0:96 offset1:112
	ds_write2_b32 v238, v18, v22 offset0:128 offset1:144
	ds_write2_b32 v238, v26, v30 offset0:160 offset1:176
	ds_write2_b32 v238, v19, v23 offset0:192 offset1:208
	ds_write2_b32 v238, v27, v31 offset0:224 offset1:240
	s_waitcnt lgkmcnt(0)
; #define WAVE_SYNC() asm volatile("s_waitcnt lgkmcnt(0)" ::: "memory")
; __device__ __forceinline__ float sigmoid_f(float x) { return rcpf_(1.f + __expf(-x)); }
; __device__ __forceinline__ float gelu_tanh_f(float x) { const float y = 0.7978845608028654f * (x + 0.044715f * x * x * x); return x * sigmoid_f(2.f * y); }
; template <bool FINAL, int D>
; __device__ __forceinline__ void rg_dir(PREF p, int l, int h, int ch, int sidx, int rowbase  , LAS bf16_t* sXc, LAS float* stg, int lane) {
;     ...
;             for (int ti = 0; ti < 16; ++ti) { const size_t row = (size_t)(rowbase + mt * 16 + 15 - ti); grv[ti] = __builtin_bit_cast(float, (unsigned)P[row * PW + 512 + ch]); hfv[ti] = __builtin_bit_cast(float, (unsigned)TMP[row * 512 + ch]); }
;     ...
;             for (int j = 0; j < 4; ++j) { const int o = ((lane >> 4) * 4 + j) * 64 + nt * 16 + (lane & 15); stg[o] = ar[nt][j]; stg[1024 + o] = ai[nt][j]; }
;         WAVE_SYNC();
;         float av[16], iv[16];
; #pragma unroll
;         for (int ti = 0; ti < 16; ++ti) { const int tk = D ? 15 - ti : ti;
;             const float zr = stg[tk * 64 + lane] + ba, zi = stg[1024 + tk * 64 + lane] + bi;
;             const float r = sigmoid_f(zr), ig = sigmoid_f(zi);
;             const float a = __builtin_amdgcn_exp2f(r * sp8);
;             const float xc = bf2f(sXc[(mt * 16 + tk) * 72 + lane]);
;             av[ti] = a; iv[ti] = __builtin_amdgcn_sqrtf(fmaxf(1.f - a * a, 0.f)) * ig * xc;
;             if (FINAL && D == 1) grv[ti] = gelu_tanh_f(grv[ti]);
	ds_read2st64_b32 v[0:1], v239 offset0:36 offset1:37
	ds_read2st64_b32 v[2:3], v239 offset0:38 offset1:39
	ds_read2st64_b32 v[4:5], v239 offset0:40 offset1:41
	ds_read2st64_b32 v[6:7], v239 offset0:42 offset1:43
	ds_read2st64_b32 v[8:9], v239 offset0:44 offset1:45
	ds_read2st64_b32 v[10:11], v239 offset0:46 offset1:47
	ds_read2st64_b32 v[12:13], v239 offset0:48 offset1:49
	ds_read2st64_b32 v[14:15], v239 offset0:50 offset1:51
	ds_read2st64_b32 v[16:17], v239 offset0:52 offset1:53
	ds_read2st64_b32 v[18:19], v239 offset0:54 offset1:55
	ds_read2st64_b32 v[20:21], v239 offset0:56 offset1:57
	ds_read2st64_b32 v[22:23], v239 offset0:58 offset1:59
	ds_read2st64_b32 v[24:25], v239 offset0:60 offset1:61
	ds_read2st64_b32 v[26:27], v239 offset0:62 offset1:63
	ds_read2st64_b32 v[28:29], v239 offset0:64 offset1:65
	ds_read2st64_b32 v[30:31], v239 offset0:66 offset1:67
	ds_read_u16 v48, v240 offset:2304
	ds_read_u16 v49, v240 offset:2448
	ds_read_u16 v50, v240 offset:2592
	ds_read_u16 v51, v240 offset:2736
	ds_read_u16 v52, v240 offset:2880
	ds_read_u16 v53, v240 offset:3024
	ds_read_u16 v54, v240 offset:3168
	ds_read_u16 v55, v240 offset:3312
	ds_read_u16 v56, v240 offset:3456
	ds_read_u16 v57, v240 offset:3600
	ds_read_u16 v58, v240 offset:3744
	ds_read_u16 v59, v240 offset:3888
	ds_read_u16 v60, v240 offset:4032
	ds_read_u16 v61, v240 offset:4176
	ds_read_u16 v62, v240 offset:4320
	ds_read_u16 v63, v240 offset:4464
	s_waitcnt vmcnt(16)
	v_lshlrev_b32_e32 v206, 16, v190
	v_lshlrev_b32_e32 v207, 16, v191
	v_lshlrev_b32_e32 v208, 16, v192
	v_lshlrev_b32_e32 v209, 16, v193
	v_lshlrev_b32_e32 v210, 16, v194
	v_lshlrev_b32_e32 v211, 16, v195
	v_lshlrev_b32_e32 v212, 16, v196
	v_lshlrev_b32_e32 v213, 16, v197
	v_lshlrev_b32_e32 v214, 16, v198
	v_lshlrev_b32_e32 v215, 16, v199
	v_lshlrev_b32_e32 v216, 16, v200
	v_lshlrev_b32_e32 v217, 16, v201
	v_lshlrev_b32_e32 v218, 16, v202
	v_lshlrev_b32_e32 v219, 16, v203
	v_lshlrev_b32_e32 v222, 16, v204
	v_lshlrev_b32_e32 v223, 16, v205
	v_pk_mul_f32 v[32:33], v[140:141], v[206:207]
	v_pk_mul_f32 v[34:35], v[140:141], v[208:209]
	v_pk_mul_f32 v[36:37], v[140:141], v[210:211]
	v_pk_mul_f32 v[38:39], v[140:141], v[212:213]
	v_pk_mul_f32 v[40:41], v[140:141], v[214:215]
	v_pk_mul_f32 v[42:43], v[140:141], v[216:217]
	v_pk_mul_f32 v[44:45], v[140:141], v[218:219]
	v_pk_mul_f32 v[46:47], v[140:141], v[222:223]
	v_pk_mul_f32 v[32:33], v[32:33], v[206:207]
	v_pk_mul_f32 v[34:35], v[34:35], v[208:209]
	v_pk_mul_f32 v[36:37], v[36:37], v[210:211]
	v_pk_mul_f32 v[38:39], v[38:39], v[212:213]
	v_pk_mul_f32 v[40:41], v[40:41], v[214:215]
	v_pk_mul_f32 v[42:43], v[42:43], v[216:217]
	v_pk_mul_f32 v[44:45], v[44:45], v[218:219]
	v_pk_mul_f32 v[46:47], v[46:47], v[222:223]
	v_fma_f32 v32, v32, v206, v206
	v_fma_f32 v33, v33, v207, v207
	v_fma_f32 v34, v34, v208, v208
	v_fma_f32 v35, v35, v209, v209
	v_fma_f32 v36, v36, v210, v210
	v_fma_f32 v37, v37, v211, v211
	v_fma_f32 v38, v38, v212, v212
	v_fma_f32 v39, v39, v213, v213
	v_fma_f32 v40, v40, v214, v214
	v_fma_f32 v41, v41, v215, v215
	v_fma_f32 v42, v42, v216, v216
	v_fma_f32 v43, v43, v217, v217
	v_fma_f32 v44, v44, v218, v218
	v_fma_f32 v45, v45, v219, v219
	v_fma_f32 v46, v46, v222, v222
	v_fma_f32 v47, v47, v223, v223
	s_mov_b32 s98, 0xc0135761
	v_pk_mul_f32 v[32:33], v[32:33], s[98:99] op_sel_hi:[1,0]
	v_pk_mul_f32 v[34:35], v[34:35], s[98:99] op_sel_hi:[1,0]
	v_pk_mul_f32 v[36:37], v[36:37], s[98:99] op_sel_hi:[1,0]
	v_pk_mul_f32 v[38:39], v[38:39], s[98:99] op_sel_hi:[1,0]
	v_pk_mul_f32 v[40:41], v[40:41], s[98:99] op_sel_hi:[1,0]
	v_pk_mul_f32 v[42:43], v[42:43], s[98:99] op_sel_hi:[1,0]
	v_pk_mul_f32 v[44:45], v[44:45], s[98:99] op_sel_hi:[1,0]
	v_pk_mul_f32 v[46:47], v[46:47], s[98:99] op_sel_hi:[1,0]
	v_exp_f32_e32 v32, v32
	v_exp_f32_e32 v33, v33
	v_exp_f32_e32 v34, v34
	v_exp_f32_e32 v35, v35
	v_exp_f32_e32 v36, v36
	v_exp_f32_e32 v37, v37
	v_exp_f32_e32 v38, v38
	v_exp_f32_e32 v39, v39
	v_exp_f32_e32 v40, v40
	v_exp_f32_e32 v41, v41
	v_exp_f32_e32 v42, v42
	v_exp_f32_e32 v43, v43
	v_exp_f32_e32 v44, v44
	v_exp_f32_e32 v45, v45
	v_exp_f32_e32 v46, v46
	v_exp_f32_e32 v47, v47
	v_pk_add_f32 v[32:33], v[32:33], 1.0 op_sel_hi:[1,0]
	v_pk_add_f32 v[34:35], v[34:35], 1.0 op_sel_hi:[1,0]
	v_pk_add_f32 v[36:37], v[36:37], 1.0 op_sel_hi:[1,0]
	v_pk_add_f32 v[38:39], v[38:39], 1.0 op_sel_hi:[1,0]
	v_pk_add_f32 v[40:41], v[40:41], 1.0 op_sel_hi:[1,0]
	v_pk_add_f32 v[42:43], v[42:43], 1.0 op_sel_hi:[1,0]
	v_pk_add_f32 v[44:45], v[44:45], 1.0 op_sel_hi:[1,0]
	v_pk_add_f32 v[46:47], v[46:47], 1.0 op_sel_hi:[1,0]
	v_rcp_f32_e32 v32, v32
	v_rcp_f32_e32 v33, v33
	v_rcp_f32_e32 v34, v34
	v_rcp_f32_e32 v35, v35
	v_rcp_f32_e32 v36, v36
	v_rcp_f32_e32 v37, v37
	v_rcp_f32_e32 v38, v38
	v_rcp_f32_e32 v39, v39
	v_rcp_f32_e32 v40, v40
	v_rcp_f32_e32 v41, v41
	v_rcp_f32_e32 v42, v42
	v_rcp_f32_e32 v43, v43
	v_rcp_f32_e32 v44, v44
	v_rcp_f32_e32 v45, v45
	v_rcp_f32_e32 v46, v46
	v_rcp_f32_e32 v47, v47
	s_nop 0
	v_pk_mul_f32 v[206:207], v[32:33], v[206:207]
	v_pk_mul_f32 v[208:209], v[34:35], v[208:209]
	v_pk_mul_f32 v[210:211], v[36:37], v[210:211]
	v_pk_mul_f32 v[212:213], v[38:39], v[212:213]
	v_pk_mul_f32 v[214:215], v[40:41], v[214:215]
	v_pk_mul_f32 v[216:217], v[42:43], v[216:217]
	v_pk_mul_f32 v[218:219], v[44:45], v[218:219]
	v_pk_mul_f32 v[222:223], v[46:47], v[222:223]
	s_add_i32 s39, s15, 0
	s_mul_hi_u32 s83, s39, 0x1600
	s_mul_i32 s82, s39, 0x1600
	s_add_u32 s82, s82, s0
	s_addc_u32 s83, s83, s1
	s_add_u32 s82, s82, 0xbc00400
	s_addc_u32 s83, s83, 0
	global_load_ushort v190, v234, s[82:83]
	s_add_u32 s82, s82, 0x1600
	s_addc_u32 s83, s83, 0
	global_load_ushort v191, v234, s[82:83]
	s_add_u32 s82, s82, 0x1600
	s_addc_u32 s83, s83, 0
	global_load_ushort v192, v234, s[82:83]
	s_add_u32 s82, s82, 0x1600
	s_addc_u32 s83, s83, 0
	global_load_ushort v193, v234, s[82:83]
	s_add_u32 s82, s82, 0x1600
	s_addc_u32 s83, s83, 0
	global_load_ushort v194, v234, s[82:83]
	s_add_u32 s82, s82, 0x1600
	s_addc_u32 s83, s83, 0
	global_load_ushort v195, v234, s[82:83]
	s_add_u32 s82, s82, 0x1600
	s_addc_u32 s83, s83, 0
	global_load_ushort v196, v234, s[82:83]
	s_add_u32 s82, s82, 0x1600
	s_addc_u32 s83, s83, 0
	global_load_ushort v197, v234, s[82:83]
	s_add_u32 s82, s82, 0x1600
	s_addc_u32 s83, s83, 0
	global_load_ushort v198, v234, s[82:83]
	s_add_u32 s82, s82, 0x1600
	s_addc_u32 s83, s83, 0
	global_load_ushort v199, v234, s[82:83]
	s_add_u32 s82, s82, 0x1600
	s_addc_u32 s83, s83, 0
	global_load_ushort v200, v234, s[82:83]
	s_add_u32 s82, s82, 0x1600
	s_addc_u32 s83, s83, 0
	global_load_ushort v201, v234, s[82:83]
	s_add_u32 s82, s82, 0x1600
	s_addc_u32 s83, s83, 0
	global_load_ushort v202, v234, s[82:83]
	s_add_u32 s82, s82, 0x1600
	s_addc_u32 s83, s83, 0
	global_load_ushort v203, v234, s[82:83]
	s_add_u32 s82, s82, 0x1600
	s_addc_u32 s83, s83, 0
	global_load_ushort v204, v234, s[82:83]
	s_add_u32 s82, s82, 0x1600
	s_addc_u32 s83, s83, 0
	global_load_ushort v205, v234, s[82:83]
	s_waitcnt lgkmcnt(0)
; __device__ __forceinline__ float sigmoid_f(float x) { return rcpf_(1.f + __expf(-x)); }
; template <bool FINAL, int D>
; __device__ __forceinline__ void rg_dir(PREF p, int l, int h, int ch, int sidx, int rowbase  , LAS bf16_t* sXc, LAS float* stg, int lane) {
;     ...
;         for (int ti = 0; ti < 16; ++ti) { const int tk = D ? 15 - ti : ti;
;             const float zr = stg[tk * 64 + lane] + ba, zi = stg[1024 + tk * 64 + lane] + bi;
;             const float r = sigmoid_f(zr), ig = sigmoid_f(zi);
;             const float a = __builtin_amdgcn_exp2f(r * sp8);
;             const float xc = bf2f(sXc[(mt * 16 + tk) * 72 + lane]);
;             av[ti] = a; iv[ti] = __builtin_amdgcn_sqrtf(fmaxf(1.f - a * a, 0.f)) * ig * xc;
	v_pk_fma_f32 v[0:1], v[0:1], v[248:249], v[242:243]
	v_pk_fma_f32 v[2:3], v[2:3], v[248:249], v[242:243]
	v_pk_fma_f32 v[4:5], v[4:5], v[248:249], v[242:243]
	v_pk_fma_f32 v[6:7], v[6:7], v[248:249], v[242:243]
	v_pk_fma_f32 v[8:9], v[8:9], v[248:249], v[242:243]
	v_pk_fma_f32 v[10:11], v[10:11], v[248:249], v[242:243]
	v_pk_fma_f32 v[12:13], v[12:13], v[248:249], v[242:243]
	v_pk_fma_f32 v[14:15], v[14:15], v[248:249], v[242:243]
	v_pk_fma_f32 v[16:17], v[16:17], v[248:249], v[244:245]
	v_pk_fma_f32 v[18:19], v[18:19], v[248:249], v[244:245]
	v_pk_fma_f32 v[20:21], v[20:21], v[248:249], v[244:245]
	v_pk_fma_f32 v[22:23], v[22:23], v[248:249], v[244:245]
	v_pk_fma_f32 v[24:25], v[24:25], v[248:249], v[244:245]
	v_pk_fma_f32 v[26:27], v[26:27], v[248:249], v[244:245]
	v_pk_fma_f32 v[28:29], v[28:29], v[248:249], v[244:245]
	v_pk_fma_f32 v[30:31], v[30:31], v[248:249], v[244:245]
	v_exp_f32_e32 v0, v0
	v_exp_f32_e32 v1, v1
	v_exp_f32_e32 v2, v2
	v_exp_f32_e32 v3, v3
	v_exp_f32_e32 v4, v4
	v_exp_f32_e32 v5, v5
	v_exp_f32_e32 v6, v6
	v_exp_f32_e32 v7, v7
	v_exp_f32_e32 v8, v8
	v_exp_f32_e32 v9, v9
	v_exp_f32_e32 v10, v10
	v_exp_f32_e32 v11, v11
	v_exp_f32_e32 v12, v12
	v_exp_f32_e32 v13, v13
	v_exp_f32_e32 v14, v14
	v_exp_f32_e32 v15, v15
	v_exp_f32_e32 v16, v16
	v_exp_f32_e32 v17, v17
	v_exp_f32_e32 v18, v18
	v_exp_f32_e32 v19, v19
	v_exp_f32_e32 v20, v20
	v_exp_f32_e32 v21, v21
	v_exp_f32_e32 v22, v22
	v_exp_f32_e32 v23, v23
	v_exp_f32_e32 v24, v24
	v_exp_f32_e32 v25, v25
	v_exp_f32_e32 v26, v26
	v_exp_f32_e32 v27, v27
	v_exp_f32_e32 v28, v28
	v_exp_f32_e32 v29, v29
	v_exp_f32_e32 v30, v30
	v_exp_f32_e32 v31, v31
	v_pk_add_f32 v[0:1], v[0:1], 1.0 op_sel_hi:[1,0]
	v_pk_add_f32 v[2:3], v[2:3], 1.0 op_sel_hi:[1,0]
	v_pk_add_f32 v[4:5], v[4:5], 1.0 op_sel_hi:[1,0]
	v_pk_add_f32 v[6:7], v[6:7], 1.0 op_sel_hi:[1,0]
	v_pk_add_f32 v[8:9], v[8:9], 1.0 op_sel_hi:[1,0]
	v_pk_add_f32 v[10:11], v[10:11], 1.0 op_sel_hi:[1,0]
	v_pk_add_f32 v[12:13], v[12:13], 1.0 op_sel_hi:[1,0]
	v_pk_add_f32 v[14:15], v[14:15], 1.0 op_sel_hi:[1,0]
	v_pk_add_f32 v[16:17], v[16:17], 1.0 op_sel_hi:[1,0]
	v_pk_add_f32 v[18:19], v[18:19], 1.0 op_sel_hi:[1,0]
	v_pk_add_f32 v[20:21], v[20:21], 1.0 op_sel_hi:[1,0]
	v_pk_add_f32 v[22:23], v[22:23], 1.0 op_sel_hi:[1,0]
	v_pk_add_f32 v[24:25], v[24:25], 1.0 op_sel_hi:[1,0]
	v_pk_add_f32 v[26:27], v[26:27], 1.0 op_sel_hi:[1,0]
	v_pk_add_f32 v[28:29], v[28:29], 1.0 op_sel_hi:[1,0]
	v_pk_add_f32 v[30:31], v[30:31], 1.0 op_sel_hi:[1,0]
	v_rcp_f32_e32 v0, v0
	v_rcp_f32_e32 v1, v1
	v_rcp_f32_e32 v2, v2
	v_rcp_f32_e32 v3, v3
	v_rcp_f32_e32 v4, v4
	v_rcp_f32_e32 v5, v5
	v_rcp_f32_e32 v6, v6
	v_rcp_f32_e32 v7, v7
	v_rcp_f32_e32 v8, v8
	v_rcp_f32_e32 v9, v9
	v_rcp_f32_e32 v10, v10
	v_rcp_f32_e32 v11, v11
	v_rcp_f32_e32 v12, v12
	v_rcp_f32_e32 v13, v13
	v_rcp_f32_e32 v14, v14
	v_rcp_f32_e32 v15, v15
	v_rcp_f32_e32 v16, v16
	v_rcp_f32_e32 v17, v17
	v_rcp_f32_e32 v18, v18
	v_rcp_f32_e32 v19, v19
	v_rcp_f32_e32 v20, v20
	v_rcp_f32_e32 v21, v21
	v_rcp_f32_e32 v22, v22
	v_rcp_f32_e32 v23, v23
	v_rcp_f32_e32 v24, v24
	v_rcp_f32_e32 v25, v25
	v_rcp_f32_e32 v26, v26
	v_rcp_f32_e32 v27, v27
	v_rcp_f32_e32 v28, v28
	v_rcp_f32_e32 v29, v29
	v_rcp_f32_e32 v30, v30
	v_rcp_f32_e32 v31, v31
	v_pk_mul_f32 v[0:1], v[246:247], v[0:1]
	v_pk_mul_f32 v[2:3], v[246:247], v[2:3]
	v_pk_mul_f32 v[4:5], v[246:247], v[4:5]
	v_pk_mul_f32 v[6:7], v[246:247], v[6:7]
	v_pk_mul_f32 v[8:9], v[246:247], v[8:9]
	v_pk_mul_f32 v[10:11], v[246:247], v[10:11]
	v_pk_mul_f32 v[12:13], v[246:247], v[12:13]
	v_pk_mul_f32 v[14:15], v[246:247], v[14:15]
	v_lshlrev_b32_e32 v48, 16, v48
	v_lshlrev_b32_e32 v49, 16, v49
	v_lshlrev_b32_e32 v50, 16, v50
	v_lshlrev_b32_e32 v51, 16, v51
	v_lshlrev_b32_e32 v52, 16, v52
	v_lshlrev_b32_e32 v53, 16, v53
	v_lshlrev_b32_e32 v54, 16, v54
	v_lshlrev_b32_e32 v55, 16, v55
	v_lshlrev_b32_e32 v56, 16, v56
	v_lshlrev_b32_e32 v57, 16, v57
	v_lshlrev_b32_e32 v58, 16, v58
	v_lshlrev_b32_e32 v59, 16, v59
	v_lshlrev_b32_e32 v60, 16, v60
	v_lshlrev_b32_e32 v61, 16, v61
	v_lshlrev_b32_e32 v62, 16, v62
	v_lshlrev_b32_e32 v63, 16, v63
	v_exp_f32_e32 v0, v0
	v_exp_f32_e32 v1, v1
	v_exp_f32_e32 v2, v2
	v_exp_f32_e32 v3, v3
	v_exp_f32_e32 v4, v4
	v_exp_f32_e32 v5, v5
	v_exp_f32_e32 v6, v6
	v_exp_f32_e32 v7, v7
	v_exp_f32_e32 v8, v8
	v_exp_f32_e32 v9, v9
	v_exp_f32_e32 v10, v10
	v_exp_f32_e32 v11, v11
	v_exp_f32_e32 v12, v12
	v_exp_f32_e32 v13, v13
	v_exp_f32_e32 v14, v14
	v_exp_f32_e32 v15, v15
	v_fma_f32 v32, -v0, v0, 1.0 clamp
	v_fma_f32 v33, -v1, v1, 1.0 clamp
	v_fma_f32 v34, -v2, v2, 1.0 clamp
	v_fma_f32 v35, -v3, v3, 1.0 clamp
	v_fma_f32 v36, -v4, v4, 1.0 clamp
	v_fma_f32 v37, -v5, v5, 1.0 clamp
	v_fma_f32 v38, -v6, v6, 1.0 clamp
	v_fma_f32 v39, -v7, v7, 1.0 clamp
	v_fma_f32 v40, -v8, v8, 1.0 clamp
	v_fma_f32 v41, -v9, v9, 1.0 clamp
	v_fma_f32 v42, -v10, v10, 1.0 clamp
	v_fma_f32 v43, -v11, v11, 1.0 clamp
	v_fma_f32 v44, -v12, v12, 1.0 clamp
	v_fma_f32 v45, -v13, v13, 1.0 clamp
	v_fma_f32 v46, -v14, v14, 1.0 clamp
	v_fma_f32 v47, -v15, v15, 1.0 clamp
	v_sqrt_f32_e32 v32, v32
	v_sqrt_f32_e32 v33, v33
	v_sqrt_f32_e32 v34, v34
	v_sqrt_f32_e32 v35, v35
	v_sqrt_f32_e32 v36, v36
	v_sqrt_f32_e32 v37, v37
	v_sqrt_f32_e32 v38, v38
	v_sqrt_f32_e32 v39, v39
	v_sqrt_f32_e32 v40, v40
	v_sqrt_f32_e32 v41, v41
	v_sqrt_f32_e32 v42, v42
	v_sqrt_f32_e32 v43, v43
	v_sqrt_f32_e32 v44, v44
	v_sqrt_f32_e32 v45, v45
	v_sqrt_f32_e32 v46, v46
	v_sqrt_f32_e32 v47, v47
	s_nop 0
	v_pk_mul_f32 v[16:17], v[16:17], v[32:33]
	v_pk_mul_f32 v[18:19], v[18:19], v[34:35]
	v_pk_mul_f32 v[20:21], v[20:21], v[36:37]
	v_pk_mul_f32 v[22:23], v[22:23], v[38:39]
	v_pk_mul_f32 v[24:25], v[24:25], v[40:41]
; #define LAS __attribute__((address_space(3)))
; #define WAVE_SYNC() asm volatile("s_waitcnt lgkmcnt(0)" ::: "memory")
; __device__ __forceinline__ unsigned f2bf(float f) { unsigned r; asm("v_cvt_pk_bf16_f32 %0, %1, %1" : "=v"(r) : "v"(f)); return r & 0xffffu; }
; __device__ __forceinline__ f32x4 mfma16(bf16x8 a, bf16x8 b, f32x4 c) { return __builtin_amdgcn_mfma_f32_16x16x32_bf16(a, b, c, 0, 0, 0); }
; template <bool FINAL, int D>
; __device__ __forceinline__ void rg_dir(PREF p, int l, int h, int ch, int sidx, int rowbase  , LAS bf16_t* sXc, LAS float* stg, int lane) {
;     ...
;         const bf16x8 A0 = *(const LAS bf16x8*)(sXc + (mt * 16 + (lane & 15)) * 72 + (lane >> 4) * 8), A1 = *(const LAS bf16x8*)(sXc + (mt * 16 + (lane & 15)) * 72 + 32 + (lane >> 4) * 8);
;         f32x4 ar[4], ai[4];
; #pragma unroll
;         for (int nt = 0; nt < 4; ++nt) { const f32x4 z = {0.f, 0.f, 0.f, 0.f};
;             ar[nt] = mfma16(A0, Br[nt][0], z); ar[nt] = mfma16(A1, Br[nt][1], ar[nt]); ai[nt] = mfma16(A0, Bi[nt][0], z); ai[nt] = mfma16(A1, Bi[nt][1], ai[nt]); }
;         WAVE_SYNC();
; #pragma unroll
;         for (int nt = 0; nt < 4; ++nt)
; #pragma unroll
;             for (int j = 0; j < 4; ++j) { const int o = ((lane >> 4) * 4 + j) * 64 + nt * 16 + (lane & 15); stg[o] = ar[nt][j]; stg[1024 + o] = ai[nt][j]; }
;     ...
;         for (int ti = 0; ti < 16; ++ti) { const int tk = D ? 15 - ti : ti;
;             hc = av[ti] * hc + iv[ti]; Ap *= av[ti];
;             if (FINAL) { const size_t row = (size_t)(rowbase + mt * 16 + tk);
;                 if (D == 0) TMP[row * 512 + ch] = (bf16_t)f2bf(hc);
;                 else MIX[row * DM + ch] = (bf16_t)f2bf(grv[ti] * (hfv[ti] + hc)); }
	v_pk_mul_f32 v[26:27], v[26:27], v[42:43]
	v_pk_mul_f32 v[28:29], v[28:29], v[44:45]
	v_pk_mul_f32 v[30:31], v[30:31], v[46:47]
	v_pk_mul_f32 v[16:17], v[16:17], v[48:49]
	v_pk_mul_f32 v[18:19], v[18:19], v[50:51]
	v_pk_mul_f32 v[20:21], v[20:21], v[52:53]
	v_pk_mul_f32 v[22:23], v[22:23], v[54:55]
	v_pk_mul_f32 v[24:25], v[24:25], v[56:57]
	v_pk_mul_f32 v[26:27], v[26:27], v[58:59]
	v_pk_mul_f32 v[28:29], v[28:29], v[60:61]
	v_pk_mul_f32 v[30:31], v[30:31], v[62:63]
	s_add_i32 s39, s15, 30
	s_lshl_b32 s39, s39, 11
	s_add_u32 s90, s0, 0x7b00000
	s_addc_u32 s91, s1, 0
	s_add_u32 s90, s90, s39
	s_addc_u32 s91, s91, 0
	v_lshlrev_b32_e32 v48, 16, v166
	v_and_b32_e32 v49, 0xffff0000, v166
	v_lshlrev_b32_e32 v50, 16, v167
	v_and_b32_e32 v51, 0xffff0000, v167
	v_lshlrev_b32_e32 v52, 16, v168
	v_and_b32_e32 v53, 0xffff0000, v168
	v_lshlrev_b32_e32 v54, 16, v169
	v_and_b32_e32 v55, 0xffff0000, v169
	v_lshlrev_b32_e32 v56, 16, v170
	v_and_b32_e32 v57, 0xffff0000, v170
	v_lshlrev_b32_e32 v58, 16, v171
	v_and_b32_e32 v59, 0xffff0000, v171
	v_lshlrev_b32_e32 v60, 16, v172
	v_and_b32_e32 v61, 0xffff0000, v172
	v_lshlrev_b32_e32 v62, 16, v173
	v_and_b32_e32 v63, 0xffff0000, v173
	v_fma_f32 v47, v15, v250, v31
	v_fma_f32 v46, v14, v47, v30
	v_fma_f32 v45, v13, v46, v29
	v_fma_f32 v44, v12, v45, v28
	v_fma_f32 v43, v11, v44, v27
	v_fma_f32 v42, v10, v43, v26
	v_fma_f32 v41, v9, v42, v25
	v_fma_f32 v40, v8, v41, v24
	v_fma_f32 v39, v7, v40, v23
	v_fma_f32 v38, v6, v39, v22
	v_fma_f32 v37, v5, v38, v21
	v_fma_f32 v36, v4, v37, v20
	v_fma_f32 v35, v3, v36, v19
	v_fma_f32 v34, v2, v35, v18
	v_fma_f32 v33, v1, v34, v17
	v_fma_f32 v32, v0, v33, v16
	v_mov_b32_e32 v250, v32
	v_pk_add_f32 v[48:49], v[48:49], v[32:33]
	v_pk_add_f32 v[50:51], v[50:51], v[34:35]
	v_pk_add_f32 v[52:53], v[52:53], v[36:37]
	v_pk_add_f32 v[54:55], v[54:55], v[38:39]
	v_pk_add_f32 v[56:57], v[56:57], v[40:41]
	v_pk_add_f32 v[58:59], v[58:59], v[42:43]
	v_pk_add_f32 v[60:61], v[60:61], v[44:45]
	v_pk_add_f32 v[62:63], v[62:63], v[46:47]
	v_pk_mul_f32 v[48:49], v[206:207], v[48:49]
	v_pk_mul_f32 v[50:51], v[208:209], v[50:51]
	v_pk_mul_f32 v[52:53], v[210:211], v[52:53]
	v_pk_mul_f32 v[54:55], v[212:213], v[54:55]
	v_pk_mul_f32 v[56:57], v[214:215], v[56:57]
	v_pk_mul_f32 v[58:59], v[216:217], v[58:59]
	v_pk_mul_f32 v[60:61], v[218:219], v[60:61]
	v_pk_mul_f32 v[62:63], v[222:223], v[62:63]
	v_cvt_pk_bf16_f32 v48, v48, v49
	v_cvt_pk_bf16_f32 v50, v50, v51
	v_cvt_pk_bf16_f32 v52, v52, v53
	v_cvt_pk_bf16_f32 v54, v54, v55
	v_cvt_pk_bf16_f32 v56, v56, v57
	v_cvt_pk_bf16_f32 v58, v58, v59
	v_cvt_pk_bf16_f32 v60, v60, v61
	v_cvt_pk_bf16_f32 v62, v62, v63
	global_store_short_d16_hi v234, v62, s[90:91] offset:2048
	global_store_short v234, v62, s[90:91]
	s_sub_u32 s90, s90, 0x1000
	s_subb_u32 s91, s91, 0
	global_store_short_d16_hi v234, v60, s[90:91] offset:2048
	global_store_short v234, v60, s[90:91]
	s_sub_u32 s90, s90, 0x1000
	s_subb_u32 s91, s91, 0
	global_store_short_d16_hi v234, v58, s[90:91] offset:2048
	global_store_short v234, v58, s[90:91]
	s_sub_u32 s90, s90, 0x1000
	s_subb_u32 s91, s91, 0
	global_store_short_d16_hi v234, v56, s[90:91] offset:2048
	global_store_short v234, v56, s[90:91]
	s_sub_u32 s90, s90, 0x1000
	s_subb_u32 s91, s91, 0
	global_store_short_d16_hi v234, v54, s[90:91] offset:2048
	global_store_short v234, v54, s[90:91]
	s_sub_u32 s90, s90, 0x1000
	s_subb_u32 s91, s91, 0
	global_store_short_d16_hi v234, v52, s[90:91] offset:2048
	global_store_short v234, v52, s[90:91]
	s_sub_u32 s90, s90, 0x1000
	s_subb_u32 s91, s91, 0
	global_store_short_d16_hi v234, v50, s[90:91] offset:2048
	global_store_short v234, v50, s[90:91]
	s_sub_u32 s90, s90, 0x1000
	s_subb_u32 s91, s91, 0
	global_store_short_d16_hi v234, v48, s[90:91] offset:2048
	global_store_short v234, v48, s[90:91]
	ds_read_b128 v[32:35], v236 offset:0
	ds_read_b128 v[36:39], v236 offset:64
	s_waitcnt lgkmcnt(0)
	v_mfma_f32_16x16x32_bf16 v[0:3], v[32:35], v[80:83], 0
	v_mfma_f32_16x16x32_bf16 v[4:7], v[32:35], v[88:91], 0
	v_mfma_f32_16x16x32_bf16 v[8:11], v[32:35], v[96:99], 0
	v_mfma_f32_16x16x32_bf16 v[12:15], v[32:35], v[104:107], 0
	v_mfma_f32_16x16x32_bf16 v[16:19], v[32:35], v[112:115], 0
	v_mfma_f32_16x16x32_bf16 v[20:23], v[32:35], v[120:123], 0
	v_mfma_f32_16x16x32_bf16 v[24:27], v[32:35], v[128:131], 0
	v_mfma_f32_16x16x32_bf16 v[28:31], v[32:35], v[136:139], 0
	v_mfma_f32_16x16x32_bf16 v[0:3], v[36:39], v[84:87], v[0:3]
	v_mfma_f32_16x16x32_bf16 v[4:7], v[36:39], v[92:95], v[4:7]
	v_mfma_f32_16x16x32_bf16 v[8:11], v[36:39], v[100:103], v[8:11]
	v_mfma_f32_16x16x32_bf16 v[12:15], v[36:39], v[108:111], v[12:15]
	v_mfma_f32_16x16x32_bf16 v[16:19], v[36:39], v[116:119], v[16:19]
	v_mfma_f32_16x16x32_bf16 v[20:23], v[36:39], v[124:127], v[20:23]
	v_mfma_f32_16x16x32_bf16 v[24:27], v[36:39], v[132:135], v[24:27]
	v_mfma_f32_16x16x32_bf16 v[28:31], v[36:39], v[228:231], v[28:31]
	s_nop 3
	ds_write2_b32 v237, v0, v4 offset0:0 offset1:16
	ds_write2_b32 v237, v8, v12 offset0:32 offset1:48
	ds_write2_b32 v237, v1, v5 offset0:64 offset1:80
	ds_write2_b32 v237, v9, v13 offset0:96 offset1:112
	ds_write2_b32 v237, v2, v6 offset0:128 offset1:144
	ds_write2_b32 v237, v10, v14 offset0:160 offset1:176
	ds_write2_b32 v237, v3, v7 offset0:192 offset1:208
	ds_write2_b32 v237, v11, v15 offset0:224 offset1:240
	ds_write2_b32 v238, v16, v20 offset0:0 offset1:16
	ds_write2_b32 v238, v24, v28 offset0:32 offset1:48
	ds_write2_b32 v238, v17, v21 offset0:64 offset1:80
	ds_write2_b32 v238, v25, v29 offset0:96 offset1:112
	ds_write2_b32 v238, v18, v22 offset0:128 offset1:144
	ds_write2_b32 v238, v26, v30 offset0:160 offset1:176
	ds_write2_b32 v238, v19, v23 offset0:192 offset1:208
	ds_write2_b32 v238, v27, v31 offset0:224 offset1:240
	s_waitcnt lgkmcnt(0)
; #define WAVE_SYNC() asm volatile("s_waitcnt lgkmcnt(0)" ::: "memory")
; __device__ __forceinline__ float sigmoid_f(float x) { return rcpf_(1.f + __expf(-x)); }
; __device__ __forceinline__ float gelu_tanh_f(float x) { const float y = 0.7978845608028654f * (x + 0.044715f * x * x * x); return x * sigmoid_f(2.f * y); }
; template <bool FINAL, int D>
; __device__ __forceinline__ void rg_dir(PREF p, int l, int h, int ch, int sidx, int rowbase  , LAS bf16_t* sXc, LAS float* stg, int lane) {
;     ...
;             for (int j = 0; j < 4; ++j) { const int o = ((lane >> 4) * 4 + j) * 64 + nt * 16 + (lane & 15); stg[o] = ar[nt][j]; stg[1024 + o] = ai[nt][j]; }
;         WAVE_SYNC();
;         float av[16], iv[16];
; #pragma unroll
;         for (int ti = 0; ti < 16; ++ti) { const int tk = D ? 15 - ti : ti;
;             const float zr = stg[tk * 64 + lane] + ba, zi = stg[1024 + tk * 64 + lane] + bi;
;             const float r = sigmoid_f(zr), ig = sigmoid_f(zi);
;             const float a = __builtin_amdgcn_exp2f(r * sp8);
;             const float xc = bf2f(sXc[(mt * 16 + tk) * 72 + lane]);
;             av[ti] = a; iv[ti] = __builtin_amdgcn_sqrtf(fmaxf(1.f - a * a, 0.f)) * ig * xc;
;             if (FINAL && D == 1) grv[ti] = gelu_tanh_f(grv[ti]);
	ds_read2st64_b32 v[0:1], v239 offset0:36 offset1:37
	ds_read2st64_b32 v[2:3], v239 offset0:38 offset1:39
	ds_read2st64_b32 v[4:5], v239 offset0:40 offset1:41
	ds_read2st64_b32 v[6:7], v239 offset0:42 offset1:43
	ds_read2st64_b32 v[8:9], v239 offset0:44 offset1:45
	ds_read2st64_b32 v[10:11], v239 offset0:46 offset1:47
	ds_read2st64_b32 v[12:13], v239 offset0:48 offset1:49
	ds_read2st64_b32 v[14:15], v239 offset0:50 offset1:51
	ds_read2st64_b32 v[16:17], v239 offset0:52 offset1:53
	ds_read2st64_b32 v[18:19], v239 offset0:54 offset1:55
	ds_read2st64_b32 v[20:21], v239 offset0:56 offset1:57
	ds_read2st64_b32 v[22:23], v239 offset0:58 offset1:59
	ds_read2st64_b32 v[24:25], v239 offset0:60 offset1:61
	ds_read2st64_b32 v[26:27], v239 offset0:62 offset1:63
	ds_read2st64_b32 v[28:29], v239 offset0:64 offset1:65
	ds_read2st64_b32 v[30:31], v239 offset0:66 offset1:67
	ds_read_u16 v48, v240 offset:0
	ds_read_u16 v49, v240 offset:144
	ds_read_u16 v50, v240 offset:288
	ds_read_u16 v51, v240 offset:432
	ds_read_u16 v52, v240 offset:576
	ds_read_u16 v53, v240 offset:720
	ds_read_u16 v54, v240 offset:864
	ds_read_u16 v55, v240 offset:1008
	ds_read_u16 v56, v240 offset:1152
	ds_read_u16 v57, v240 offset:1296
	ds_read_u16 v58, v240 offset:1440
	ds_read_u16 v59, v240 offset:1584
	ds_read_u16 v60, v240 offset:1728
	ds_read_u16 v61, v240 offset:1872
	ds_read_u16 v62, v240 offset:2016
	ds_read_u16 v63, v240 offset:2160
	s_waitcnt vmcnt(16)
	v_lshlrev_b32_e32 v206, 16, v190
	v_lshlrev_b32_e32 v207, 16, v191
	v_lshlrev_b32_e32 v208, 16, v192
	v_lshlrev_b32_e32 v209, 16, v193
	v_lshlrev_b32_e32 v210, 16, v194
	v_lshlrev_b32_e32 v211, 16, v195
	v_lshlrev_b32_e32 v212, 16, v196
	v_lshlrev_b32_e32 v213, 16, v197
	v_lshlrev_b32_e32 v214, 16, v198
	v_lshlrev_b32_e32 v215, 16, v199
	v_lshlrev_b32_e32 v216, 16, v200
	v_lshlrev_b32_e32 v217, 16, v201
	v_lshlrev_b32_e32 v218, 16, v202
	v_lshlrev_b32_e32 v219, 16, v203
	v_lshlrev_b32_e32 v222, 16, v204
	v_lshlrev_b32_e32 v223, 16, v205
	v_pk_mul_f32 v[32:33], v[140:141], v[206:207]
	v_pk_mul_f32 v[34:35], v[140:141], v[208:209]
	v_pk_mul_f32 v[36:37], v[140:141], v[210:211]
	v_pk_mul_f32 v[38:39], v[140:141], v[212:213]
	v_pk_mul_f32 v[40:41], v[140:141], v[214:215]
	v_pk_mul_f32 v[42:43], v[140:141], v[216:217]
	v_pk_mul_f32 v[44:45], v[140:141], v[218:219]
	v_pk_mul_f32 v[46:47], v[140:141], v[222:223]
	v_pk_mul_f32 v[32:33], v[32:33], v[206:207]
	v_pk_mul_f32 v[34:35], v[34:35], v[208:209]
	v_pk_mul_f32 v[36:37], v[36:37], v[210:211]
	v_pk_mul_f32 v[38:39], v[38:39], v[212:213]
	v_pk_mul_f32 v[40:41], v[40:41], v[214:215]
	v_pk_mul_f32 v[42:43], v[42:43], v[216:217]
	v_pk_mul_f32 v[44:45], v[44:45], v[218:219]
	v_pk_mul_f32 v[46:47], v[46:47], v[222:223]
	v_fma_f32 v32, v32, v206, v206
	v_fma_f32 v33, v33, v207, v207
	v_fma_f32 v34, v34, v208, v208
	v_fma_f32 v35, v35, v209, v209
	v_fma_f32 v36, v36, v210, v210
	v_fma_f32 v37, v37, v211, v211
	v_fma_f32 v38, v38, v212, v212
	v_fma_f32 v39, v39, v213, v213
	v_fma_f32 v40, v40, v214, v214
	v_fma_f32 v41, v41, v215, v215
	v_fma_f32 v42, v42, v216, v216
	v_fma_f32 v43, v43, v217, v217
	v_fma_f32 v44, v44, v218, v218
	v_fma_f32 v45, v45, v219, v219
	v_fma_f32 v46, v46, v222, v222
	v_fma_f32 v47, v47, v223, v223
	s_mov_b32 s98, 0xc0135761
	v_pk_mul_f32 v[32:33], v[32:33], s[98:99] op_sel_hi:[1,0]
	v_pk_mul_f32 v[34:35], v[34:35], s[98:99] op_sel_hi:[1,0]
	v_pk_mul_f32 v[36:37], v[36:37], s[98:99] op_sel_hi:[1,0]
	v_pk_mul_f32 v[38:39], v[38:39], s[98:99] op_sel_hi:[1,0]
	v_pk_mul_f32 v[40:41], v[40:41], s[98:99] op_sel_hi:[1,0]
	v_pk_mul_f32 v[42:43], v[42:43], s[98:99] op_sel_hi:[1,0]
	v_pk_mul_f32 v[44:45], v[44:45], s[98:99] op_sel_hi:[1,0]
	v_pk_mul_f32 v[46:47], v[46:47], s[98:99] op_sel_hi:[1,0]
	v_exp_f32_e32 v32, v32
	v_exp_f32_e32 v33, v33
	v_exp_f32_e32 v34, v34
	v_exp_f32_e32 v35, v35
	v_exp_f32_e32 v36, v36
	v_exp_f32_e32 v37, v37
	v_exp_f32_e32 v38, v38
	v_exp_f32_e32 v39, v39
	v_exp_f32_e32 v40, v40
	v_exp_f32_e32 v41, v41
	v_exp_f32_e32 v42, v42
	v_exp_f32_e32 v43, v43
	v_exp_f32_e32 v44, v44
	v_exp_f32_e32 v45, v45
	v_exp_f32_e32 v46, v46
	v_exp_f32_e32 v47, v47
	v_pk_add_f32 v[32:33], v[32:33], 1.0 op_sel_hi:[1,0]
	v_pk_add_f32 v[34:35], v[34:35], 1.0 op_sel_hi:[1,0]
	v_pk_add_f32 v[36:37], v[36:37], 1.0 op_sel_hi:[1,0]
	v_pk_add_f32 v[38:39], v[38:39], 1.0 op_sel_hi:[1,0]
	v_pk_add_f32 v[40:41], v[40:41], 1.0 op_sel_hi:[1,0]
	v_pk_add_f32 v[42:43], v[42:43], 1.0 op_sel_hi:[1,0]
	v_pk_add_f32 v[44:45], v[44:45], 1.0 op_sel_hi:[1,0]
	v_pk_add_f32 v[46:47], v[46:47], 1.0 op_sel_hi:[1,0]
	v_rcp_f32_e32 v32, v32
	v_rcp_f32_e32 v33, v33
	v_rcp_f32_e32 v34, v34
	v_rcp_f32_e32 v35, v35
	v_rcp_f32_e32 v36, v36
	v_rcp_f32_e32 v37, v37
	v_rcp_f32_e32 v38, v38
	v_rcp_f32_e32 v39, v39
	v_rcp_f32_e32 v40, v40
	v_rcp_f32_e32 v41, v41
	v_rcp_f32_e32 v42, v42
	v_rcp_f32_e32 v43, v43
	v_rcp_f32_e32 v44, v44
	v_rcp_f32_e32 v45, v45
	v_rcp_f32_e32 v46, v46
	v_rcp_f32_e32 v47, v47
	s_nop 0
	v_pk_mul_f32 v[206:207], v[32:33], v[206:207]
	v_pk_mul_f32 v[208:209], v[34:35], v[208:209]
	v_pk_mul_f32 v[210:211], v[36:37], v[210:211]
	v_pk_mul_f32 v[212:213], v[38:39], v[212:213]
	v_pk_mul_f32 v[214:215], v[40:41], v[214:215]
	v_pk_mul_f32 v[216:217], v[42:43], v[216:217]
	v_pk_mul_f32 v[218:219], v[44:45], v[218:219]
	v_pk_mul_f32 v[222:223], v[46:47], v[222:223]
	s_waitcnt lgkmcnt(0)
; __device__ __forceinline__ float sigmoid_f(float x) { return rcpf_(1.f + __expf(-x)); }
; template <bool FINAL, int D>
; __device__ __forceinline__ void rg_dir(PREF p, int l, int h, int ch, int sidx, int rowbase  , LAS bf16_t* sXc, LAS float* stg, int lane) {
;     ...
;         for (int ti = 0; ti < 16; ++ti) { const int tk = D ? 15 - ti : ti;
;             const float zr = stg[tk * 64 + lane] + ba, zi = stg[1024 + tk * 64 + lane] + bi;
;             const float r = sigmoid_f(zr), ig = sigmoid_f(zi);
;             const float a = __builtin_amdgcn_exp2f(r * sp8);
;             const float xc = bf2f(sXc[(mt * 16 + tk) * 72 + lane]);
;             av[ti] = a; iv[ti] = __builtin_amdgcn_sqrtf(fmaxf(1.f - a * a, 0.f)) * ig * xc;
	v_pk_fma_f32 v[0:1], v[0:1], v[248:249], v[242:243]
	v_pk_fma_f32 v[2:3], v[2:3], v[248:249], v[242:243]
	v_pk_fma_f32 v[4:5], v[4:5], v[248:249], v[242:243]
	v_pk_fma_f32 v[6:7], v[6:7], v[248:249], v[242:243]
	v_pk_fma_f32 v[8:9], v[8:9], v[248:249], v[242:243]
	v_pk_fma_f32 v[10:11], v[10:11], v[248:249], v[242:243]
	v_pk_fma_f32 v[12:13], v[12:13], v[248:249], v[242:243]
	v_pk_fma_f32 v[14:15], v[14:15], v[248:249], v[242:243]
	v_pk_fma_f32 v[16:17], v[16:17], v[248:249], v[244:245]
	v_pk_fma_f32 v[18:19], v[18:19], v[248:249], v[244:245]
	v_pk_fma_f32 v[20:21], v[20:21], v[248:249], v[244:245]
	v_pk_fma_f32 v[22:23], v[22:23], v[248:249], v[244:245]
	v_pk_fma_f32 v[24:25], v[24:25], v[248:249], v[244:245]
	v_pk_fma_f32 v[26:27], v[26:27], v[248:249], v[244:245]
	v_pk_fma_f32 v[28:29], v[28:29], v[248:249], v[244:245]
	v_pk_fma_f32 v[30:31], v[30:31], v[248:249], v[244:245]
	v_exp_f32_e32 v0, v0
	v_exp_f32_e32 v1, v1
	v_exp_f32_e32 v2, v2
	v_exp_f32_e32 v3, v3
	v_exp_f32_e32 v4, v4
	v_exp_f32_e32 v5, v5
	v_exp_f32_e32 v6, v6
	v_exp_f32_e32 v7, v7
	v_exp_f32_e32 v8, v8
	v_exp_f32_e32 v9, v9
	v_exp_f32_e32 v10, v10
	v_exp_f32_e32 v11, v11
	v_exp_f32_e32 v12, v12
	v_exp_f32_e32 v13, v13
	v_exp_f32_e32 v14, v14
	v_exp_f32_e32 v15, v15
	v_exp_f32_e32 v16, v16
	v_exp_f32_e32 v17, v17
	v_exp_f32_e32 v18, v18
	v_exp_f32_e32 v19, v19
	v_exp_f32_e32 v20, v20
	v_exp_f32_e32 v21, v21
	v_exp_f32_e32 v22, v22
	v_exp_f32_e32 v23, v23
	v_exp_f32_e32 v24, v24
	v_exp_f32_e32 v25, v25
	v_exp_f32_e32 v26, v26
	v_exp_f32_e32 v27, v27
	v_exp_f32_e32 v28, v28
	v_exp_f32_e32 v29, v29
	v_exp_f32_e32 v30, v30
	v_exp_f32_e32 v31, v31
	v_pk_add_f32 v[0:1], v[0:1], 1.0 op_sel_hi:[1,0]
	v_pk_add_f32 v[2:3], v[2:3], 1.0 op_sel_hi:[1,0]
	v_pk_add_f32 v[4:5], v[4:5], 1.0 op_sel_hi:[1,0]
	v_pk_add_f32 v[6:7], v[6:7], 1.0 op_sel_hi:[1,0]
	v_pk_add_f32 v[8:9], v[8:9], 1.0 op_sel_hi:[1,0]
	v_pk_add_f32 v[10:11], v[10:11], 1.0 op_sel_hi:[1,0]
	v_pk_add_f32 v[12:13], v[12:13], 1.0 op_sel_hi:[1,0]
	v_pk_add_f32 v[14:15], v[14:15], 1.0 op_sel_hi:[1,0]
	v_pk_add_f32 v[16:17], v[16:17], 1.0 op_sel_hi:[1,0]
	v_pk_add_f32 v[18:19], v[18:19], 1.0 op_sel_hi:[1,0]
	v_pk_add_f32 v[20:21], v[20:21], 1.0 op_sel_hi:[1,0]
	v_pk_add_f32 v[22:23], v[22:23], 1.0 op_sel_hi:[1,0]
	v_pk_add_f32 v[24:25], v[24:25], 1.0 op_sel_hi:[1,0]
	v_pk_add_f32 v[26:27], v[26:27], 1.0 op_sel_hi:[1,0]
	v_pk_add_f32 v[28:29], v[28:29], 1.0 op_sel_hi:[1,0]
	v_pk_add_f32 v[30:31], v[30:31], 1.0 op_sel_hi:[1,0]
	v_rcp_f32_e32 v0, v0
	v_rcp_f32_e32 v1, v1
	v_rcp_f32_e32 v2, v2
	v_rcp_f32_e32 v3, v3
	v_rcp_f32_e32 v4, v4
	v_rcp_f32_e32 v5, v5
	v_rcp_f32_e32 v6, v6
	v_rcp_f32_e32 v7, v7
	v_rcp_f32_e32 v8, v8
	v_rcp_f32_e32 v9, v9
	v_rcp_f32_e32 v10, v10
	v_rcp_f32_e32 v11, v11
	v_rcp_f32_e32 v12, v12
	v_rcp_f32_e32 v13, v13
	v_rcp_f32_e32 v14, v14
	v_rcp_f32_e32 v15, v15
	v_rcp_f32_e32 v16, v16
	v_rcp_f32_e32 v17, v17
	v_rcp_f32_e32 v18, v18
	v_rcp_f32_e32 v19, v19
	v_rcp_f32_e32 v20, v20
	v_rcp_f32_e32 v21, v21
	v_rcp_f32_e32 v22, v22
	v_rcp_f32_e32 v23, v23
	v_rcp_f32_e32 v24, v24
	v_rcp_f32_e32 v25, v25
	v_rcp_f32_e32 v26, v26
	v_rcp_f32_e32 v27, v27
	v_rcp_f32_e32 v28, v28
	v_rcp_f32_e32 v29, v29
	v_rcp_f32_e32 v30, v30
	v_rcp_f32_e32 v31, v31
	v_pk_mul_f32 v[0:1], v[246:247], v[0:1]
	v_pk_mul_f32 v[2:3], v[246:247], v[2:3]
	v_pk_mul_f32 v[4:5], v[246:247], v[4:5]
	v_pk_mul_f32 v[6:7], v[246:247], v[6:7]
	v_pk_mul_f32 v[8:9], v[246:247], v[8:9]
	v_pk_mul_f32 v[10:11], v[246:247], v[10:11]
	v_pk_mul_f32 v[12:13], v[246:247], v[12:13]
	v_pk_mul_f32 v[14:15], v[246:247], v[14:15]
	v_lshlrev_b32_e32 v48, 16, v48
	v_lshlrev_b32_e32 v49, 16, v49
	v_lshlrev_b32_e32 v50, 16, v50
	v_lshlrev_b32_e32 v51, 16, v51
	v_lshlrev_b32_e32 v52, 16, v52
	v_lshlrev_b32_e32 v53, 16, v53
	v_lshlrev_b32_e32 v54, 16, v54
	v_lshlrev_b32_e32 v55, 16, v55
	v_lshlrev_b32_e32 v56, 16, v56
	v_lshlrev_b32_e32 v57, 16, v57
	v_lshlrev_b32_e32 v58, 16, v58
	v_lshlrev_b32_e32 v59, 16, v59
	v_lshlrev_b32_e32 v60, 16, v60
	v_lshlrev_b32_e32 v61, 16, v61
	v_lshlrev_b32_e32 v62, 16, v62
	v_lshlrev_b32_e32 v63, 16, v63
	v_exp_f32_e32 v0, v0
	v_exp_f32_e32 v1, v1
	v_exp_f32_e32 v2, v2
	v_exp_f32_e32 v3, v3
	v_exp_f32_e32 v4, v4
	v_exp_f32_e32 v5, v5
	v_exp_f32_e32 v6, v6
	v_exp_f32_e32 v7, v7
	v_exp_f32_e32 v8, v8
	v_exp_f32_e32 v9, v9
	v_exp_f32_e32 v10, v10
	v_exp_f32_e32 v11, v11
	v_exp_f32_e32 v12, v12
	v_exp_f32_e32 v13, v13
	v_exp_f32_e32 v14, v14
	v_exp_f32_e32 v15, v15
	v_fma_f32 v32, -v0, v0, 1.0 clamp
	v_fma_f32 v33, -v1, v1, 1.0 clamp
	v_fma_f32 v34, -v2, v2, 1.0 clamp
	v_fma_f32 v35, -v3, v3, 1.0 clamp
	v_fma_f32 v36, -v4, v4, 1.0 clamp
	v_fma_f32 v37, -v5, v5, 1.0 clamp
	v_fma_f32 v38, -v6, v6, 1.0 clamp
	v_fma_f32 v39, -v7, v7, 1.0 clamp
	v_fma_f32 v40, -v8, v8, 1.0 clamp
	v_fma_f32 v41, -v9, v9, 1.0 clamp
	v_fma_f32 v42, -v10, v10, 1.0 clamp
	v_fma_f32 v43, -v11, v11, 1.0 clamp
; __device__ __forceinline__ unsigned f2bf(float f) { unsigned r; asm("v_cvt_pk_bf16_f32 %0, %1, %1" : "=v"(r) : "v"(f)); return r & 0xffffu; }
; __device__ __forceinline__ float sigmoid_f(float x) { return rcpf_(1.f + __expf(-x)); }
; __device__ __forceinline__ float gelu_tanh_f(float x) { const float y = 0.7978845608028654f * (x + 0.044715f * x * x * x); return x * sigmoid_f(2.f * y); }
; template <bool FINAL, int D>
; __device__ __forceinline__ void rg_dir(PREF p, int l, int h, int ch, int sidx, int rowbase  , LAS bf16_t* sXc, LAS float* stg, int lane) {
;     ...
;         for (int ti = 0; ti < 16; ++ti) { const int tk = D ? 15 - ti : ti;
;             const float zr = stg[tk * 64 + lane] + ba, zi = stg[1024 + tk * 64 + lane] + bi;
;             const float r = sigmoid_f(zr), ig = sigmoid_f(zi);
;             const float a = __builtin_amdgcn_exp2f(r * sp8);
;             const float xc = bf2f(sXc[(mt * 16 + tk) * 72 + lane]);
;             av[ti] = a; iv[ti] = __builtin_amdgcn_sqrtf(fmaxf(1.f - a * a, 0.f)) * ig * xc;
;             if (FINAL && D == 1) grv[ti] = gelu_tanh_f(grv[ti]);
;         }
; #pragma unroll
;         for (int ti = 0; ti < 16; ++ti) { const int tk = D ? 15 - ti : ti;
;             hc = av[ti] * hc + iv[ti]; Ap *= av[ti];
;             if (FINAL) { const size_t row = (size_t)(rowbase + mt * 16 + tk);
;                 if (D == 0) TMP[row * 512 + ch] = (bf16_t)f2bf(hc);
;                 else MIX[row * DM + ch] = (bf16_t)f2bf(grv[ti] * (hfv[ti] + hc)); }
; __global__ void __launch_bounds__(NTHREADS, 2) mega_fwd(Params p_arg) {
;     ...
;             for (int item = gw; item < nrg; item += NGW) rg_item<true>(p, l, item, lds + wave * 18432, lane);
	v_fma_f32 v44, -v12, v12, 1.0 clamp
	v_fma_f32 v45, -v13, v13, 1.0 clamp
	v_fma_f32 v46, -v14, v14, 1.0 clamp
	v_fma_f32 v47, -v15, v15, 1.0 clamp
	v_sqrt_f32_e32 v32, v32
	v_sqrt_f32_e32 v33, v33
	v_sqrt_f32_e32 v34, v34
	v_sqrt_f32_e32 v35, v35
	v_sqrt_f32_e32 v36, v36
	v_sqrt_f32_e32 v37, v37
	v_sqrt_f32_e32 v38, v38
	v_sqrt_f32_e32 v39, v39
	v_sqrt_f32_e32 v40, v40
	v_sqrt_f32_e32 v41, v41
	v_sqrt_f32_e32 v42, v42
	v_sqrt_f32_e32 v43, v43
	v_sqrt_f32_e32 v44, v44
	v_sqrt_f32_e32 v45, v45
	v_sqrt_f32_e32 v46, v46
	v_sqrt_f32_e32 v47, v47
	s_nop 0
	v_pk_mul_f32 v[16:17], v[16:17], v[32:33]
	v_pk_mul_f32 v[18:19], v[18:19], v[34:35]
	v_pk_mul_f32 v[20:21], v[20:21], v[36:37]
	v_pk_mul_f32 v[22:23], v[22:23], v[38:39]
	v_pk_mul_f32 v[24:25], v[24:25], v[40:41]
	v_pk_mul_f32 v[26:27], v[26:27], v[42:43]
	v_pk_mul_f32 v[28:29], v[28:29], v[44:45]
	v_pk_mul_f32 v[30:31], v[30:31], v[46:47]
	v_pk_mul_f32 v[16:17], v[16:17], v[48:49]
	v_pk_mul_f32 v[18:19], v[18:19], v[50:51]
	v_pk_mul_f32 v[20:21], v[20:21], v[52:53]
	v_pk_mul_f32 v[22:23], v[22:23], v[54:55]
	v_pk_mul_f32 v[24:25], v[24:25], v[56:57]
	v_pk_mul_f32 v[26:27], v[26:27], v[58:59]
	v_pk_mul_f32 v[28:29], v[28:29], v[60:61]
	v_pk_mul_f32 v[30:31], v[30:31], v[62:63]
	s_add_i32 s39, s15, 14
	s_lshl_b32 s39, s39, 11
	s_add_u32 s90, s0, 0x7b00000
	s_addc_u32 s91, s1, 0
	s_add_u32 s90, s90, s39
	s_addc_u32 s91, s91, 0
	v_lshlrev_b32_e32 v48, 16, v158
	v_and_b32_e32 v49, 0xffff0000, v158
	v_lshlrev_b32_e32 v50, 16, v159
	v_and_b32_e32 v51, 0xffff0000, v159
	v_lshlrev_b32_e32 v52, 16, v160
	v_and_b32_e32 v53, 0xffff0000, v160
	v_lshlrev_b32_e32 v54, 16, v161
	v_and_b32_e32 v55, 0xffff0000, v161
	v_lshlrev_b32_e32 v56, 16, v162
	v_and_b32_e32 v57, 0xffff0000, v162
	v_lshlrev_b32_e32 v58, 16, v163
	v_and_b32_e32 v59, 0xffff0000, v163
	v_lshlrev_b32_e32 v60, 16, v164
	v_and_b32_e32 v61, 0xffff0000, v164
	v_lshlrev_b32_e32 v62, 16, v165
	v_and_b32_e32 v63, 0xffff0000, v165
	v_fma_f32 v47, v15, v250, v31
	v_fma_f32 v46, v14, v47, v30
	v_fma_f32 v45, v13, v46, v29
	v_fma_f32 v44, v12, v45, v28
	v_fma_f32 v43, v11, v44, v27
	v_fma_f32 v42, v10, v43, v26
	v_fma_f32 v41, v9, v42, v25
	v_fma_f32 v40, v8, v41, v24
	v_fma_f32 v39, v7, v40, v23
	v_fma_f32 v38, v6, v39, v22
	v_fma_f32 v37, v5, v38, v21
	v_fma_f32 v36, v4, v37, v20
	v_fma_f32 v35, v3, v36, v19
	v_fma_f32 v34, v2, v35, v18
	v_fma_f32 v33, v1, v34, v17
	v_fma_f32 v32, v0, v33, v16
	v_mov_b32_e32 v250, v32
	v_pk_add_f32 v[48:49], v[48:49], v[32:33]
	v_pk_add_f32 v[50:51], v[50:51], v[34:35]
	v_pk_add_f32 v[52:53], v[52:53], v[36:37]
	v_pk_add_f32 v[54:55], v[54:55], v[38:39]
	v_pk_add_f32 v[56:57], v[56:57], v[40:41]
	v_pk_add_f32 v[58:59], v[58:59], v[42:43]
	v_pk_add_f32 v[60:61], v[60:61], v[44:45]
	v_pk_add_f32 v[62:63], v[62:63], v[46:47]
	v_pk_mul_f32 v[48:49], v[206:207], v[48:49]
	v_pk_mul_f32 v[50:51], v[208:209], v[50:51]
	v_pk_mul_f32 v[52:53], v[210:211], v[52:53]
	v_pk_mul_f32 v[54:55], v[212:213], v[54:55]
	v_pk_mul_f32 v[56:57], v[214:215], v[56:57]
	v_pk_mul_f32 v[58:59], v[216:217], v[58:59]
	v_pk_mul_f32 v[60:61], v[218:219], v[60:61]
	v_pk_mul_f32 v[62:63], v[222:223], v[62:63]
	v_cvt_pk_bf16_f32 v48, v48, v49
	v_cvt_pk_bf16_f32 v50, v50, v51
	v_cvt_pk_bf16_f32 v52, v52, v53
	v_cvt_pk_bf16_f32 v54, v54, v55
	v_cvt_pk_bf16_f32 v56, v56, v57
	v_cvt_pk_bf16_f32 v58, v58, v59
	v_cvt_pk_bf16_f32 v60, v60, v61
	v_cvt_pk_bf16_f32 v62, v62, v63
	global_store_short_d16_hi v234, v62, s[90:91] offset:2048
	global_store_short v234, v62, s[90:91]
	s_sub_u32 s90, s90, 0x1000
	s_subb_u32 s91, s91, 0
	global_store_short_d16_hi v234, v60, s[90:91] offset:2048
	global_store_short v234, v60, s[90:91]
	s_sub_u32 s90, s90, 0x1000
	s_subb_u32 s91, s91, 0
	global_store_short_d16_hi v234, v58, s[90:91] offset:2048
	global_store_short v234, v58, s[90:91]
	s_sub_u32 s90, s90, 0x1000
	s_subb_u32 s91, s91, 0
	global_store_short_d16_hi v234, v56, s[90:91] offset:2048
	global_store_short v234, v56, s[90:91]
	s_sub_u32 s90, s90, 0x1000
	s_subb_u32 s91, s91, 0
	global_store_short_d16_hi v234, v54, s[90:91] offset:2048
	global_store_short v234, v54, s[90:91]
	s_sub_u32 s90, s90, 0x1000
	s_subb_u32 s91, s91, 0
	global_store_short_d16_hi v234, v52, s[90:91] offset:2048
	global_store_short v234, v52, s[90:91]
	s_sub_u32 s90, s90, 0x1000
	s_subb_u32 s91, s91, 0
	global_store_short_d16_hi v234, v50, s[90:91] offset:2048
	global_store_short v234, v50, s[90:91]
	s_sub_u32 s90, s90, 0x1000
	s_subb_u32 s91, s91, 0
	global_store_short_d16_hi v234, v48, s[90:91] offset:2048
	global_store_short v234, v48, s[90:91]
	s_waitcnt lgkmcnt(0)
	v_readlane_b32 s84, v253, 29
	s_add_i32 s12, s12, s84
	s_cmpk_lt_i32 s12, 0x1000
	s_cbranch_scc1 .Lrg7_keep
	s_sub_i32 s0, s12, 0x1000
	s_lshr_b32 s1, s0, 5
	s_and_b32 s0, s0, 31
	s_and_b32 s12, s1, 7
	s_add_i32 s1, s1, 0x1000
	s_cmp_eq_u32 s0, s12
	s_cselect_b32 s12, s1, 0x2000
